# clean variant + unreachable s_nop padding after the new gate code so later GEMM code keeps its baseline addresses
# baseline (speedup 1.0000x reference)
; #define LAS __attribute__((address_space(3)))
; DI float bf2f(bf16_t v) { return __uint_as_float(((unsigned)v) << 16); }
; DI bf16_t f2bf(float f) { return (bf16_t)(cvt_pk(f, 0.f) & 0xffffu); }
; DI float logsig16(float z) { return (fminf(z, 0.f) - __logf(1.0f + __expf(-fabsf(z)))) * (1.0f / 16.0f); }
; DI void gla_gate_phase(const Params& P, LAS unsigned char* lds, int lj) {
;     ...
;       for (int ii = 0; ii < 16; ++ii) {
;         const int i = ib * 16 + ii;
;         float z = bf_;
; #pragma unroll
;         for (int j4 = 0; j4 < 4; ++j4) { const f32x4 zz = *(const LAS f32x4*)(zL + i * 32 + j4 * 4); z += zz[0] * wf[j4 * 4] + zz[1] * wf[j4 * 4 + 1] + zz[2] * wf[j4 * 4 + 2] + zz[3] * wf[j4 * 4 + 3]; }
;         runf += logsig16(z);
;         const float Bi = totb - runb; runb += lsb[i];
;         const size_t tokrow = (size_t)item * 64 + i;
;         bf16_t* pr = proj + tokrow * 3072 + col;
;         const float q = bf2f(qraw[ii]), k = bf2f(kraw[ii]);
;         pr[0] = f2bf(q * __expf(runf)); pr[512] = f2bf(k * __expf(-runf));
;         QB[tokrow * 512 + col] = f2bf(q * __expf(Bi)); KB[tokrow * 512 + col] = f2bf(k * __expf(-Bi));
.Lgt_nold:
	s_waitcnt lgkmcnt(0)
	ds_read_b32 v134, v50 offset:0
	ds_read_b32 v135, v50 offset:2048
	v_mul_f32_e32 v120, v3, v85
	v_mul_f32_e32 v136, v3, v101
	v_fmac_f32_e32 v120, v2, v84
	v_fmac_f32_e32 v136, v2, v100
	v_fmac_f32_e32 v120, v4, v86
	v_fmac_f32_e32 v136, v4, v102
	v_fmac_f32_e32 v120, v5, v87
	v_fmac_f32_e32 v136, v5, v103
	v_add_f32_e32 v124, v34, v120
	v_add_f32_e32 v140, v34, v136
	v_mul_f32_e32 v120, v7, v89
	v_mul_f32_e32 v136, v7, v105
	v_fmac_f32_e32 v120, v6, v88
	v_fmac_f32_e32 v136, v6, v104
	v_fmac_f32_e32 v120, v8, v90
	v_fmac_f32_e32 v136, v8, v106
	v_fmac_f32_e32 v120, v9, v91
	v_fmac_f32_e32 v136, v9, v107
	v_add_f32_e32 v124, v124, v120
	v_add_f32_e32 v140, v140, v136
	v_mul_f32_e32 v120, v11, v93
	v_mul_f32_e32 v136, v11, v109
	v_fmac_f32_e32 v120, v10, v92
	v_fmac_f32_e32 v136, v10, v108
	v_fmac_f32_e32 v120, v12, v94
	v_fmac_f32_e32 v136, v12, v110
	v_fmac_f32_e32 v120, v13, v95
	v_fmac_f32_e32 v136, v13, v111
	v_add_f32_e32 v124, v124, v120
	v_add_f32_e32 v140, v140, v136
	v_mul_f32_e32 v120, v15, v97
	v_mul_f32_e32 v136, v15, v113
	v_fmac_f32_e32 v120, v14, v96
	v_fmac_f32_e32 v136, v14, v112
	v_fmac_f32_e32 v120, v16, v98
	v_fmac_f32_e32 v136, v16, v114
	v_fmac_f32_e32 v120, v17, v99
	v_fmac_f32_e32 v136, v17, v115
	v_add_f32_e32 v124, v124, v120
	v_add_f32_e32 v140, v140, v136
	ds_read_b128 v[84:87], v49 offset:256
	ds_read_b128 v[88:91], v49 offset:272
	ds_read_b128 v[92:95], v49 offset:288
	ds_read_b128 v[96:99], v49 offset:304
	ds_read_b128 v[100:103], v49 offset:384
	ds_read_b128 v[104:107], v49 offset:400
	ds_read_b128 v[108:111], v49 offset:416
	ds_read_b128 v[112:115], v49 offset:432
	v_min_f32_e32 v121, 0, v124
	v_min_f32_e32 v137, 0, v140
	v_mul_f32_e64 v122, |v124|, s16
	v_mul_f32_e64 v138, |v140|, s16
	v_exp_f32_e32 v122, v122
	v_exp_f32_e32 v138, v138
	v_add_f32_e32 v122, 1.0, v122
	v_add_f32_e32 v138, 1.0, v138
	v_log_f32_e32 v122, v122
	v_log_f32_e32 v138, v138
	v_mul_f32_e32 v123, 0x3f317217, v122
	v_mul_f32_e32 v139, 0x3f317217, v138
	v_fma_f32 v123, v122, s55, -v123
	v_fma_f32 v139, v138, s55, -v139
	v_fmac_f32_e32 v123, 0x3377d1cf, v122
	v_fmac_f32_e32 v139, 0x3377d1cf, v138
	v_fmac_f32_e32 v123, 0x3f317217, v122
	v_fmac_f32_e32 v139, 0x3f317217, v138
	v_sub_f32_e32 v124, v121, v123
	v_sub_f32_e32 v140, v137, v139
	s_waitcnt lgkmcnt(8)
	v_fma_f32 v144, v124, s57, v128
	v_sub_f32_e32 v127, v130, v129
	v_add_f32_e32 v145, v129, v134
	v_fma_f32 v128, v140, s57, v144
	v_sub_f32_e32 v143, v130, v145
	v_add_f32_e32 v129, v145, v135
	v_mul_f32_e32 v132, 0x3fb8aa3b, v144
	v_mul_f32_e32 v133, 0x3fb8aa3b, v128
	v_exp_f32_e32 v125, v132
	v_exp_f32_e32 v141, v133
	v_exp_f32_e64 v126, -v132
	v_exp_f32_e64 v142, -v133
	v_mul_f32_e32 v132, 0x3fb8aa3b, v127
	v_mul_f32_e32 v133, 0x3fb8aa3b, v143
	v_mul_f32_e32 v125, v125, v68
	v_mul_f32_e32 v141, v141, v69
	v_mul_f32_e32 v126, v126, v76
	v_mul_f32_e32 v142, v142, v77
	v_cvt_pk_bf16_f32 v125, v125, v1
	v_cvt_pk_bf16_f32 v141, v141, v1
	v_cvt_pk_bf16_f32 v126, v126, v1
	v_cvt_pk_bf16_f32 v142, v142, v1
	global_store_short v38, v125, s[46:47]
	global_store_short v39, v141, s[46:47]
	global_store_short v38, v126, s[46:47] offset:1024
	global_store_short v39, v142, s[46:47] offset:1024
	v_exp_f32_e32 v120, v132
	v_exp_f32_e32 v136, v133
	v_exp_f32_e64 v121, -v132
	v_exp_f32_e64 v137, -v133
	v_nop
	v_nop
	v_nop
	v_nop
	v_mul_f32_e32 v120, v120, v68
	v_mul_f32_e32 v136, v136, v69
	v_mul_f32_e32 v121, v121, v76
	v_mul_f32_e32 v137, v137, v77
	v_cvt_pk_bf16_f32 v120, v120, v1
	v_cvt_pk_bf16_f32 v136, v136, v1
	v_cvt_pk_bf16_f32 v121, v121, v1
	v_cvt_pk_bf16_f32 v137, v137, v1
	global_store_short v37, v120, s[48:49]
	global_store_short v37, v136, s[48:49] offset:1024
	global_store_short v37, v121, s[50:51]
	global_store_short v37, v137, s[50:51] offset:1024
	s_waitcnt lgkmcnt(0)
	ds_read_b32 v134, v50 offset:4096
	ds_read_b32 v135, v50 offset:6144
	v_mul_f32_e32 v120, v3, v85
	v_mul_f32_e32 v136, v3, v101
	v_fmac_f32_e32 v120, v2, v84
	v_fmac_f32_e32 v136, v2, v100
	v_fmac_f32_e32 v120, v4, v86
	v_fmac_f32_e32 v136, v4, v102
	v_fmac_f32_e32 v120, v5, v87
	v_fmac_f32_e32 v136, v5, v103
	v_add_f32_e32 v124, v34, v120
	v_add_f32_e32 v140, v34, v136
	v_mul_f32_e32 v120, v7, v89
	v_mul_f32_e32 v136, v7, v105
	v_fmac_f32_e32 v120, v6, v88
	v_fmac_f32_e32 v136, v6, v104
	v_fmac_f32_e32 v120, v8, v90
	v_fmac_f32_e32 v136, v8, v106
	v_fmac_f32_e32 v120, v9, v91
	v_fmac_f32_e32 v136, v9, v107
	v_add_f32_e32 v124, v124, v120
	v_add_f32_e32 v140, v140, v136
	v_mul_f32_e32 v120, v11, v93
	v_mul_f32_e32 v136, v11, v109
	v_fmac_f32_e32 v120, v10, v92
	v_fmac_f32_e32 v136, v10, v108
	v_fmac_f32_e32 v120, v12, v94
	v_fmac_f32_e32 v136, v12, v110
	v_fmac_f32_e32 v120, v13, v95
	v_fmac_f32_e32 v136, v13, v111
	v_add_f32_e32 v124, v124, v120
	v_add_f32_e32 v140, v140, v136
	v_mul_f32_e32 v120, v15, v97
	v_mul_f32_e32 v136, v15, v113
	v_fmac_f32_e32 v120, v14, v96
	v_fmac_f32_e32 v136, v14, v112
	v_fmac_f32_e32 v120, v16, v98
	v_fmac_f32_e32 v136, v16, v114
	v_fmac_f32_e32 v120, v17, v99
	v_fmac_f32_e32 v136, v17, v115
	v_add_f32_e32 v124, v124, v120
	v_add_f32_e32 v140, v140, v136
	ds_read_b128 v[84:87], v49 offset:512
	ds_read_b128 v[88:91], v49 offset:528
	ds_read_b128 v[92:95], v49 offset:544
	ds_read_b128 v[96:99], v49 offset:560
	ds_read_b128 v[100:103], v49 offset:640
	ds_read_b128 v[104:107], v49 offset:656
	ds_read_b128 v[108:111], v49 offset:672
	ds_read_b128 v[112:115], v49 offset:688
	v_min_f32_e32 v121, 0, v124
	v_min_f32_e32 v137, 0, v140
	v_mul_f32_e64 v122, |v124|, s16
	v_mul_f32_e64 v138, |v140|, s16
	v_exp_f32_e32 v122, v122
	v_exp_f32_e32 v138, v138
	v_add_f32_e32 v122, 1.0, v122
	v_add_f32_e32 v138, 1.0, v138
	v_log_f32_e32 v122, v122
	v_log_f32_e32 v138, v138
	v_mul_f32_e32 v123, 0x3f317217, v122
	v_mul_f32_e32 v139, 0x3f317217, v138
	v_fma_f32 v123, v122, s55, -v123
	v_fma_f32 v139, v138, s55, -v139
	v_fmac_f32_e32 v123, 0x3377d1cf, v122
	v_fmac_f32_e32 v139, 0x3377d1cf, v138
	v_fmac_f32_e32 v123, 0x3f317217, v122
	v_fmac_f32_e32 v139, 0x3f317217, v138
	v_sub_f32_e32 v124, v121, v123
	v_sub_f32_e32 v140, v137, v139
	s_waitcnt lgkmcnt(8)
; #define LAS __attribute__((address_space(3)))
; DI float bf2f(bf16_t v) { return __uint_as_float(((unsigned)v) << 16); }
; DI bf16_t f2bf(float f) { return (bf16_t)(cvt_pk(f, 0.f) & 0xffffu); }
; DI float logsig16(float z) { return (fminf(z, 0.f) - __logf(1.0f + __expf(-fabsf(z)))) * (1.0f / 16.0f); }
; DI void gla_gate_phase(const Params& P, LAS unsigned char* lds, int lj) {
;     ...
;       for (int ii = 0; ii < 16; ++ii) {
;         const int i = ib * 16 + ii;
;         float z = bf_;
; #pragma unroll
;         for (int j4 = 0; j4 < 4; ++j4) { const f32x4 zz = *(const LAS f32x4*)(zL + i * 32 + j4 * 4); z += zz[0] * wf[j4 * 4] + zz[1] * wf[j4 * 4 + 1] + zz[2] * wf[j4 * 4 + 2] + zz[3] * wf[j4 * 4 + 3]; }
;         runf += logsig16(z);
;         const float Bi = totb - runb; runb += lsb[i];
;         const size_t tokrow = (size_t)item * 64 + i;
;         bf16_t* pr = proj + tokrow * 3072 + col;
;         const float q = bf2f(qraw[ii]), k = bf2f(kraw[ii]);
;         pr[0] = f2bf(q * __expf(runf)); pr[512] = f2bf(k * __expf(-runf));
;         QB[tokrow * 512 + col] = f2bf(q * __expf(Bi)); KB[tokrow * 512 + col] = f2bf(k * __expf(-Bi));
	v_fma_f32 v144, v124, s57, v128
	v_sub_f32_e32 v127, v130, v129
	v_add_f32_e32 v145, v129, v134
	v_fma_f32 v128, v140, s57, v144
	v_sub_f32_e32 v143, v130, v145
	v_add_f32_e32 v129, v145, v135
	v_mul_f32_e32 v132, 0x3fb8aa3b, v144
	v_mul_f32_e32 v133, 0x3fb8aa3b, v128
	v_exp_f32_e32 v125, v132
	v_exp_f32_e32 v141, v133
	v_exp_f32_e64 v126, -v132
	v_exp_f32_e64 v142, -v133
	v_mul_f32_e32 v132, 0x3fb8aa3b, v127
	v_mul_f32_e32 v133, 0x3fb8aa3b, v143
	v_mul_f32_e32 v125, v125, v70
	v_mul_f32_e32 v141, v141, v71
	v_mul_f32_e32 v126, v126, v78
	v_mul_f32_e32 v142, v142, v79
	v_cvt_pk_bf16_f32 v125, v125, v1
	v_cvt_pk_bf16_f32 v141, v141, v1
	v_cvt_pk_bf16_f32 v126, v126, v1
	v_cvt_pk_bf16_f32 v142, v142, v1
	global_store_short v40, v125, s[46:47]
	global_store_short v41, v141, s[46:47]
	global_store_short v40, v126, s[46:47] offset:1024
	global_store_short v41, v142, s[46:47] offset:1024
	v_exp_f32_e32 v120, v132
	v_exp_f32_e32 v136, v133
	v_exp_f32_e64 v121, -v132
	v_exp_f32_e64 v137, -v133
	v_nop
	v_nop
	v_nop
	v_nop
	v_mul_f32_e32 v120, v120, v70
	v_mul_f32_e32 v136, v136, v71
	v_mul_f32_e32 v121, v121, v78
	v_mul_f32_e32 v137, v137, v79
	v_cvt_pk_bf16_f32 v120, v120, v1
	v_cvt_pk_bf16_f32 v136, v136, v1
	v_cvt_pk_bf16_f32 v121, v121, v1
	v_cvt_pk_bf16_f32 v137, v137, v1
	global_store_short v37, v120, s[48:49] offset:2048
	global_store_short v37, v136, s[48:49] offset:3072
	global_store_short v37, v121, s[50:51] offset:2048
	global_store_short v37, v137, s[50:51] offset:3072
	s_waitcnt lgkmcnt(0)
	ds_read_b32 v134, v50 offset:8192
	ds_read_b32 v135, v50 offset:10240
	v_mul_f32_e32 v120, v3, v85
	v_mul_f32_e32 v136, v3, v101
	v_fmac_f32_e32 v120, v2, v84
	v_fmac_f32_e32 v136, v2, v100
	v_fmac_f32_e32 v120, v4, v86
	v_fmac_f32_e32 v136, v4, v102
	v_fmac_f32_e32 v120, v5, v87
	v_fmac_f32_e32 v136, v5, v103
	v_add_f32_e32 v124, v34, v120
	v_add_f32_e32 v140, v34, v136
	v_mul_f32_e32 v120, v7, v89
	v_mul_f32_e32 v136, v7, v105
	v_fmac_f32_e32 v120, v6, v88
	v_fmac_f32_e32 v136, v6, v104
	v_fmac_f32_e32 v120, v8, v90
	v_fmac_f32_e32 v136, v8, v106
	v_fmac_f32_e32 v120, v9, v91
	v_fmac_f32_e32 v136, v9, v107
	v_add_f32_e32 v124, v124, v120
	v_add_f32_e32 v140, v140, v136
	v_mul_f32_e32 v120, v11, v93
	v_mul_f32_e32 v136, v11, v109
	v_fmac_f32_e32 v120, v10, v92
	v_fmac_f32_e32 v136, v10, v108
	v_fmac_f32_e32 v120, v12, v94
	v_fmac_f32_e32 v136, v12, v110
	v_fmac_f32_e32 v120, v13, v95
	v_fmac_f32_e32 v136, v13, v111
	v_add_f32_e32 v124, v124, v120
	v_add_f32_e32 v140, v140, v136
	v_mul_f32_e32 v120, v15, v97
	v_mul_f32_e32 v136, v15, v113
	v_fmac_f32_e32 v120, v14, v96
	v_fmac_f32_e32 v136, v14, v112
	v_fmac_f32_e32 v120, v16, v98
	v_fmac_f32_e32 v136, v16, v114
	v_fmac_f32_e32 v120, v17, v99
	v_fmac_f32_e32 v136, v17, v115
	v_add_f32_e32 v124, v124, v120
	v_add_f32_e32 v140, v140, v136
	ds_read_b128 v[84:87], v49 offset:768
	ds_read_b128 v[88:91], v49 offset:784
	ds_read_b128 v[92:95], v49 offset:800
	ds_read_b128 v[96:99], v49 offset:816
	ds_read_b128 v[100:103], v49 offset:896
	ds_read_b128 v[104:107], v49 offset:912
	ds_read_b128 v[108:111], v49 offset:928
	ds_read_b128 v[112:115], v49 offset:944
	v_min_f32_e32 v121, 0, v124
	v_min_f32_e32 v137, 0, v140
	v_mul_f32_e64 v122, |v124|, s16
	v_mul_f32_e64 v138, |v140|, s16
	v_exp_f32_e32 v122, v122
	v_exp_f32_e32 v138, v138
	v_add_f32_e32 v122, 1.0, v122
	v_add_f32_e32 v138, 1.0, v138
	v_log_f32_e32 v122, v122
	v_log_f32_e32 v138, v138
	v_mul_f32_e32 v123, 0x3f317217, v122
	v_mul_f32_e32 v139, 0x3f317217, v138
	v_fma_f32 v123, v122, s55, -v123
	v_fma_f32 v139, v138, s55, -v139
	v_fmac_f32_e32 v123, 0x3377d1cf, v122
	v_fmac_f32_e32 v139, 0x3377d1cf, v138
	v_fmac_f32_e32 v123, 0x3f317217, v122
	v_fmac_f32_e32 v139, 0x3f317217, v138
	v_sub_f32_e32 v124, v121, v123
	v_sub_f32_e32 v140, v137, v139
	s_waitcnt lgkmcnt(8)
	v_fma_f32 v144, v124, s57, v128
	v_sub_f32_e32 v127, v130, v129
	v_add_f32_e32 v145, v129, v134
	v_fma_f32 v128, v140, s57, v144
	v_sub_f32_e32 v143, v130, v145
	v_add_f32_e32 v129, v145, v135
	v_mul_f32_e32 v132, 0x3fb8aa3b, v144
	v_mul_f32_e32 v133, 0x3fb8aa3b, v128
	v_exp_f32_e32 v125, v132
	v_exp_f32_e32 v141, v133
	v_exp_f32_e64 v126, -v132
	v_exp_f32_e64 v142, -v133
	v_mul_f32_e32 v132, 0x3fb8aa3b, v127
	v_mul_f32_e32 v133, 0x3fb8aa3b, v143
	v_mul_f32_e32 v125, v125, v72
	v_mul_f32_e32 v141, v141, v73
	v_mul_f32_e32 v126, v126, v80
	v_mul_f32_e32 v142, v142, v81
	v_cvt_pk_bf16_f32 v125, v125, v1
	v_cvt_pk_bf16_f32 v141, v141, v1
	v_cvt_pk_bf16_f32 v126, v126, v1
	v_cvt_pk_bf16_f32 v142, v142, v1
	global_store_short v42, v125, s[46:47]
	global_store_short v43, v141, s[46:47]
	global_store_short v42, v126, s[46:47] offset:1024
	global_store_short v43, v142, s[46:47] offset:1024
	v_exp_f32_e32 v120, v132
	v_exp_f32_e32 v136, v133
	v_exp_f32_e64 v121, -v132
	v_exp_f32_e64 v137, -v133
	v_nop
	v_nop
	v_nop
	v_nop
	v_mul_f32_e32 v120, v120, v72
	v_mul_f32_e32 v136, v136, v73
	v_mul_f32_e32 v121, v121, v80
	v_mul_f32_e32 v137, v137, v81
	v_cvt_pk_bf16_f32 v120, v120, v1
	v_cvt_pk_bf16_f32 v136, v136, v1
	v_cvt_pk_bf16_f32 v121, v121, v1
	v_cvt_pk_bf16_f32 v137, v137, v1
	global_store_short v46, v120, s[48:49]
	global_store_short v46, v136, s[48:49] offset:1024
	global_store_short v46, v121, s[50:51]
	global_store_short v46, v137, s[50:51] offset:1024
	s_waitcnt lgkmcnt(0)
; #define LAS __attribute__((address_space(3)))
; DI float bf2f(bf16_t v) { return __uint_as_float(((unsigned)v) << 16); }
; DI bf16_t f2bf(float f) { return (bf16_t)(cvt_pk(f, 0.f) & 0xffffu); }
; DI float logsig16(float z) { return (fminf(z, 0.f) - __logf(1.0f + __expf(-fabsf(z)))) * (1.0f / 16.0f); }
; DI void gla_gate_phase(const Params& P, LAS unsigned char* lds, int lj) {
;     ...
;       for (int ii = 0; ii < 16; ++ii) {
;         const int i = ib * 16 + ii;
;         float z = bf_;
; #pragma unroll
;         for (int j4 = 0; j4 < 4; ++j4) { const f32x4 zz = *(const LAS f32x4*)(zL + i * 32 + j4 * 4); z += zz[0] * wf[j4 * 4] + zz[1] * wf[j4 * 4 + 1] + zz[2] * wf[j4 * 4 + 2] + zz[3] * wf[j4 * 4 + 3]; }
;         runf += logsig16(z);
;         const float Bi = totb - runb; runb += lsb[i];
;         const size_t tokrow = (size_t)item * 64 + i;
;         bf16_t* pr = proj + tokrow * 3072 + col;
;         const float q = bf2f(qraw[ii]), k = bf2f(kraw[ii]);
;         pr[0] = f2bf(q * __expf(runf)); pr[512] = f2bf(k * __expf(-runf));
;         QB[tokrow * 512 + col] = f2bf(q * __expf(Bi)); KB[tokrow * 512 + col] = f2bf(k * __expf(-Bi));
;       }
;       asm volatile("" ::: "memory");
;     }
;     dect[(size_t)item * 512 + col] = __expf(runf);
;     dect[(size_t)(512 + item) * 512 + col] = __expf(totb);
;   }
	ds_read_b32 v134, v50 offset:12288
	ds_read_b32 v135, v50 offset:14336
	v_mul_f32_e32 v120, v3, v85
	v_mul_f32_e32 v136, v3, v101
	v_fmac_f32_e32 v120, v2, v84
	v_fmac_f32_e32 v136, v2, v100
	v_fmac_f32_e32 v120, v4, v86
	v_fmac_f32_e32 v136, v4, v102
	v_fmac_f32_e32 v120, v5, v87
	v_fmac_f32_e32 v136, v5, v103
	v_add_f32_e32 v124, v34, v120
	v_add_f32_e32 v140, v34, v136
	v_mul_f32_e32 v120, v7, v89
	v_mul_f32_e32 v136, v7, v105
	v_fmac_f32_e32 v120, v6, v88
	v_fmac_f32_e32 v136, v6, v104
	v_fmac_f32_e32 v120, v8, v90
	v_fmac_f32_e32 v136, v8, v106
	v_fmac_f32_e32 v120, v9, v91
	v_fmac_f32_e32 v136, v9, v107
	v_add_f32_e32 v124, v124, v120
	v_add_f32_e32 v140, v140, v136
	v_mul_f32_e32 v120, v11, v93
	v_mul_f32_e32 v136, v11, v109
	v_fmac_f32_e32 v120, v10, v92
	v_fmac_f32_e32 v136, v10, v108
	v_fmac_f32_e32 v120, v12, v94
	v_fmac_f32_e32 v136, v12, v110
	v_fmac_f32_e32 v120, v13, v95
	v_fmac_f32_e32 v136, v13, v111
	v_add_f32_e32 v124, v124, v120
	v_add_f32_e32 v140, v140, v136
	v_mul_f32_e32 v120, v15, v97
	v_mul_f32_e32 v136, v15, v113
	v_fmac_f32_e32 v120, v14, v96
	v_fmac_f32_e32 v136, v14, v112
	v_fmac_f32_e32 v120, v16, v98
	v_fmac_f32_e32 v136, v16, v114
	v_fmac_f32_e32 v120, v17, v99
	v_fmac_f32_e32 v136, v17, v115
	v_add_f32_e32 v124, v124, v120
	v_add_f32_e32 v140, v140, v136
	v_add_u32_e32 v49, 0x400, v49
	ds_read_b128 v[84:87], v49 offset:0
	ds_read_b128 v[88:91], v49 offset:16
	ds_read_b128 v[92:95], v49 offset:32
	ds_read_b128 v[96:99], v49 offset:48
	ds_read_b128 v[100:103], v49 offset:128
	ds_read_b128 v[104:107], v49 offset:144
	ds_read_b128 v[108:111], v49 offset:160
	ds_read_b128 v[112:115], v49 offset:176
	v_min_f32_e32 v121, 0, v124
	v_min_f32_e32 v137, 0, v140
	v_mul_f32_e64 v122, |v124|, s16
	v_mul_f32_e64 v138, |v140|, s16
	v_exp_f32_e32 v122, v122
	v_exp_f32_e32 v138, v138
	v_add_f32_e32 v122, 1.0, v122
	v_add_f32_e32 v138, 1.0, v138
	v_log_f32_e32 v122, v122
	v_log_f32_e32 v138, v138
	v_mul_f32_e32 v123, 0x3f317217, v122
	v_mul_f32_e32 v139, 0x3f317217, v138
	v_fma_f32 v123, v122, s55, -v123
	v_fma_f32 v139, v138, s55, -v139
	v_fmac_f32_e32 v123, 0x3377d1cf, v122
	v_fmac_f32_e32 v139, 0x3377d1cf, v138
	v_fmac_f32_e32 v123, 0x3f317217, v122
	v_fmac_f32_e32 v139, 0x3f317217, v138
	v_sub_f32_e32 v124, v121, v123
	v_sub_f32_e32 v140, v137, v139
	s_waitcnt lgkmcnt(8)
	v_fma_f32 v144, v124, s57, v128
	v_sub_f32_e32 v127, v130, v129
	v_add_f32_e32 v145, v129, v134
	v_fma_f32 v128, v140, s57, v144
	v_sub_f32_e32 v143, v130, v145
	v_add_f32_e32 v129, v145, v135
	v_mul_f32_e32 v132, 0x3fb8aa3b, v144
	v_mul_f32_e32 v133, 0x3fb8aa3b, v128
	v_exp_f32_e32 v125, v132
	v_exp_f32_e32 v141, v133
	v_exp_f32_e64 v126, -v132
	v_exp_f32_e64 v142, -v133
	v_mul_f32_e32 v132, 0x3fb8aa3b, v127
	v_mul_f32_e32 v133, 0x3fb8aa3b, v143
	v_mul_f32_e32 v125, v125, v74
	v_mul_f32_e32 v141, v141, v75
	v_mul_f32_e32 v126, v126, v82
	v_mul_f32_e32 v142, v142, v83
	v_cvt_pk_bf16_f32 v125, v125, v1
	v_cvt_pk_bf16_f32 v141, v141, v1
	v_cvt_pk_bf16_f32 v126, v126, v1
	v_cvt_pk_bf16_f32 v142, v142, v1
	global_store_short v44, v125, s[46:47]
	global_store_short v45, v141, s[46:47]
	global_store_short v44, v126, s[46:47] offset:1024
	global_store_short v45, v142, s[46:47] offset:1024
	v_exp_f32_e32 v120, v132
	v_exp_f32_e32 v136, v133
	v_exp_f32_e64 v121, -v132
	v_exp_f32_e64 v137, -v133
	v_nop
	v_nop
	v_nop
	v_nop
	v_mul_f32_e32 v120, v120, v74
	v_mul_f32_e32 v136, v136, v75
	v_mul_f32_e32 v121, v121, v82
	v_mul_f32_e32 v137, v137, v83
	v_cvt_pk_bf16_f32 v120, v120, v1
	v_cvt_pk_bf16_f32 v136, v136, v1
	v_cvt_pk_bf16_f32 v121, v121, v1
	v_cvt_pk_bf16_f32 v137, v137, v1
	global_store_short v46, v120, s[48:49] offset:2048
	global_store_short v46, v136, s[48:49] offset:3072
	global_store_short v46, v121, s[50:51] offset:2048
	global_store_short v46, v137, s[50:51] offset:3072
	v_add_u32_e32 v50, 0x4000, v50
	s_add_u32 s46, s46, 0xc000
	s_addc_u32 s47, s47, 0
	s_add_u32 s48, s48, 0x2000
	s_addc_u32 s49, s49, 0
	s_add_u32 s50, s50, 0x2000
	s_addc_u32 s51, s51, 0
	s_add_i32 s43, s43, 1
	s_cmp_lt_u32 s43, 8
	s_cbranch_scc1 .Lgt_main
	s_lshl_b32 s0, s42, 11
	s_add_u32 s0, s6, s0
	s_addc_u32 s1, s7, 0
	s_add_u32 s0, s0, 0xe00000
	s_addc_u32 s1, s1, 0
	v_mul_f32_e32 v120, 0x3fb8aa3b, v128
	v_mul_f32_e32 v136, 0x3fb8aa3b, v130
	v_exp_f32_e32 v120, v120
	v_exp_f32_e32 v136, v136
	s_nop 1
	global_store_dword v36, v120, s[0:1]
	s_add_u32 s0, s0, 0x100000
	s_addc_u32 s1, s1, 0
	global_store_dword v36, v136, s[0:1]
	s_add_i32 s42, s42, s10
	s_cmpk_lt_i32 s42, 0x200
	s_cbranch_scc1 .Lgt_item
	s_branch .LBB0_181
; DI void gla_gate_phase(const Params& P, LAS unsigned char* lds, int lj) {
;     ...
;   __syncthreads();
	s_nop 0
	s_nop 0
	s_nop 0
	s_nop 0
	s_nop 0
	s_nop 0
	s_nop 0
	s_nop 0
	s_nop 0
	s_nop 0
	s_nop 0
	s_nop 0
	s_nop 0
	s_nop 0
	s_nop 0
	s_nop 0
	s_nop 0
	s_nop 0
	s_nop 0
	s_nop 0
	s_nop 0
	s_nop 0
	s_nop 0
	s_nop 0
	s_nop 0
	s_nop 0
	s_nop 0
	s_nop 0
	s_nop 0
	s_nop 0
	s_nop 0
	s_nop 0
	s_nop 0
	s_nop 0
	s_nop 0
	s_nop 0
	s_nop 0
	s_nop 0
	s_nop 0
	s_nop 0
	s_nop 0
	s_nop 0
	s_nop 0
	s_nop 0
	s_nop 0
	s_nop 0
	s_nop 0
	s_nop 0
	s_nop 0
	s_nop 0
	s_nop 0
	s_nop 0
	s_nop 0
	s_nop 0
	s_nop 0
	s_nop 0
	s_nop 0
	s_nop 0
	s_nop 0
	s_nop 0
	s_nop 0
	s_nop 0
	s_nop 0
	s_nop 0
	s_nop 0
	s_nop 0
	s_nop 0
	s_nop 0
	s_nop 0
	s_nop 0
	s_nop 0
	s_nop 0
	s_nop 0
	s_nop 0
	s_nop 0
	s_nop 0
	s_nop 0
	s_nop 0
	s_nop 0
	s_nop 0
	s_nop 0
	s_nop 0
	s_nop 0
	s_nop 0
	s_nop 0
	s_nop 0
	s_nop 0
	s_nop 0
	s_nop 0
	s_nop 0
	s_nop 0
	s_nop 0
	s_nop 0
	s_nop 0
	s_nop 0
	s_nop 0
	s_nop 0
	s_nop 0
	s_nop 0
	s_nop 0
	s_nop 0
	s_nop 0
	s_nop 0
	s_nop 0
	s_nop 0
	s_nop 0
	s_nop 0
	s_nop 0
	s_nop 0
	s_nop 0
	s_nop 0
	s_nop 0
	s_nop 0
	s_nop 0
	s_nop 0
	s_nop 0
	s_nop 0
	s_nop 0
	s_nop 0
	s_nop 0
	s_nop 0
	s_nop 0
	s_nop 0
	s_nop 0
	s_nop 0
	s_nop 0
	s_nop 0
	s_nop 0
	s_nop 0
	s_nop 0
	s_nop 0
	s_nop 0
	s_nop 0
	s_nop 0
	s_nop 0
	s_nop 0
	s_nop 0
	s_nop 0
	s_nop 0
	s_nop 0
	s_nop 0
	s_nop 0
	s_nop 0
	s_nop 0
	s_nop 0
	s_nop 0
	s_nop 0
	s_nop 0
	s_nop 0
	s_nop 0
	s_nop 0
	s_nop 0
	s_nop 0
	s_nop 0
	s_nop 0
	s_nop 0
	s_nop 0
	s_nop 0
	s_nop 0
	s_nop 0
	s_nop 0
	s_nop 0
	s_nop 0
	s_nop 0
	s_nop 0
	s_nop 0
	s_nop 0
	s_nop 0
	s_nop 0
	s_nop 0
	s_nop 0
	s_nop 0
	s_nop 0
	s_nop 0
	s_nop 0
	s_nop 0
	s_nop 0
	s_nop 0
	s_nop 0
	s_nop 0
	s_nop 0
	s_nop 0
	s_nop 0
	s_nop 0
	s_nop 0
	s_nop 0
	s_nop 0
	s_nop 0
	s_nop 0
	s_nop 0
	s_nop 0
	s_nop 0
	s_nop 0
	s_nop 0
	s_nop 0
	s_nop 0
	s_nop 0
	s_nop 0
	s_nop 0
	s_nop 0
	s_nop 0
	s_nop 0
	s_nop 0
	s_nop 0
	s_nop 0
	s_nop 0
	s_nop 0
	s_nop 0
	s_nop 0
	s_nop 0
	s_nop 0
	s_nop 0
	s_nop 0
	s_nop 0
	s_nop 0
	s_nop 0
	s_nop 0
	s_nop 0
	s_nop 0
	s_nop 0
	s_nop 0
	s_nop 0
	s_nop 0
	s_nop 0
	s_nop 0
	s_nop 0
	s_nop 0
	s_nop 0
	s_nop 0
	s_nop 0
	s_nop 0
	s_nop 0
	s_nop 0
	s_nop 0
	s_nop 0
	s_nop 0
	s_nop 0
	s_nop 0
	s_nop 0
	s_nop 0
	s_nop 0
	s_nop 0
	s_nop 0
	s_nop 0
	s_nop 0
	s_nop 0
	s_nop 0
	s_nop 0
	s_nop 0
	s_nop 0
	s_nop 0
	s_nop 0
	s_nop 0
	s_nop 0
	s_nop 0
	s_nop 0
	s_nop 0
	s_nop 0
	s_nop 0
	s_nop 0
	s_nop 0
	s_nop 0
	s_nop 0
	s_nop 0
	s_nop 0
	s_nop 0
	s_nop 0
	s_nop 0
	s_nop 0
	s_nop 0
	s_nop 0
	s_nop 0
	s_nop 0
	s_nop 0
	s_nop 0
	s_nop 0
	s_nop 0
	s_nop 0
	s_nop 0
	s_nop 0
	s_nop 0
	s_nop 0
	s_nop 0
	s_nop 0
	s_nop 0
	s_nop 0
	s_nop 0
	s_nop 0
	s_nop 0
	s_nop 0
	s_nop 0
	s_nop 0
	s_nop 0
	s_nop 0
	s_nop 0
	s_nop 0
	s_nop 0
	s_nop 0
	s_nop 0
	s_nop 0
	s_nop 0
	s_nop 0
	s_nop 0
	s_nop 0
	s_nop 0
	s_nop 0
	s_nop 0
	s_nop 0
	s_nop 0
	s_nop 0
	s_nop 0
	s_nop 0
	s_nop 0
	s_nop 0
	s_nop 0
	s_nop 0
	s_nop 0
	s_nop 0
	s_nop 0
	s_nop 0
	s_nop 0
	s_nop 0
	s_nop 0
	s_nop 0
	s_nop 0
	s_nop 0
	s_nop 0
	s_nop 0
	s_nop 0
	s_nop 0
	s_nop 0
	s_nop 0
	s_nop 0
	s_nop 0
	s_nop 0
	s_nop 0
	s_nop 0
	s_nop 0
	s_nop 0
	s_nop 0
	s_nop 0
	s_nop 0
	s_nop 0
	s_nop 0
	s_nop 0
	s_nop 0
	s_nop 0
	s_nop 0
	s_nop 0
	s_nop 0
	s_nop 0
	s_nop 0
	s_nop 0
	s_nop 0
	s_nop 0
	s_nop 0
	s_nop 0
	s_nop 0
	s_nop 0
	s_nop 0
	s_nop 0
	s_nop 0
	s_nop 0
	s_nop 0
	s_nop 0
	s_nop 0
	s_nop 0
	s_nop 0
	s_nop 0
	s_nop 0
	s_nop 0
	s_nop 0
	s_nop 0
	s_nop 0
	s_nop 0
	s_nop 0
	s_nop 0
	s_nop 0
	s_nop 0
	s_nop 0
	s_nop 0
	s_nop 0
	s_nop 0
	s_nop 0
	s_nop 0
	s_nop 0
	s_nop 0
	s_nop 0
	s_nop 0
	s_nop 0
	s_nop 0
	s_nop 0
	s_nop 0
	s_nop 0
	s_nop 0
	s_nop 0
	s_nop 0
	s_nop 0
	s_nop 0
	s_nop 0
	s_nop 0
	s_nop 0
	s_nop 0
	s_nop 0
	s_nop 0
	s_nop 0
	s_nop 0
	s_nop 0
	s_nop 0
	s_nop 0
	s_nop 0
	s_nop 0
	s_nop 0
	s_nop 0
	s_nop 0
	s_nop 0
	s_nop 0
	s_nop 0
	s_nop 0
	s_nop 0
	s_nop 0
	s_nop 0
	s_nop 0
	s_nop 0
	s_nop 0
	s_nop 0
	s_nop 0
	s_nop 0
	s_nop 0
	s_nop 0
	s_nop 0
	s_nop 0
	s_nop 0
	s_nop 0
	s_nop 0
	s_nop 0
	s_nop 0
	s_nop 0
	s_nop 0
	s_nop 0
	s_nop 0
	s_nop 0
	s_nop 0
	s_nop 0
	s_nop 0
	s_nop 0
	s_nop 0
	s_nop 0
	s_nop 0
	s_nop 0
	s_nop 0
	s_nop 0
	s_nop 0
	s_nop 0
	s_nop 0
	s_nop 0
	s_nop 0
	s_nop 0
	s_nop 0
	s_nop 0
	s_nop 0
	s_nop 0
	s_nop 0
	s_nop 0
	s_nop 0
	s_nop 0
	s_nop 0
	s_nop 0
	s_nop 0
	s_nop 0
	s_nop 0
	s_nop 0
	s_nop 0
	s_nop 0
	s_nop 0
	s_nop 0
	s_nop 0
	s_nop 0
	s_nop 0
	s_nop 0
	s_nop 0
	s_nop 0
	s_nop 0
	s_nop 0
	s_nop 0
	s_nop 0
	s_nop 0
	s_nop 0
	s_nop 0
	s_nop 0
	s_nop 0
	s_nop 0
	s_nop 0
	s_nop 0
	s_nop 0
	s_nop 0
	s_nop 0
	s_nop 0
	s_nop 0
	s_nop 0
	s_nop 0
	s_nop 0
	s_nop 0
	s_nop 0
	s_nop 0
	s_nop 0
	s_nop 0
	s_nop 0
	s_nop 0
	s_nop 0
	s_nop 0
	s_nop 0
	s_nop 0
	s_nop 0
	s_nop 0
	s_nop 0
	s_nop 0
	s_nop 0
	s_nop 0
	s_nop 0
	s_nop 0
	s_nop 0
	s_nop 0
	s_nop 0
	s_nop 0
	s_nop 0
	s_nop 0
	s_nop 0
	s_nop 0
	s_nop 0
	s_nop 0
	s_nop 0
	s_nop 0
	s_nop 0
	s_nop 0
	s_nop 0
	s_nop 0
	s_nop 0
	s_nop 0
	s_nop 0
	s_nop 0
	s_nop 0
	s_nop 0
	s_nop 0
	s_nop 0
	s_nop 0
	s_nop 0
	s_nop 0
	s_nop 0
	s_nop 0
	s_nop 0
	s_nop 0
	s_nop 0
	s_nop 0
	s_nop 0
	s_nop 0
	s_nop 0
	s_nop 0
	s_nop 0
	s_nop 0
	s_nop 0
	s_nop 0
	s_nop 0
	s_nop 0
	s_nop 0
	s_nop 0
	s_nop 0
	s_nop 0
	s_nop 0
	s_nop 0
	s_nop 0
	s_nop 0
	s_nop 0
	s_nop 0
	s_nop 0
	s_nop 0
	s_nop 0
	s_nop 0
	s_nop 0
	s_nop 0
	s_nop 0
	s_nop 0
	s_nop 0
	s_nop 0
	s_nop 0
	s_nop 0
	s_nop 0
	s_nop 0
	s_nop 0
	s_nop 0
	s_nop 0
	s_nop 0
	s_nop 0
	s_nop 0
	s_nop 0
	s_nop 0
	s_nop 0
	s_nop 0
	s_nop 0
	s_nop 0
	s_nop 0
	s_nop 0
	s_nop 0
	s_nop 0
	s_nop 0
	s_nop 0
	s_nop 0
	s_nop 0
	s_nop 0
	s_nop 0
	s_nop 0
	s_nop 0
	s_nop 0
	s_nop 0
	s_nop 0
	s_nop 0
	s_nop 0
	s_nop 0
	s_nop 0
	s_nop 0
	s_nop 0
	s_nop 0
	s_nop 0
	s_nop 0
	s_nop 0
	s_nop 0
	s_nop 0
; DI void gla_gate_phase(const Params& P, LAS unsigned char* lds, int lj) {
;     ...
;   __syncthreads();
	s_nop 0
	s_nop 0
	s_nop 0
	s_nop 0
	s_nop 0
	s_nop 0
	s_nop 0
	s_nop 0
	s_nop 0
	s_nop 0
	s_nop 0
	s_nop 0
	s_nop 0
	s_nop 0
	s_nop 0
	s_nop 0
	s_nop 0
	s_nop 0
	s_nop 0
	s_nop 0
	s_nop 0
	s_nop 0
	s_nop 0
	s_nop 0
	s_nop 0
	s_nop 0
	s_nop 0
	s_nop 0
	s_nop 0
	s_nop 0
	s_nop 0
	s_nop 0
	s_nop 0
	s_nop 0
	s_nop 0
	s_nop 0
	s_nop 0
	s_nop 0
	s_nop 0
	s_nop 0
	s_nop 0
	s_nop 0
	s_nop 0
	s_nop 0
	s_nop 0
	s_nop 0
	s_nop 0
	s_nop 0
	s_nop 0
	s_nop 0
	s_nop 0
	s_nop 0
	s_nop 0
	s_nop 0
	s_nop 0
	s_nop 0
	s_nop 0
	s_nop 0
	s_nop 0
	s_nop 0
	s_nop 0
	s_nop 0
	s_nop 0
	s_nop 0
	s_nop 0
	s_nop 0
	s_nop 0
	s_nop 0
	s_nop 0
	s_nop 0
	s_nop 0
	s_nop 0
	s_nop 0
	s_nop 0
	s_nop 0
	s_nop 0
	s_nop 0
	s_nop 0
	s_nop 0
	s_nop 0
	s_nop 0
	s_nop 0
	s_nop 0
	s_nop 0
	s_nop 0
	s_nop 0
	s_nop 0
	s_nop 0
	s_nop 0
	s_nop 0
	s_nop 0
	s_nop 0
	s_nop 0
	s_nop 0
	s_nop 0
	s_nop 0
	s_nop 0
	s_nop 0
	s_nop 0
	s_nop 0
	s_nop 0
	s_nop 0
	s_nop 0
	s_nop 0
	s_nop 0
	s_nop 0
	s_nop 0
	s_nop 0
	s_nop 0
	s_nop 0
	s_nop 0
	s_nop 0
	s_nop 0
	s_nop 0
	s_nop 0
	s_nop 0
	s_nop 0
	s_nop 0
	s_nop 0
	s_nop 0
	s_nop 0
	s_nop 0
	s_nop 0
	s_nop 0
	s_nop 0
	s_nop 0
	s_nop 0
	s_nop 0
	s_nop 0
	s_nop 0
	s_nop 0
	s_nop 0
	s_nop 0
	s_nop 0
	s_nop 0
	s_nop 0
	s_nop 0
	s_nop 0
	s_nop 0
	s_nop 0
	s_nop 0
	s_nop 0
	s_nop 0
	s_nop 0
	s_nop 0
	s_nop 0
	s_nop 0
	s_nop 0
	s_nop 0
	s_nop 0
	s_nop 0
	s_nop 0
	s_nop 0
	s_nop 0
	s_nop 0
	s_nop 0
	s_nop 0
	s_nop 0
	s_nop 0
	s_nop 0
	s_nop 0
	s_nop 0
	s_nop 0
	s_nop 0
	s_nop 0
	s_nop 0
	s_nop 0
	s_nop 0
	s_nop 0
	s_nop 0
	s_nop 0
	s_nop 0
	s_nop 0
	s_nop 0
	s_nop 0
	s_nop 0
	s_nop 0
	s_nop 0
	s_nop 0
	s_nop 0
	s_nop 0
	s_nop 0
	s_nop 0
	s_nop 0
	s_nop 0
	s_nop 0
	s_nop 0
	s_nop 0
	s_nop 0
	s_nop 0
	s_nop 0
	s_nop 0
	s_nop 0
	s_nop 0
	s_nop 0
	s_nop 0
	s_nop 0
	s_nop 0
	s_nop 0
	s_nop 0
	s_nop 0
	s_nop 0
	s_nop 0
	s_nop 0
	s_nop 0
	s_nop 0
	s_nop 0
	s_nop 0
	s_nop 0
	s_nop 0
	s_nop 0
	s_nop 0
	s_nop 0
	s_nop 0
	s_nop 0
	s_nop 0
	s_nop 0
	s_nop 0
	s_nop 0
	s_nop 0
	s_nop 0
	s_nop 0
	s_nop 0
	s_nop 0
	s_nop 0
	s_nop 0
	s_nop 0
	s_nop 0
	s_nop 0
	s_nop 0
	s_nop 0
	s_nop 0
	s_nop 0
	s_nop 0
	s_nop 0
	s_nop 0
	s_nop 0
	s_nop 0
	s_nop 0
	s_nop 0
	s_nop 0
	s_nop 0
	s_nop 0
	s_nop 0
	s_nop 0
	s_nop 0
	s_nop 0
	s_nop 0
	s_nop 0
	s_nop 0
	s_nop 0
	s_nop 0
	s_nop 0
	s_nop 0
	s_nop 0
	s_nop 0
	s_nop 0
	s_nop 0
	s_nop 0
	s_nop 0
	s_nop 0
	s_nop 0
	s_nop 0
	s_nop 0
	s_nop 0
	s_nop 0
	s_nop 0
	s_nop 0
	s_nop 0
	s_nop 0
	s_nop 0
	s_nop 0
	s_nop 0
	s_nop 0
	s_nop 0
	s_nop 0
	s_nop 0
	s_nop 0
	s_nop 0
	s_nop 0
	s_nop 0
	s_nop 0
	s_nop 0
	s_nop 0
	s_nop 0
	s_nop 0
	s_nop 0
	s_nop 0
	s_nop 0
	s_nop 0
	s_nop 0
	s_nop 0
	s_nop 0
	s_nop 0
	s_nop 0
	s_nop 0
	s_nop 0
	s_nop 0
	s_nop 0
	s_nop 0
	s_nop 0
	s_nop 0
	s_nop 0
	s_nop 0
	s_nop 0
	s_nop 0
	s_nop 0
	s_nop 0
	s_nop 0
	s_nop 0
	s_nop 0
	s_nop 0
	s_nop 0
	s_nop 0
	s_nop 0
	s_nop 0
	s_nop 0
	s_nop 0
	s_nop 0
	s_nop 0
	s_nop 0
	s_nop 0
	s_nop 0
	s_nop 0
	s_nop 0
	s_nop 0
	s_nop 0
	s_nop 0
	s_nop 0
	s_nop 0
	s_nop 0
	s_nop 0
	s_nop 0
	s_nop 0
	s_nop 0
	s_nop 0
	s_nop 0
	s_nop 0
	s_nop 0
	s_nop 0
	s_nop 0
	s_nop 0
	s_nop 0
	s_nop 0
	s_nop 0
	s_nop 0
	s_nop 0
	s_nop 0
	s_nop 0
	s_nop 0
	s_nop 0
	s_nop 0
	s_nop 0
	s_nop 0
	s_nop 0
	s_nop 0
	s_nop 0
	s_nop 0
	s_nop 0
	s_nop 0
	s_nop 0
	s_nop 0
	s_nop 0
	s_nop 0
	s_nop 0
	s_nop 0
	s_nop 0
	s_nop 0
	s_nop 0
	s_nop 0
	s_nop 0
	s_nop 0
	s_nop 0
	s_nop 0
	s_nop 0
	s_nop 0
	s_nop 0
	s_nop 0
	s_nop 0
	s_nop 0
	s_nop 0
	s_nop 0
	s_nop 0
	s_nop 0
	s_nop 0
	s_nop 0
	s_nop 0
	s_nop 0
	s_nop 0
	s_nop 0
	s_nop 0
	s_nop 0
	s_nop 0
	s_nop 0
	s_nop 0
	s_nop 0
	s_nop 0
	s_nop 0
	s_nop 0
	s_nop 0
	s_nop 0
	s_nop 0
	s_nop 0
	s_nop 0
	s_nop 0
	s_nop 0
	s_nop 0
	s_nop 0
	s_nop 0
	s_nop 0
	s_nop 0
	s_nop 0
	s_nop 0
	s_nop 0
	s_nop 0
	s_nop 0
	s_nop 0
	s_nop 0
	s_nop 0
	s_nop 0
	s_nop 0
	s_nop 0
	s_nop 0
	s_nop 0
	s_nop 0
	s_nop 0
	s_nop 0
	s_nop 0
	s_nop 0
	s_nop 0
	s_nop 0
	s_nop 0
	s_nop 0
	s_nop 0
	s_nop 0
	s_nop 0
	s_nop 0
	s_nop 0
	s_nop 0
	s_nop 0
	s_nop 0
	s_nop 0
	s_nop 0
	s_nop 0
	s_nop 0
	s_nop 0
	s_nop 0
	s_nop 0
	s_nop 0
	s_nop 0
	s_nop 0
	s_nop 0
	s_nop 0
	s_nop 0
	s_nop 0
	s_nop 0
	s_nop 0
	s_nop 0
	s_nop 0
	s_nop 0
	s_nop 0
	s_nop 0
	s_nop 0
	s_nop 0
	s_nop 0
	s_nop 0
	s_nop 0
	s_nop 0
	s_nop 0
	s_nop 0
	s_nop 0
	s_nop 0
	s_nop 0
	s_nop 0
	s_nop 0
	s_nop 0
	s_nop 0
	s_nop 0
	s_nop 0
	s_nop 0
	s_nop 0
	s_nop 0
	s_nop 0
	s_nop 0
	s_nop 0
	s_nop 0
	s_nop 0
	s_nop 0
	s_nop 0
	s_nop 0
	s_nop 0
	s_nop 0
	s_nop 0
	s_nop 0
	s_nop 0
	s_nop 0
	s_nop 0
	s_nop 0
	s_nop 0
	s_nop 0
	s_nop 0
	s_nop 0
	s_nop 0
	s_nop 0
	s_nop 0
	s_nop 0
	s_nop 0
	s_nop 0
	s_nop 0
	s_nop 0
	s_nop 0
	s_nop 0
	s_nop 0
	s_nop 0
	s_nop 0
	s_nop 0
	s_nop 0
	s_nop 0
	s_nop 0
	s_nop 0
	s_nop 0
	s_nop 0
	s_nop 0
	s_nop 0
	s_nop 0
	s_nop 0
	s_nop 0
	s_nop 0
	s_nop 0
	s_nop 0
	s_nop 0
	s_nop 0
	s_nop 0
	s_nop 0
	s_nop 0
	s_nop 0
	s_nop 0
	s_nop 0
	s_nop 0
	s_nop 0
	s_nop 0
	s_nop 0
	s_nop 0
	s_nop 0
	s_nop 0
	s_nop 0
	s_nop 0
	s_nop 0
	s_nop 0
	s_nop 0
	s_nop 0
	s_nop 0
	s_nop 0
	s_nop 0
	s_nop 0
	s_nop 0
	s_nop 0
	s_nop 0
	s_nop 0
	s_nop 0
	s_nop 0
	s_nop 0
	s_nop 0
	s_nop 0
	s_nop 0
	s_nop 0
	s_nop 0
	s_nop 0
	s_nop 0
	s_nop 0
	s_nop 0
	s_nop 0
	s_nop 0
	s_nop 0
	s_nop 0
	s_nop 0
	s_nop 0
	s_nop 0
	s_nop 0
	s_nop 0
	s_nop 0
	s_nop 0
	s_nop 0
	s_nop 0
	s_nop 0
	s_nop 0
	s_nop 0
	s_nop 0
	s_nop 0
	s_nop 0
	s_nop 0
	s_nop 0
	s_nop 0
	s_nop 0
	s_nop 0
	s_nop 0
	s_nop 0
	s_nop 0
	s_nop 0
	s_nop 0
	s_nop 0
	s_nop 0
	s_nop 0
	s_nop 0
	s_nop 0
	s_nop 0
	s_nop 0
	s_nop 0
	s_nop 0
	s_nop 0
	s_nop 0
	s_nop 0
	s_nop 0
	s_nop 0
	s_nop 0
	s_nop 0
	s_nop 0
	s_nop 0
	s_nop 0
	s_nop 0
	s_nop 0
	s_nop 0
	s_nop 0
	s_nop 0
	s_nop 0
	s_nop 0
	s_nop 0
; #define LAS __attribute__((address_space(3)))
; DI float bf2f(bf16_t v) { return __uint_as_float(((unsigned)v) << 16); }
; DI bf16_t f2bf(float f) { return (bf16_t)(cvt_pk(f, 0.f) & 0xffffu); }
; DI float logsig16(float z) { return (fminf(z, 0.f) - __logf(1.0f + __expf(-fabsf(z)))) * (1.0f / 16.0f); }
; DI void gla_gate_phase(const Params& P, LAS unsigned char* lds, int lj) {
;     ...
;   for (int item = blockIdx.x; item < 512; item += gridDim.x) {
;     __syncthreads();
;     { const int row = tid >> 3, part = tid & 7; *(LAS f32x4*)(zL + row * 32 + part * 4) = *(const f32x4*)(zbuf + ((size_t)item * 64 + row) * 32 + part * 4); }
;     __syncthreads();
;     float lsb[64]; float totb = 0.f;
; #pragma unroll
;     for (int i = 0; i < 64; ++i) {
;       float z = bb_;
; #pragma unroll
;       for (int j4 = 0; j4 < 4; ++j4) { const f32x4 zz = *(const LAS f32x4*)(zL + i * 32 + 16 + j4 * 4); z += zz[0] * wb[j4 * 4] + zz[1] * wb[j4 * 4 + 1] + zz[2] * wb[j4 * 4 + 2] + zz[3] * wb[j4 * 4 + 3]; }
;       lsb[i] = logsig16(z); totb += lsb[i];
;     }
;     float runf = 0.f, runb = 0.f;
; #pragma unroll
;     for (int ib = 0; ib < 4; ++ib) {
;       bf16_t qraw[16], kraw[16];
; #pragma unroll
;       for (int ii = 0; ii < 16; ++ii) { const bf16_t* pr = proj + ((size_t)item * 64 + ib * 16 + ii) * 3072 + col; qraw[ii] = pr[0]; kraw[ii] = pr[512]; }
;       asm volatile("" ::: "memory");
; #pragma unroll
;       for (int ii = 0; ii < 16; ++ii) {
;         const int i = ib * 16 + ii;
;         float z = bf_;
; #pragma unroll
;         for (int j4 = 0; j4 < 4; ++j4) { const f32x4 zz = *(const LAS f32x4*)(zL + i * 32 + j4 * 4); z += zz[0] * wf[j4 * 4] + zz[1] * wf[j4 * 4 + 1] + zz[2] * wf[j4 * 4 + 2] + zz[3] * wf[j4 * 4 + 3]; }
;         runf += logsig16(z);
;         const float Bi = totb - runb; runb += lsb[i];
;         const size_t tokrow = (size_t)item * 64 + i;
;         bf16_t* pr = proj + tokrow * 3072 + col;
;         const float q = bf2f(qraw[ii]), k = bf2f(kraw[ii]);
;         pr[0] = f2bf(q * __expf(runf)); pr[512] = f2bf(k * __expf(-runf));
;         QB[tokrow * 512 + col] = f2bf(q * __expf(Bi)); KB[tokrow * 512 + col] = f2bf(k * __expf(-Bi));
;       }
;       asm volatile("" ::: "memory");
;     }
;     dect[(size_t)item * 512 + col] = __expf(runf);
;     dect[(size_t)(512 + item) * 512 + col] = __expf(totb);
;   }
	s_nop 0
	s_nop 0
	s_nop 0
	s_nop 0
	s_nop 0
	s_nop 0
	s_nop 0
	s_nop 0
	s_nop 0
	s_nop 0
	s_nop 0
	s_nop 0
	s_nop 0
	s_nop 0
	s_nop 0
	s_nop 0
	s_nop 0
	s_nop 0
	s_nop 0
	s_nop 0
	s_nop 0
	s_nop 0
	s_nop 0
	s_nop 0
	s_nop 0
	s_nop 0
	s_nop 0
	s_nop 0
	s_nop 0
	s_nop 0
	s_nop 0
	s_nop 0
	s_nop 0
	s_nop 0
	s_nop 0
	s_nop 0
	s_nop 0
	s_nop 0
	s_nop 0
	s_nop 0
	s_nop 0
	s_nop 0
	s_nop 0
	s_nop 0
	s_nop 0
	s_nop 0
	s_nop 0
	s_nop 0
	s_nop 0
	s_nop 0
	s_nop 0
	s_nop 0
	s_nop 0
	s_nop 0
	s_nop 0
	s_nop 0
	s_nop 0
	s_nop 0
	s_nop 0
	s_nop 0
	s_nop 0
	s_nop 0
	s_nop 0
	s_nop 0
	s_nop 0
	s_nop 0
	s_nop 0
	s_nop 0
	s_nop 0
	s_nop 0
	s_nop 0
	s_nop 0
	s_nop 0
	s_nop 0
	s_nop 0
	s_nop 0
	s_nop 0
	s_nop 0
	s_nop 0
	s_nop 0
	s_nop 0
	s_nop 0
	s_nop 0
	s_nop 0
	s_nop 0
	s_nop 0
	s_nop 0
	s_nop 0
	s_nop 0
	s_nop 0
	s_nop 0
	s_nop 0
	s_nop 0
	s_nop 0
	s_nop 0
	s_nop 0
	s_nop 0
	s_nop 0
	s_nop 0
	s_nop 0
	s_nop 0
	s_nop 0
	s_nop 0
	s_nop 0
	s_nop 0
	s_nop 0
	s_nop 0
	s_nop 0
	s_nop 0
	s_nop 0
	s_nop 0
	s_nop 0
	s_nop 0
	s_nop 0
	s_nop 0
	s_nop 0
	s_nop 0
	s_nop 0
	s_nop 0
	s_nop 0
	s_nop 0
	s_nop 0
	s_nop 0
	s_nop 0
	s_nop 0
	s_nop 0
	s_nop 0
	s_nop 0
	s_nop 0
	s_nop 0
	s_nop 0
	s_nop 0
	s_nop 0
	s_nop 0
	s_nop 0
	s_nop 0
	s_nop 0
	s_nop 0
	s_nop 0
	s_nop 0
	s_nop 0
	s_nop 0
	s_nop 0
	s_nop 0
	s_nop 0
	s_nop 0
	s_nop 0
	s_nop 0
	s_nop 0
	s_nop 0
	s_nop 0
	s_nop 0
	s_nop 0
	s_nop 0
	s_nop 0
	s_nop 0
	s_nop 0
	s_nop 0
	s_nop 0
	s_nop 0
	s_nop 0
	s_nop 0
	s_nop 0
	s_nop 0
	s_nop 0
	s_nop 0
	s_nop 0
	s_nop 0
	s_nop 0
	s_nop 0
	s_nop 0
	s_nop 0
	s_nop 0
	s_nop 0
	s_nop 0
	s_nop 0
	s_nop 0
	s_nop 0
	s_nop 0
	s_nop 0
	s_nop 0
	s_nop 0
	s_nop 0
	s_nop 0
	s_nop 0
	s_nop 0
	s_nop 0
	s_nop 0
	s_nop 0
	s_nop 0
	s_nop 0
	s_nop 0
	s_nop 0
	s_nop 0
	s_nop 0
	s_nop 0
	s_nop 0
	s_nop 0
	s_nop 0
	s_nop 0
	s_nop 0
	s_nop 0
	s_nop 0
	s_nop 0
	s_nop 0
	s_nop 0
	s_nop 0
	s_nop 0
	s_nop 0
	s_nop 0
	s_nop 0
	s_nop 0
	s_nop 0
	s_nop 0
	s_nop 0
	s_nop 0
	s_nop 0
	s_nop 0
	s_nop 0
	s_nop 0
	s_nop 0
	s_nop 0
	s_nop 0
	s_nop 0
	s_nop 0
	s_nop 0
	s_nop 0
	s_nop 0
	s_nop 0
	s_nop 0
	s_nop 0
	s_nop 0
	s_nop 0
	s_nop 0
	s_nop 0
	s_nop 0
	s_nop 0
	s_nop 0
	s_nop 0
	s_nop 0
	s_nop 0
	s_nop 0
	s_nop 0
	s_nop 0
	s_nop 0
	s_nop 0
	s_nop 0
	s_nop 0
	s_nop 0
	s_nop 0
	s_nop 0
	s_nop 0
	s_nop 0
	s_nop 0
	s_nop 0
	s_nop 0
	s_nop 0
	s_nop 0
	s_nop 0
	s_nop 0
	s_nop 0
	s_nop 0
	s_nop 0
	s_nop 0
	s_nop 0
	s_nop 0
	s_nop 0
	s_nop 0
	s_nop 0
	s_nop 0
	s_nop 0
	s_nop 0
	s_nop 0
	s_nop 0
	s_nop 0
	s_nop 0
	s_nop 0
	s_nop 0
	s_nop 0
	s_nop 0
	s_nop 0
	s_nop 0
	s_nop 0
	s_nop 0
	s_nop 0
	s_nop 0
	s_nop 0
	s_nop 0
	s_nop 0
	s_nop 0
	s_nop 0
	s_nop 0
	s_nop 0
	s_nop 0
	s_nop 0
	s_nop 0
	s_nop 0
	s_nop 0
	s_nop 0
	s_nop 0
	s_nop 0
	s_nop 0
	s_nop 0
	s_nop 0
	s_nop 0
	s_nop 0
	s_nop 0
	s_nop 0
	s_nop 0
	s_nop 0
	s_nop 0
	s_nop 0
	s_nop 0
	s_nop 0
	s_nop 0
	s_nop 0
	s_nop 0
	s_nop 0
	s_nop 0
	s_nop 0
	s_nop 0
	s_nop 0
	s_nop 0
	s_nop 0
	s_nop 0
	s_nop 0
	s_nop 0
	s_nop 0
	s_nop 0
	s_nop 0
	s_nop 0
	s_nop 0
	s_nop 0
	s_nop 0
	s_nop 0
	s_nop 0
	s_nop 0
	s_nop 0
	s_nop 0
	s_nop 0
	s_nop 0
	s_nop 0
	s_nop 0
	s_nop 0
	s_nop 0
	s_nop 0
	s_nop 0
	s_nop 0
	s_nop 0
	s_nop 0
	s_nop 0
	s_nop 0
	s_nop 0
	s_nop 0
	s_nop 0
	s_nop 0
	s_nop 0
	s_nop 0
	s_nop 0
	s_nop 0
	s_nop 0
	s_nop 0
	s_nop 0
	s_nop 0
	s_nop 0
	s_nop 0
	s_nop 0
	s_nop 0
	s_nop 0
	s_nop 0
	s_nop 0
	s_nop 0
	s_nop 0
	s_nop 0
	s_nop 0
	s_nop 0
	s_nop 0
	s_nop 0
	s_nop 0
	s_nop 0
	s_nop 0
	s_nop 0
	s_nop 0
	s_nop 0
	s_nop 0
	s_nop 0
	s_nop 0
	s_nop 0
	s_nop 0
	s_nop 0
	s_nop 0
	s_nop 0
	s_nop 0
	s_nop 0
	s_nop 0
	s_nop 0
	s_nop 0
	s_nop 0
	s_nop 0
	s_nop 0
	s_nop 0
	s_nop 0
	s_nop 0
	s_nop 0
	s_nop 0
	s_nop 0
	s_nop 0
	s_nop 0
	s_nop 0
	s_nop 0
	s_nop 0
	s_nop 0
	s_nop 0
	s_nop 0
	s_nop 0
	s_nop 0
	s_nop 0
	s_nop 0
	s_nop 0
	s_nop 0
	s_nop 0
	s_nop 0
	s_nop 0
	s_nop 0
	s_nop 0
	s_nop 0
	s_nop 0
	s_nop 0
	s_nop 0
	s_nop 0
	s_nop 0
	s_nop 0
	s_nop 0
	s_nop 0
	s_nop 0
	s_nop 0
	s_nop 0
	s_nop 0
	s_nop 0
	s_nop 0
	s_nop 0
	s_nop 0
	s_nop 0
	s_nop 0
	s_nop 0
	s_nop 0
	s_nop 0
	s_nop 0
	s_nop 0
	s_nop 0
	s_nop 0
	s_nop 0
	s_nop 0
	s_nop 0
	s_nop 0
	s_nop 0
	s_nop 0
	s_nop 0
	s_nop 0
	s_nop 0
	s_nop 0
	s_nop 0
	s_nop 0
	s_nop 0
	s_nop 0
	s_nop 0
	s_nop 0
	s_nop 0
	s_nop 0
	s_nop 0
	s_nop 0
	s_nop 0
	s_nop 0
	s_nop 0
	s_nop 0
	s_nop 0
	s_nop 0
	s_nop 0
	s_nop 0
	s_nop 0
	s_nop 0
	s_nop 0
	s_nop 0
	s_nop 0
	s_nop 0
	s_nop 0
	s_nop 0
	s_nop 0
	s_nop 0
	s_nop 0
	s_nop 0
	s_nop 0
	s_nop 0
	s_nop 0
	s_nop 0
	s_nop 0
	s_nop 0
	s_nop 0
	s_nop 0
	s_nop 0
	s_nop 0
	s_nop 0
	s_nop 0
	s_nop 0
	s_nop 0
	s_nop 0
	s_nop 0
	s_nop 0
	s_nop 0
	s_nop 0
	s_nop 0
	s_nop 0
	s_nop 0
	s_nop 0
	s_nop 0
	s_nop 0
	s_nop 0
	s_nop 0
	s_nop 0
	s_nop 0
	s_nop 0
	s_nop 0
	s_nop 0
	s_nop 0
	s_nop 0
	s_nop 0
	s_nop 0
	s_nop 0
	s_nop 0
	s_nop 0
	s_nop 0
	s_nop 0
	s_nop 0
	s_nop 0
	s_nop 0
	s_nop 0
	s_nop 0
	s_nop 0
	s_nop 0
	s_nop 0
	s_nop 0
	s_nop 0
	s_nop 0
	s_nop 0
	s_nop 0
	s_nop 0
	s_nop 0
	s_nop 0
	s_nop 0
	s_nop 0
	s_nop 0
	s_nop 0
	s_nop 0
	s_nop 0
	s_nop 0
	s_nop 0
	s_nop 0
	s_nop 0
	s_nop 0
	s_nop 0
	s_nop 0
	s_nop 0
	s_nop 0
	s_nop 0
	s_nop 0
	s_nop 0
	s_nop 0
	s_nop 0
	s_nop 0
	s_nop 0
	s_nop 0
	s_nop 0
	s_nop 0
	s_nop 0
	s_nop 0
	s_nop 0
	s_nop 0
	s_nop 0
	s_nop 0
	s_nop 0
	s_nop 0
	s_nop 0
	s_nop 0
	s_nop 0
	s_nop 0
	s_nop 0
	s_nop 0
	s_nop 0
	s_nop 0
	s_nop 0
	s_nop 0
	s_nop 0
	s_nop 0
	s_nop 0
	s_nop 0
	s_nop 0
	s_nop 0
	s_nop 0
	s_nop 0
	s_nop 0
	s_nop 0
	s_nop 0
	s_nop 0
	s_nop 0
	s_nop 0
	s_nop 0
	s_nop 0
	s_nop 0
	s_nop 0
	s_nop 0
	s_nop 0
	s_nop 0
	s_nop 0
	s_nop 0
	s_nop 0
	s_nop 0
	s_nop 0
	s_nop 0
	s_nop 0
	s_nop 0
	s_nop 0
	s_nop 0
	s_nop 0
	s_nop 0
	s_nop 0
	s_nop 0
	s_nop 0
; #define LAS __attribute__((address_space(3)))
; DI float bf2f(bf16_t v) { return __uint_as_float(((unsigned)v) << 16); }
; DI bf16_t f2bf(float f) { return (bf16_t)(cvt_pk(f, 0.f) & 0xffffu); }
; DI float logsig16(float z) { return (fminf(z, 0.f) - __logf(1.0f + __expf(-fabsf(z)))) * (1.0f / 16.0f); }
; DI void gla_gate_phase(const Params& P, LAS unsigned char* lds, int lj) {
;     ...
;   for (int item = blockIdx.x; item < 512; item += gridDim.x) {
;     __syncthreads();
;     { const int row = tid >> 3, part = tid & 7; *(LAS f32x4*)(zL + row * 32 + part * 4) = *(const f32x4*)(zbuf + ((size_t)item * 64 + row) * 32 + part * 4); }
;     __syncthreads();
;     float lsb[64]; float totb = 0.f;
; #pragma unroll
;     for (int i = 0; i < 64; ++i) {
;       float z = bb_;
; #pragma unroll
;       for (int j4 = 0; j4 < 4; ++j4) { const f32x4 zz = *(const LAS f32x4*)(zL + i * 32 + 16 + j4 * 4); z += zz[0] * wb[j4 * 4] + zz[1] * wb[j4 * 4 + 1] + zz[2] * wb[j4 * 4 + 2] + zz[3] * wb[j4 * 4 + 3]; }
;       lsb[i] = logsig16(z); totb += lsb[i];
;     }
;     float runf = 0.f, runb = 0.f;
; #pragma unroll
;     for (int ib = 0; ib < 4; ++ib) {
;       bf16_t qraw[16], kraw[16];
; #pragma unroll
;       for (int ii = 0; ii < 16; ++ii) { const bf16_t* pr = proj + ((size_t)item * 64 + ib * 16 + ii) * 3072 + col; qraw[ii] = pr[0]; kraw[ii] = pr[512]; }
;       asm volatile("" ::: "memory");
; #pragma unroll
;       for (int ii = 0; ii < 16; ++ii) {
;         const int i = ib * 16 + ii;
;         float z = bf_;
; #pragma unroll
;         for (int j4 = 0; j4 < 4; ++j4) { const f32x4 zz = *(const LAS f32x4*)(zL + i * 32 + j4 * 4); z += zz[0] * wf[j4 * 4] + zz[1] * wf[j4 * 4 + 1] + zz[2] * wf[j4 * 4 + 2] + zz[3] * wf[j4 * 4 + 3]; }
;         runf += logsig16(z);
;         const float Bi = totb - runb; runb += lsb[i];
;         const size_t tokrow = (size_t)item * 64 + i;
;         bf16_t* pr = proj + tokrow * 3072 + col;
;         const float q = bf2f(qraw[ii]), k = bf2f(kraw[ii]);
;         pr[0] = f2bf(q * __expf(runf)); pr[512] = f2bf(k * __expf(-runf));
;         QB[tokrow * 512 + col] = f2bf(q * __expf(Bi)); KB[tokrow * 512 + col] = f2bf(k * __expf(-Bi));
;       }
;       asm volatile("" ::: "memory");
;     }
;     dect[(size_t)item * 512 + col] = __expf(runf);
;     dect[(size_t)(512 + item) * 512 + col] = __expf(totb);
;   }
	s_nop 0
	s_nop 0
	s_nop 0
	s_nop 0
	s_nop 0
	s_nop 0
	s_nop 0
	s_nop 0
	s_nop 0
	s_nop 0
	s_nop 0
	s_nop 0
	s_nop 0
	s_nop 0
	s_nop 0
	s_nop 0
	s_nop 0
	s_nop 0
	s_nop 0
	s_nop 0
	s_nop 0
	s_nop 0
	s_nop 0
	s_nop 0
	s_nop 0
	s_nop 0
	s_nop 0
	s_nop 0
	s_nop 0
	s_nop 0
	s_nop 0
	s_nop 0
	s_nop 0
	s_nop 0
	s_nop 0
	s_nop 0
	s_nop 0
	s_nop 0
	s_nop 0
	s_nop 0
	s_nop 0
	s_nop 0
	s_nop 0
	s_nop 0
	s_nop 0
	s_nop 0
	s_nop 0
	s_nop 0
	s_nop 0
	s_nop 0
	s_nop 0
	s_nop 0
	s_nop 0
	s_nop 0
	s_nop 0
	s_nop 0
	s_nop 0
	s_nop 0
	s_nop 0
	s_nop 0
	s_nop 0
	s_nop 0
	s_nop 0
	s_nop 0
	s_nop 0
	s_nop 0
	s_nop 0
	s_nop 0
	s_nop 0
	s_nop 0
	s_nop 0
	s_nop 0
	s_nop 0
	s_nop 0
	s_nop 0
	s_nop 0
	s_nop 0
	s_nop 0
	s_nop 0
	s_nop 0
	s_nop 0
	s_nop 0
	s_nop 0
	s_nop 0
	s_nop 0
	s_nop 0
	s_nop 0
	s_nop 0
	s_nop 0
	s_nop 0
	s_nop 0
	s_nop 0
	s_nop 0
	s_nop 0
	s_nop 0
	s_nop 0
	s_nop 0
	s_nop 0
	s_nop 0
	s_nop 0
	s_nop 0
	s_nop 0
	s_nop 0
	s_nop 0
	s_nop 0
	s_nop 0
	s_nop 0
	s_nop 0
	s_nop 0
	s_nop 0
	s_nop 0
	s_nop 0
	s_nop 0
	s_nop 0
	s_nop 0
	s_nop 0
	s_nop 0
	s_nop 0
	s_nop 0
	s_nop 0
	s_nop 0
	s_nop 0
	s_nop 0
	s_nop 0
	s_nop 0
	s_nop 0
	s_nop 0
	s_nop 0
	s_nop 0
	s_nop 0
	s_nop 0
	s_nop 0
	s_nop 0
	s_nop 0
	s_nop 0
	s_nop 0
	s_nop 0
	s_nop 0
	s_nop 0
	s_nop 0
	s_nop 0
	s_nop 0
	s_nop 0
	s_nop 0
	s_nop 0
	s_nop 0
	s_nop 0
	s_nop 0
	s_nop 0
	s_nop 0
	s_nop 0
	s_nop 0
	s_nop 0
	s_nop 0
	s_nop 0
	s_nop 0
	s_nop 0
	s_nop 0
	s_nop 0
	s_nop 0
	s_nop 0
	s_nop 0
	s_nop 0
	s_nop 0
	s_nop 0
	s_nop 0
	s_nop 0
	s_nop 0
	s_nop 0
	s_nop 0
	s_nop 0
	s_nop 0
	s_nop 0
	s_nop 0
	s_nop 0
	s_nop 0
	s_nop 0
	s_nop 0
	s_nop 0
	s_nop 0
	s_nop 0
	s_nop 0
	s_nop 0
	s_nop 0
	s_nop 0
	s_nop 0
	s_nop 0
	s_nop 0
	s_nop 0
	s_nop 0
	s_nop 0
	s_nop 0
	s_nop 0
	s_nop 0
	s_nop 0
	s_nop 0
	s_nop 0
	s_nop 0
	s_nop 0
	s_nop 0
	s_nop 0
	s_nop 0
	s_nop 0
	s_nop 0
	s_nop 0
	s_nop 0
	s_nop 0
	s_nop 0
	s_nop 0
	s_nop 0
	s_nop 0
	s_nop 0
	s_nop 0
	s_nop 0
	s_nop 0
	s_nop 0
	s_nop 0
	s_nop 0
	s_nop 0
	s_nop 0
	s_nop 0
	s_nop 0
	s_nop 0
	s_nop 0
	s_nop 0
	s_nop 0
	s_nop 0
	s_nop 0
	s_nop 0
	s_nop 0
	s_nop 0
	s_nop 0
	s_nop 0
	s_nop 0
	s_nop 0
	s_nop 0
	s_nop 0
	s_nop 0
	s_nop 0
	s_nop 0
	s_nop 0
	s_nop 0
	s_nop 0
	s_nop 0
	s_nop 0
	s_nop 0
	s_nop 0
	s_nop 0
	s_nop 0
	s_nop 0
	s_nop 0
	s_nop 0
	s_nop 0
	s_nop 0
	s_nop 0
	s_nop 0
	s_nop 0
	s_nop 0
	s_nop 0
	s_nop 0
	s_nop 0
	s_nop 0
	s_nop 0
	s_nop 0
	s_nop 0
	s_nop 0
	s_nop 0
	s_nop 0
	s_nop 0
	s_nop 0
	s_nop 0
	s_nop 0
	s_nop 0
	s_nop 0
	s_nop 0
	s_nop 0
	s_nop 0
	s_nop 0
	s_nop 0
	s_nop 0
	s_nop 0
	s_nop 0
	s_nop 0
	s_nop 0
	s_nop 0
	s_nop 0
	s_nop 0
	s_nop 0
	s_nop 0
	s_nop 0
	s_nop 0
	s_nop 0
	s_nop 0
	s_nop 0
	s_nop 0
	s_nop 0
	s_nop 0
	s_nop 0
	s_nop 0
	s_nop 0
	s_nop 0
	s_nop 0
	s_nop 0
	s_nop 0
	s_nop 0
	s_nop 0
	s_nop 0
	s_nop 0
	s_nop 0
	s_nop 0
	s_nop 0
	s_nop 0
	s_nop 0
	s_nop 0
	s_nop 0
	s_nop 0
	s_nop 0
	s_nop 0
	s_nop 0
	s_nop 0
	s_nop 0
	s_nop 0
	s_nop 0
	s_nop 0
	s_nop 0
	s_nop 0
	s_nop 0
	s_nop 0
	s_nop 0
	s_nop 0
	s_nop 0
	s_nop 0
	s_nop 0
	s_nop 0
	s_nop 0
	s_nop 0
	s_nop 0
	s_nop 0
	s_nop 0
	s_nop 0
	s_nop 0
	s_nop 0
	s_nop 0
	s_nop 0
	s_nop 0
	s_nop 0
	s_nop 0
	s_nop 0
	s_nop 0
	s_nop 0
	s_nop 0
	s_nop 0
	s_nop 0
	s_nop 0
	s_nop 0
	s_nop 0
	s_nop 0
	s_nop 0
	s_nop 0
	s_nop 0
	s_nop 0
	s_nop 0
	s_nop 0
	s_nop 0
	s_nop 0
	s_nop 0
	s_nop 0
	s_nop 0
	s_nop 0
	s_nop 0
	s_nop 0
	s_nop 0
	s_nop 0
	s_nop 0
	s_nop 0
	s_nop 0
	s_nop 0
	s_nop 0
	s_nop 0
	s_nop 0
	s_nop 0
	s_nop 0
	s_nop 0
	s_nop 0
	s_nop 0
	s_nop 0
	s_nop 0
	s_nop 0
	s_nop 0
	s_nop 0
	s_nop 0
	s_nop 0
	s_nop 0
	s_nop 0
	s_nop 0
	s_nop 0
	s_nop 0
	s_nop 0
	s_nop 0
	s_nop 0
	s_nop 0
	s_nop 0
	s_nop 0
	s_nop 0
	s_nop 0
	s_nop 0
	s_nop 0
	s_nop 0
	s_nop 0
	s_nop 0
	s_nop 0
	s_nop 0
	s_nop 0
	s_nop 0
	s_nop 0
	s_nop 0
	s_nop 0
	s_nop 0
	s_nop 0
	s_nop 0
	s_nop 0
	s_nop 0
	s_nop 0
	s_nop 0
	s_nop 0
	s_nop 0
	s_nop 0
	s_nop 0
	s_nop 0
	s_nop 0
	s_nop 0
	s_nop 0
	s_nop 0
	s_nop 0
	s_nop 0
	s_nop 0
	s_nop 0
	s_nop 0
	s_nop 0
	s_nop 0
	s_nop 0
	s_nop 0
	s_nop 0
	s_nop 0
	s_nop 0
	s_nop 0
	s_nop 0
	s_nop 0
	s_nop 0
	s_nop 0
	s_nop 0
	s_nop 0
	s_nop 0
	s_nop 0
	s_nop 0
	s_nop 0
	s_nop 0
	s_nop 0
	s_nop 0
	s_nop 0
	s_nop 0
	s_nop 0
	s_nop 0
	s_nop 0
	s_nop 0
	s_nop 0
	s_nop 0
	s_nop 0
	s_nop 0
	s_nop 0
	s_nop 0
	s_nop 0
	s_nop 0
	s_nop 0
	s_nop 0
	s_nop 0
	s_nop 0
	s_nop 0
	s_nop 0
	s_nop 0
	s_nop 0
	s_nop 0
	s_nop 0
	s_nop 0
	s_nop 0
	s_nop 0
	s_nop 0
	s_nop 0
	s_nop 0
	s_nop 0
	s_nop 0
	s_nop 0
	s_nop 0
	s_nop 0
	s_nop 0
	s_nop 0
	s_nop 0
	s_nop 0
	s_nop 0
	s_nop 0
	s_nop 0
	s_nop 0
	s_nop 0
	s_nop 0
	s_nop 0
	s_nop 0
	s_nop 0
	s_nop 0
	s_nop 0
	s_nop 0
	s_nop 0
	s_nop 0
	s_nop 0
	s_nop 0
	s_nop 0
	s_nop 0
	s_nop 0
	s_nop 0
	s_nop 0
	s_nop 0
	s_nop 0
	s_nop 0
	s_nop 0
	s_nop 0
	s_nop 0
	s_nop 0
	s_nop 0
	s_nop 0
	s_nop 0
	s_nop 0
	s_nop 0
	s_nop 0
	s_nop 0
	s_nop 0
	s_nop 0
	s_nop 0
	s_nop 0
	s_nop 0
	s_nop 0
	s_nop 0
	s_nop 0
	s_nop 0
	s_nop 0
	s_nop 0
	s_nop 0
	s_nop 0
	s_nop 0
	s_nop 0
	s_nop 0
	s_nop 0
	s_nop 0
	s_nop 0
	s_nop 0
	s_nop 0
	s_nop 0
	s_nop 0
	s_nop 0
	s_nop 0
	s_nop 0
	s_nop 0
	s_nop 0
	s_nop 0
	s_nop 0
	s_nop 0
	s_nop 0
	s_nop 0
	s_nop 0
	s_nop 0
	s_nop 0
	s_nop 0
	s_nop 0
	s_nop 0
	s_nop 0
	s_nop 0
	s_nop 0
	s_nop 0
	s_nop 0
	s_nop 0
	s_nop 0
	s_nop 0
	s_nop 0
	s_nop 0
	s_nop 0
	s_nop 0
	s_nop 0
	s_nop 0
	s_nop 0
	s_nop 0
	s_nop 0
	s_nop 0
	s_nop 0
	s_nop 0
	s_nop 0
	s_nop 0
	s_nop 0
	s_nop 0
	s_nop 0
	s_nop 0
	s_nop 0
	s_nop 0
	s_nop 0
	s_nop 0
	s_nop 0
	s_nop 0
	s_nop 0
	s_nop 0
	s_nop 0
	s_nop 0
	s_nop 0
	s_nop 0
	s_nop 0
	s_nop 0
	s_nop 0
	s_nop 0
	s_nop 0
	s_nop 0
	s_nop 0
	s_nop 0
	s_nop 0
	s_nop 0
	s_nop 0
	s_nop 0
	s_nop 0
	s_nop 0
	s_nop 0
	s_nop 0
	s_nop 0
; #define LAS __attribute__((address_space(3)))
; DI float bf2f(bf16_t v) { return __uint_as_float(((unsigned)v) << 16); }
; DI bf16_t f2bf(float f) { return (bf16_t)(cvt_pk(f, 0.f) & 0xffffu); }
; DI float logsig16(float z) { return (fminf(z, 0.f) - __logf(1.0f + __expf(-fabsf(z)))) * (1.0f / 16.0f); }
; DI void gla_gate_phase(const Params& P, LAS unsigned char* lds, int lj) {
;     ...
;   for (int item = blockIdx.x; item < 512; item += gridDim.x) {
;     __syncthreads();
;     { const int row = tid >> 3, part = tid & 7; *(LAS f32x4*)(zL + row * 32 + part * 4) = *(const f32x4*)(zbuf + ((size_t)item * 64 + row) * 32 + part * 4); }
;     __syncthreads();
;     float lsb[64]; float totb = 0.f;
; #pragma unroll
;     for (int i = 0; i < 64; ++i) {
;       float z = bb_;
; #pragma unroll
;       for (int j4 = 0; j4 < 4; ++j4) { const f32x4 zz = *(const LAS f32x4*)(zL + i * 32 + 16 + j4 * 4); z += zz[0] * wb[j4 * 4] + zz[1] * wb[j4 * 4 + 1] + zz[2] * wb[j4 * 4 + 2] + zz[3] * wb[j4 * 4 + 3]; }
;       lsb[i] = logsig16(z); totb += lsb[i];
;     }
;     float runf = 0.f, runb = 0.f;
; #pragma unroll
;     for (int ib = 0; ib < 4; ++ib) {
;       bf16_t qraw[16], kraw[16];
; #pragma unroll
;       for (int ii = 0; ii < 16; ++ii) { const bf16_t* pr = proj + ((size_t)item * 64 + ib * 16 + ii) * 3072 + col; qraw[ii] = pr[0]; kraw[ii] = pr[512]; }
;       asm volatile("" ::: "memory");
; #pragma unroll
;       for (int ii = 0; ii < 16; ++ii) {
;         const int i = ib * 16 + ii;
;         float z = bf_;
; #pragma unroll
;         for (int j4 = 0; j4 < 4; ++j4) { const f32x4 zz = *(const LAS f32x4*)(zL + i * 32 + j4 * 4); z += zz[0] * wf[j4 * 4] + zz[1] * wf[j4 * 4 + 1] + zz[2] * wf[j4 * 4 + 2] + zz[3] * wf[j4 * 4 + 3]; }
;         runf += logsig16(z);
;         const float Bi = totb - runb; runb += lsb[i];
;         const size_t tokrow = (size_t)item * 64 + i;
;         bf16_t* pr = proj + tokrow * 3072 + col;
;         const float q = bf2f(qraw[ii]), k = bf2f(kraw[ii]);
;         pr[0] = f2bf(q * __expf(runf)); pr[512] = f2bf(k * __expf(-runf));
;         QB[tokrow * 512 + col] = f2bf(q * __expf(Bi)); KB[tokrow * 512 + col] = f2bf(k * __expf(-Bi));
;       }
;       asm volatile("" ::: "memory");
;     }
;     dect[(size_t)item * 512 + col] = __expf(runf);
;     dect[(size_t)(512 + item) * 512 + col] = __expf(totb);
;   }
	s_nop 0
	s_nop 0
	s_nop 0
	s_nop 0
	s_nop 0
	s_nop 0
	s_nop 0
	s_nop 0
	s_nop 0
	s_nop 0
	s_nop 0
	s_nop 0
	s_nop 0
	s_nop 0
	s_nop 0
	s_nop 0
	s_nop 0
	s_nop 0
	s_nop 0
	s_nop 0
	s_nop 0
	s_nop 0
	s_nop 0
	s_nop 0
	s_nop 0
	s_nop 0
	s_nop 0
	s_nop 0
	s_nop 0
	s_nop 0
	s_nop 0
	s_nop 0
	s_nop 0
	s_nop 0
	s_nop 0
	s_nop 0
	s_nop 0
	s_nop 0
	s_nop 0
	s_nop 0
	s_nop 0
	s_nop 0
	s_nop 0
	s_nop 0
	s_nop 0
	s_nop 0
	s_nop 0
	s_nop 0
	s_nop 0
	s_nop 0
	s_nop 0
	s_nop 0
	s_nop 0
	s_nop 0
	s_nop 0
	s_nop 0
	s_nop 0
	s_nop 0
	s_nop 0
	s_nop 0
	s_nop 0
	s_nop 0
	s_nop 0
	s_nop 0
	s_nop 0
	s_nop 0
	s_nop 0
	s_nop 0
	s_nop 0
	s_nop 0
	s_nop 0
	s_nop 0
	s_nop 0
	s_nop 0
	s_nop 0
	s_nop 0
	s_nop 0
	s_nop 0
	s_nop 0
	s_nop 0
	s_nop 0
	s_nop 0
	s_nop 0
	s_nop 0
	s_nop 0
	s_nop 0
	s_nop 0
	s_nop 0
	s_nop 0
	s_nop 0
	s_nop 0
	s_nop 0
	s_nop 0
	s_nop 0
	s_nop 0
	s_nop 0
	s_nop 0
	s_nop 0
	s_nop 0
	s_nop 0
	s_nop 0
	s_nop 0
	s_nop 0
	s_nop 0
	s_nop 0
	s_nop 0
	s_nop 0
	s_nop 0
	s_nop 0
	s_nop 0
	s_nop 0
	s_nop 0
	s_nop 0
	s_nop 0
	s_nop 0
	s_nop 0
	s_nop 0
	s_nop 0
	s_nop 0
	s_nop 0
	s_nop 0
	s_nop 0
	s_nop 0
	s_nop 0
	s_nop 0
	s_nop 0
	s_nop 0
	s_nop 0
	s_nop 0
	s_nop 0
	s_nop 0
	s_nop 0
	s_nop 0
	s_nop 0
	s_nop 0
	s_nop 0
	s_nop 0
	s_nop 0
	s_nop 0
	s_nop 0
	s_nop 0
	s_nop 0
	s_nop 0
	s_nop 0
	s_nop 0
	s_nop 0
	s_nop 0
	s_nop 0
	s_nop 0
	s_nop 0
	s_nop 0
	s_nop 0
	s_nop 0
	s_nop 0
	s_nop 0
	s_nop 0
	s_nop 0
	s_nop 0
	s_nop 0
	s_nop 0
	s_nop 0
	s_nop 0
	s_nop 0
	s_nop 0
	s_nop 0
	s_nop 0
	s_nop 0
	s_nop 0
	s_nop 0
	s_nop 0
	s_nop 0
	s_nop 0
	s_nop 0
	s_nop 0
	s_nop 0
	s_nop 0
	s_nop 0
	s_nop 0
	s_nop 0
	s_nop 0
	s_nop 0
	s_nop 0
	s_nop 0
	s_nop 0
	s_nop 0
	s_nop 0
	s_nop 0
	s_nop 0
	s_nop 0
	s_nop 0
	s_nop 0
	s_nop 0
	s_nop 0
	s_nop 0
	s_nop 0
	s_nop 0
	s_nop 0
	s_nop 0
	s_nop 0
	s_nop 0
	s_nop 0
	s_nop 0
	s_nop 0
	s_nop 0
	s_nop 0
	s_nop 0
	s_nop 0
	s_nop 0
	s_nop 0
	s_nop 0
	s_nop 0
	s_nop 0
	s_nop 0
	s_nop 0
	s_nop 0
	s_nop 0
	s_nop 0
	s_nop 0
	s_nop 0
	s_nop 0
	s_nop 0
	s_nop 0
	s_nop 0
	s_nop 0
	s_nop 0
	s_nop 0
	s_nop 0
	s_nop 0
	s_nop 0
	s_nop 0
	s_nop 0
	s_nop 0
	s_nop 0
	s_nop 0
	s_nop 0
	s_nop 0
	s_nop 0
	s_nop 0
	s_nop 0
	s_nop 0
	s_nop 0
	s_nop 0
	s_nop 0
	s_nop 0
	s_nop 0
	s_nop 0
	s_nop 0
	s_nop 0
	s_nop 0
	s_nop 0
	s_nop 0
	s_nop 0
	s_nop 0
	s_nop 0
	s_nop 0
	s_nop 0
	s_nop 0
	s_nop 0
	s_nop 0
	s_nop 0
	s_nop 0
	s_nop 0
	s_nop 0
	s_nop 0
	s_nop 0
	s_nop 0
	s_nop 0
	s_nop 0
	s_nop 0
	s_nop 0
	s_nop 0
	s_nop 0
	s_nop 0
	s_nop 0
	s_nop 0
	s_nop 0
	s_nop 0
	s_nop 0
	s_nop 0
	s_nop 0
	s_nop 0
	s_nop 0
	s_nop 0
	s_nop 0
	s_nop 0
	s_nop 0
	s_nop 0
	s_nop 0
	s_nop 0
	s_nop 0
	s_nop 0
	s_nop 0
	s_nop 0
	s_nop 0
	s_nop 0
	s_nop 0
	s_nop 0
	s_nop 0
	s_nop 0
	s_nop 0
	s_nop 0
	s_nop 0
	s_nop 0
	s_nop 0
	s_nop 0
	s_nop 0
	s_nop 0
	s_nop 0
	s_nop 0
	s_nop 0
	s_nop 0
	s_nop 0
	s_nop 0
	s_nop 0
	s_nop 0
	s_nop 0
	s_nop 0
	s_nop 0
	s_nop 0
	s_nop 0
	s_nop 0
	s_nop 0
	s_nop 0
	s_nop 0
	s_nop 0
	s_nop 0
	s_nop 0
	s_nop 0
	s_nop 0
	s_nop 0
	s_nop 0
	s_nop 0
	s_nop 0
	s_nop 0
	s_nop 0
	s_nop 0
	s_nop 0
	s_nop 0
	s_nop 0
	s_nop 0
	s_nop 0
	s_nop 0
	s_nop 0
	s_nop 0
	s_nop 0
	s_nop 0
	s_nop 0
	s_nop 0
	s_nop 0
	s_nop 0
	s_nop 0
	s_nop 0
	s_nop 0
	s_nop 0
	s_nop 0
	s_nop 0
	s_nop 0
	s_nop 0
	s_nop 0
	s_nop 0
	s_nop 0
	s_nop 0
	s_nop 0
	s_nop 0
	s_nop 0
	s_nop 0
	s_nop 0
	s_nop 0
	s_nop 0
	s_nop 0
	s_nop 0
	s_nop 0
	s_nop 0
	s_nop 0
	s_nop 0
	s_nop 0
	s_nop 0
	s_nop 0
	s_nop 0
	s_nop 0
	s_nop 0
	s_nop 0
	s_nop 0
	s_nop 0
	s_nop 0
	s_nop 0
	s_nop 0
	s_nop 0
	s_nop 0
	s_nop 0
	s_nop 0
	s_nop 0
	s_nop 0
	s_nop 0
	s_nop 0
	s_nop 0
	s_nop 0
	s_nop 0
	s_nop 0
	s_nop 0
	s_nop 0
	s_nop 0
	s_nop 0
	s_nop 0
	s_nop 0
	s_nop 0
	s_nop 0
	s_nop 0
	s_nop 0
	s_nop 0
	s_nop 0
	s_nop 0
	s_nop 0
	s_nop 0
	s_nop 0
	s_nop 0
	s_nop 0
	s_nop 0
	s_nop 0
	s_nop 0
	s_nop 0
	s_nop 0
	s_nop 0
	s_nop 0
	s_nop 0
	s_nop 0
	s_nop 0
	s_nop 0
	s_nop 0
	s_nop 0
	s_nop 0
	s_nop 0
	s_nop 0
	s_nop 0
	s_nop 0
	s_nop 0
	s_nop 0
	s_nop 0
	s_nop 0
	s_nop 0
	s_nop 0
	s_nop 0
	s_nop 0
	s_nop 0
	s_nop 0
	s_nop 0
	s_nop 0
	s_nop 0
	s_nop 0
	s_nop 0
	s_nop 0
	s_nop 0
	s_nop 0
	s_nop 0
	s_nop 0
	s_nop 0
	s_nop 0
	s_nop 0
	s_nop 0
	s_nop 0
	s_nop 0
	s_nop 0
	s_nop 0
	s_nop 0
	s_nop 0
	s_nop 0
	s_nop 0
	s_nop 0
	s_nop 0
	s_nop 0
	s_nop 0
	s_nop 0
	s_nop 0
	s_nop 0
	s_nop 0
	s_nop 0
	s_nop 0
	s_nop 0
	s_nop 0
	s_nop 0
	s_nop 0
	s_nop 0
	s_nop 0
	s_nop 0
	s_nop 0
	s_nop 0
	s_nop 0
	s_nop 0
	s_nop 0
	s_nop 0
	s_nop 0
	s_nop 0
	s_nop 0
	s_nop 0
	s_nop 0
	s_nop 0
	s_nop 0
	s_nop 0
	s_nop 0
	s_nop 0
	s_nop 0
	s_nop 0
	s_nop 0
	s_nop 0
	s_nop 0
	s_nop 0
	s_nop 0
	s_nop 0
	s_nop 0
	s_nop 0
	s_nop 0
	s_nop 0
	s_nop 0
	s_nop 0
	s_nop 0
	s_nop 0
	s_nop 0
	s_nop 0
	s_nop 0
	s_nop 0
	s_nop 0
	s_nop 0
	s_nop 0
	s_nop 0
	s_nop 0
	s_nop 0
	s_nop 0
	s_nop 0
	s_nop 0
	s_nop 0
	s_nop 0
	s_nop 0
	s_nop 0
	s_nop 0
	s_nop 0
	s_nop 0
	s_nop 0
	s_nop 0
	s_nop 0
	s_nop 0
	s_nop 0
	s_nop 0
	s_nop 0
	s_nop 0
	s_nop 0
	s_nop 0
	s_nop 0
	s_nop 0
	s_nop 0
	s_nop 0
	s_nop 0
	s_nop 0
	s_nop 0
	s_nop 0
	s_nop 0
	s_nop 0
	s_nop 0
	s_nop 0
	s_nop 0
	s_nop 0
	s_nop 0
	s_nop 0
	s_nop 0
	s_nop 0
	s_nop 0
	s_nop 0
	s_nop 0
	s_nop 0
	s_nop 0
	s_nop 0
	s_nop 0
	s_nop 0
	s_nop 0
	s_nop 0
	s_nop 0
	s_nop 0
	s_nop 0
	s_nop 0
	s_nop 0
	s_nop 0
	s_nop 0
	s_nop 0
	s_nop 0
	s_nop 0
	s_nop 0
	s_nop 0
	s_nop 0
	s_nop 0
	s_nop 0
	s_nop 0
	s_nop 0
	s_nop 0
	s_nop 0
	s_nop 0
	s_nop 0
	s_nop 0
	s_nop 0
	s_nop 0
	s_nop 0
	s_nop 0
	s_nop 0
	s_nop 0
	s_nop 0
	s_nop 0
	s_nop 0
	s_nop 0
	s_nop 0
	s_nop 0
	s_nop 0
	s_nop 0
	s_nop 0
	s_nop 0
	s_nop 0
	s_nop 0
	s_nop 0
	s_nop 0
	s_nop 0
	s_nop 0
	s_nop 0
	s_nop 0
	s_nop 0
	s_nop 0
	s_nop 0
	s_nop 0
	s_nop 0
	s_nop 0
	s_nop 0
; #define LAS __attribute__((address_space(3)))
; DI float bf2f(bf16_t v) { return __uint_as_float(((unsigned)v) << 16); }
; DI bf16_t f2bf(float f) { return (bf16_t)(cvt_pk(f, 0.f) & 0xffffu); }
; DI float logsig16(float z) { return (fminf(z, 0.f) - __logf(1.0f + __expf(-fabsf(z)))) * (1.0f / 16.0f); }
; DI void gla_gate_phase(const Params& P, LAS unsigned char* lds, int lj) {
;     ...
;   for (int item = blockIdx.x; item < 512; item += gridDim.x) {
;     __syncthreads();
;     { const int row = tid >> 3, part = tid & 7; *(LAS f32x4*)(zL + row * 32 + part * 4) = *(const f32x4*)(zbuf + ((size_t)item * 64 + row) * 32 + part * 4); }
;     __syncthreads();
;     float lsb[64]; float totb = 0.f;
; #pragma unroll
;     for (int i = 0; i < 64; ++i) {
;       float z = bb_;
; #pragma unroll
;       for (int j4 = 0; j4 < 4; ++j4) { const f32x4 zz = *(const LAS f32x4*)(zL + i * 32 + 16 + j4 * 4); z += zz[0] * wb[j4 * 4] + zz[1] * wb[j4 * 4 + 1] + zz[2] * wb[j4 * 4 + 2] + zz[3] * wb[j4 * 4 + 3]; }
;       lsb[i] = logsig16(z); totb += lsb[i];
;     }
;     float runf = 0.f, runb = 0.f;
; #pragma unroll
;     for (int ib = 0; ib < 4; ++ib) {
;       bf16_t qraw[16], kraw[16];
; #pragma unroll
;       for (int ii = 0; ii < 16; ++ii) { const bf16_t* pr = proj + ((size_t)item * 64 + ib * 16 + ii) * 3072 + col; qraw[ii] = pr[0]; kraw[ii] = pr[512]; }
;       asm volatile("" ::: "memory");
; #pragma unroll
;       for (int ii = 0; ii < 16; ++ii) {
;         const int i = ib * 16 + ii;
;         float z = bf_;
; #pragma unroll
;         for (int j4 = 0; j4 < 4; ++j4) { const f32x4 zz = *(const LAS f32x4*)(zL + i * 32 + j4 * 4); z += zz[0] * wf[j4 * 4] + zz[1] * wf[j4 * 4 + 1] + zz[2] * wf[j4 * 4 + 2] + zz[3] * wf[j4 * 4 + 3]; }
;         runf += logsig16(z);
;         const float Bi = totb - runb; runb += lsb[i];
;         const size_t tokrow = (size_t)item * 64 + i;
;         bf16_t* pr = proj + tokrow * 3072 + col;
;         const float q = bf2f(qraw[ii]), k = bf2f(kraw[ii]);
;         pr[0] = f2bf(q * __expf(runf)); pr[512] = f2bf(k * __expf(-runf));
;         QB[tokrow * 512 + col] = f2bf(q * __expf(Bi)); KB[tokrow * 512 + col] = f2bf(k * __expf(-Bi));
;       }
;       asm volatile("" ::: "memory");
;     }
;     dect[(size_t)item * 512 + col] = __expf(runf);
;     dect[(size_t)(512 + item) * 512 + col] = __expf(totb);
;   }
	s_nop 0
	s_nop 0
	s_nop 0
	s_nop 0
	s_nop 0
	s_nop 0
	s_nop 0
	s_nop 0
	s_nop 0
	s_nop 0
	s_nop 0
	s_nop 0
	s_nop 0
	s_nop 0
	s_nop 0
	s_nop 0
	s_nop 0
	s_nop 0
	s_nop 0
	s_nop 0
	s_nop 0
	s_nop 0
	s_nop 0
	s_nop 0
	s_nop 0
	s_nop 0
	s_nop 0
	s_nop 0
	s_nop 0
	s_nop 0
	s_nop 0
	s_nop 0
	s_nop 0
	s_nop 0
	s_nop 0
	s_nop 0
	s_nop 0
	s_nop 0
	s_nop 0
	s_nop 0
	s_nop 0
	s_nop 0
	s_nop 0
	s_nop 0
	s_nop 0
	s_nop 0
	s_nop 0
	s_nop 0
	s_nop 0
	s_nop 0
	s_nop 0
	s_nop 0
	s_nop 0
	s_nop 0
	s_nop 0
	s_nop 0
	s_nop 0
	s_nop 0
	s_nop 0
	s_nop 0
	s_nop 0
	s_nop 0
	s_nop 0
	s_nop 0
	s_nop 0
	s_nop 0
	s_nop 0
	s_nop 0
	s_nop 0
	s_nop 0
	s_nop 0
	s_nop 0
	s_nop 0
	s_nop 0
	s_nop 0
	s_nop 0
	s_nop 0
	s_nop 0
	s_nop 0
	s_nop 0
	s_nop 0
	s_nop 0
	s_nop 0
	s_nop 0
	s_nop 0
	s_nop 0
	s_nop 0
	s_nop 0
	s_nop 0
	s_nop 0
	s_nop 0
	s_nop 0
	s_nop 0
	s_nop 0
	s_nop 0
	s_nop 0
	s_nop 0
	s_nop 0
	s_nop 0
	s_nop 0
	s_nop 0
	s_nop 0
	s_nop 0
	s_nop 0
	s_nop 0
	s_nop 0
	s_nop 0
	s_nop 0
	s_nop 0
	s_nop 0
	s_nop 0
	s_nop 0
	s_nop 0
	s_nop 0
	s_nop 0
	s_nop 0
	s_nop 0
	s_nop 0
	s_nop 0
	s_nop 0
	s_nop 0
	s_nop 0
	s_nop 0
	s_nop 0
	s_nop 0
	s_nop 0
	s_nop 0
	s_nop 0
	s_nop 0
	s_nop 0
	s_nop 0
	s_nop 0
	s_nop 0
	s_nop 0
	s_nop 0
	s_nop 0
	s_nop 0
	s_nop 0
	s_nop 0
	s_nop 0
	s_nop 0
	s_nop 0
	s_nop 0
	s_nop 0
	s_nop 0
	s_nop 0
	s_nop 0
	s_nop 0
	s_nop 0
	s_nop 0
	s_nop 0
	s_nop 0
	s_nop 0
	s_nop 0
	s_nop 0
	s_nop 0
	s_nop 0
	s_nop 0
	s_nop 0
	s_nop 0
	s_nop 0
	s_nop 0
	s_nop 0
	s_nop 0
	s_nop 0
	s_nop 0
	s_nop 0
	s_nop 0
	s_nop 0
	s_nop 0
	s_nop 0
	s_nop 0
	s_nop 0
	s_nop 0
	s_nop 0
	s_nop 0
	s_nop 0
	s_nop 0
	s_nop 0
	s_nop 0
	s_nop 0
	s_nop 0
	s_nop 0
	s_nop 0
	s_nop 0
	s_nop 0
	s_nop 0
	s_nop 0
	s_nop 0
	s_nop 0
	s_nop 0
	s_nop 0
	s_nop 0
	s_nop 0
	s_nop 0
	s_nop 0
	s_nop 0
	s_nop 0
	s_nop 0
	s_nop 0
	s_nop 0
	s_nop 0
	s_nop 0
	s_nop 0
	s_nop 0
	s_nop 0
	s_nop 0
	s_nop 0
	s_nop 0
	s_nop 0
	s_nop 0
	s_nop 0
	s_nop 0
	s_nop 0
	s_nop 0
	s_nop 0
	s_nop 0
	s_nop 0
	s_nop 0
	s_nop 0
	s_nop 0
	s_nop 0
	s_nop 0
	s_nop 0
	s_nop 0
	s_nop 0
	s_nop 0
	s_nop 0
	s_nop 0
	s_nop 0
	s_nop 0
	s_nop 0
	s_nop 0
	s_nop 0
	s_nop 0
	s_nop 0
	s_nop 0
	s_nop 0
	s_nop 0
	s_nop 0
	s_nop 0
	s_nop 0
	s_nop 0
	s_nop 0
	s_nop 0
	s_nop 0
	s_nop 0
	s_nop 0
	s_nop 0
	s_nop 0
	s_nop 0
	s_nop 0
	s_nop 0
	s_nop 0
	s_nop 0
	s_nop 0
	s_nop 0
	s_nop 0
	s_nop 0
	s_nop 0
	s_nop 0
	s_nop 0
	s_nop 0
	s_nop 0
	s_nop 0
	s_nop 0
	s_nop 0
	s_nop 0
	s_nop 0
	s_nop 0
	s_nop 0
	s_nop 0
	s_nop 0
	s_nop 0
	s_nop 0
	s_nop 0
	s_nop 0
	s_nop 0
	s_nop 0
	s_nop 0
	s_nop 0
	s_nop 0
	s_nop 0
	s_nop 0
	s_nop 0
	s_nop 0
	s_nop 0
	s_nop 0
	s_nop 0
	s_nop 0
	s_nop 0
	s_nop 0
	s_nop 0
	s_nop 0
	s_nop 0
	s_nop 0
	s_nop 0
	s_nop 0
	s_nop 0
	s_nop 0
	s_nop 0
	s_nop 0
	s_nop 0
	s_nop 0
	s_nop 0
	s_nop 0
	s_nop 0
	s_nop 0
	s_nop 0
	s_nop 0
	s_nop 0
	s_nop 0
	s_nop 0
	s_nop 0
	s_nop 0
	s_nop 0
	s_nop 0
	s_nop 0
	s_nop 0
	s_nop 0
	s_nop 0
	s_nop 0
	s_nop 0
	s_nop 0
	s_nop 0
	s_nop 0
	s_nop 0
	s_nop 0
	s_nop 0
	s_nop 0
	s_nop 0
	s_nop 0
	s_nop 0
	s_nop 0
	s_nop 0
	s_nop 0
	s_nop 0
	s_nop 0
	s_nop 0
	s_nop 0
	s_nop 0
	s_nop 0
	s_nop 0
	s_nop 0
	s_nop 0
	s_nop 0
	s_nop 0
	s_nop 0
	s_nop 0
	s_nop 0
	s_nop 0
	s_nop 0
	s_nop 0
	s_nop 0
	s_nop 0
	s_nop 0
	s_nop 0
	s_nop 0
	s_nop 0
	s_nop 0
	s_nop 0
	s_nop 0
	s_nop 0
	s_nop 0
	s_nop 0
	s_nop 0
	s_nop 0
	s_nop 0
	s_nop 0
	s_nop 0
	s_nop 0
	s_nop 0
	s_nop 0
	s_nop 0
	s_nop 0
	s_nop 0
	s_nop 0
	s_nop 0
	s_nop 0
	s_nop 0
	s_nop 0
	s_nop 0
	s_nop 0
	s_nop 0
	s_nop 0
	s_nop 0
	s_nop 0
	s_nop 0
	s_nop 0
	s_nop 0
	s_nop 0
	s_nop 0
	s_nop 0
	s_nop 0
	s_nop 0
	s_nop 0
	s_nop 0
	s_nop 0
	s_nop 0
	s_nop 0
	s_nop 0
	s_nop 0
	s_nop 0
	s_nop 0
	s_nop 0
	s_nop 0
	s_nop 0
	s_nop 0
	s_nop 0
	s_nop 0
	s_nop 0
	s_nop 0
	s_nop 0
	s_nop 0
	s_nop 0
	s_nop 0
	s_nop 0
	s_nop 0
	s_nop 0
	s_nop 0
	s_nop 0
	s_nop 0
	s_nop 0
	s_nop 0
	s_nop 0
	s_nop 0
	s_nop 0
	s_nop 0
	s_nop 0
	s_nop 0
	s_nop 0
	s_nop 0
	s_nop 0
	s_nop 0
	s_nop 0
	s_nop 0
	s_nop 0
	s_nop 0
	s_nop 0
	s_nop 0
	s_nop 0
	s_nop 0
	s_nop 0
	s_nop 0
	s_nop 0
	s_nop 0
	s_nop 0
	s_nop 0
	s_nop 0
	s_nop 0
	s_nop 0
	s_nop 0
	s_nop 0
	s_nop 0
	s_nop 0
	s_nop 0
	s_nop 0
	s_nop 0
	s_nop 0
	s_nop 0
	s_nop 0
	s_nop 0
	s_nop 0
	s_nop 0
	s_nop 0
	s_nop 0
	s_nop 0
	s_nop 0
	s_nop 0
	s_nop 0
	s_nop 0
	s_nop 0
	s_nop 0
	s_nop 0
	s_nop 0
	s_nop 0
	s_nop 0
	s_nop 0
	s_nop 0
	s_nop 0
	s_nop 0
	s_nop 0
	s_nop 0
	s_nop 0
	s_nop 0
	s_nop 0
	s_nop 0
	s_nop 0
	s_nop 0
	s_nop 0
	s_nop 0
	s_nop 0
	s_nop 0
	s_nop 0
	s_nop 0
	s_nop 0
	s_nop 0
	s_nop 0
	s_nop 0
	s_nop 0
	s_nop 0
	s_nop 0
	s_nop 0
	s_nop 0
	s_nop 0
	s_nop 0
	s_nop 0
	s_nop 0
	s_nop 0
	s_nop 0
	s_nop 0
	s_nop 0
	s_nop 0
	s_nop 0
	s_nop 0
	s_nop 0
	s_nop 0
	s_nop 0
	s_nop 0
	s_nop 0
	s_nop 0
	s_nop 0
	s_nop 0
	s_nop 0
	s_nop 0
	s_nop 0
	s_nop 0
	s_nop 0
	s_nop 0
	s_nop 0
	s_nop 0
	s_nop 0
	s_nop 0
	s_nop 0
	s_nop 0
	s_nop 0
	s_nop 0
	s_nop 0
	s_nop 0
	s_nop 0
	s_nop 0
	s_nop 0
	s_nop 0
	s_nop 0
	s_nop 0
	s_nop 0
	s_nop 0
	s_nop 0
	s_nop 0
	s_nop 0
	s_nop 0
	s_nop 0
	s_nop 0
	s_nop 0
	s_nop 0
	s_nop 0
	s_nop 0
	s_nop 0
	s_nop 0
	s_nop 0
	s_nop 0
	s_nop 0
	s_nop 0
	s_nop 0
	s_nop 0
	s_nop 0
	s_nop 0
	s_nop 0
	s_nop 0
	s_nop 0
	s_nop 0
	s_nop 0
	s_nop 0
	s_nop 0
	s_nop 0
	s_nop 0
	s_nop 0
	s_nop 0
	s_nop 0
	s_nop 0
	s_nop 0
	s_nop 0
	s_nop 0
	s_nop 0
	s_nop 0
	s_nop 0
	s_nop 0
	s_nop 0
	s_nop 0
	s_nop 0
	s_nop 0
	s_nop 0
	s_nop 0
	s_nop 0
	s_nop 0
	s_nop 0
	s_nop 0
	s_nop 0
	s_nop 0
	s_nop 0
	s_nop 0
	s_nop 0
	s_nop 0
	s_nop 0
	s_nop 0
	s_nop 0
	s_nop 0
	s_nop 0
	s_nop 0
	s_nop 0
	s_nop 0
	s_nop 0
	s_nop 0
	s_nop 0
	s_nop 0
	s_nop 0
	s_nop 0
	s_nop 0
	s_nop 0
	s_nop 0
	s_nop 0
	s_nop 0
	s_nop 0
	s_nop 0
	s_nop 0
	s_nop 0
	s_nop 0
; #define LAS __attribute__((address_space(3)))
; DI float bf2f(bf16_t v) { return __uint_as_float(((unsigned)v) << 16); }
; DI bf16_t f2bf(float f) { return (bf16_t)(cvt_pk(f, 0.f) & 0xffffu); }
; DI float logsig16(float z) { return (fminf(z, 0.f) - __logf(1.0f + __expf(-fabsf(z)))) * (1.0f / 16.0f); }
; DI void gla_gate_phase(const Params& P, LAS unsigned char* lds, int lj) {
;     ...
;   for (int item = blockIdx.x; item < 512; item += gridDim.x) {
;     __syncthreads();
;     { const int row = tid >> 3, part = tid & 7; *(LAS f32x4*)(zL + row * 32 + part * 4) = *(const f32x4*)(zbuf + ((size_t)item * 64 + row) * 32 + part * 4); }
;     __syncthreads();
;     float lsb[64]; float totb = 0.f;
; #pragma unroll
;     for (int i = 0; i < 64; ++i) {
;       float z = bb_;
; #pragma unroll
;       for (int j4 = 0; j4 < 4; ++j4) { const f32x4 zz = *(const LAS f32x4*)(zL + i * 32 + 16 + j4 * 4); z += zz[0] * wb[j4 * 4] + zz[1] * wb[j4 * 4 + 1] + zz[2] * wb[j4 * 4 + 2] + zz[3] * wb[j4 * 4 + 3]; }
;       lsb[i] = logsig16(z); totb += lsb[i];
;     }
;     float runf = 0.f, runb = 0.f;
; #pragma unroll
;     for (int ib = 0; ib < 4; ++ib) {
;       bf16_t qraw[16], kraw[16];
; #pragma unroll
;       for (int ii = 0; ii < 16; ++ii) { const bf16_t* pr = proj + ((size_t)item * 64 + ib * 16 + ii) * 3072 + col; qraw[ii] = pr[0]; kraw[ii] = pr[512]; }
;       asm volatile("" ::: "memory");
; #pragma unroll
;       for (int ii = 0; ii < 16; ++ii) {
;         const int i = ib * 16 + ii;
;         float z = bf_;
; #pragma unroll
;         for (int j4 = 0; j4 < 4; ++j4) { const f32x4 zz = *(const LAS f32x4*)(zL + i * 32 + j4 * 4); z += zz[0] * wf[j4 * 4] + zz[1] * wf[j4 * 4 + 1] + zz[2] * wf[j4 * 4 + 2] + zz[3] * wf[j4 * 4 + 3]; }
;         runf += logsig16(z);
;         const float Bi = totb - runb; runb += lsb[i];
;         const size_t tokrow = (size_t)item * 64 + i;
;         bf16_t* pr = proj + tokrow * 3072 + col;
;         const float q = bf2f(qraw[ii]), k = bf2f(kraw[ii]);
;         pr[0] = f2bf(q * __expf(runf)); pr[512] = f2bf(k * __expf(-runf));
;         QB[tokrow * 512 + col] = f2bf(q * __expf(Bi)); KB[tokrow * 512 + col] = f2bf(k * __expf(-Bi));
;       }
;       asm volatile("" ::: "memory");
;     }
;     dect[(size_t)item * 512 + col] = __expf(runf);
;     dect[(size_t)(512 + item) * 512 + col] = __expf(totb);
;   }
	s_nop 0
	s_nop 0
	s_nop 0
	s_nop 0
	s_nop 0
	s_nop 0
	s_nop 0
	s_nop 0
	s_nop 0
	s_nop 0
	s_nop 0
	s_nop 0
	s_nop 0
	s_nop 0
	s_nop 0
	s_nop 0
	s_nop 0
	s_nop 0
	s_nop 0
	s_nop 0
	s_nop 0
	s_nop 0
	s_nop 0
	s_nop 0
	s_nop 0
	s_nop 0
	s_nop 0
	s_nop 0
	s_nop 0
	s_nop 0
	s_nop 0
	s_nop 0
	s_nop 0
	s_nop 0
	s_nop 0
	s_nop 0
	s_nop 0
	s_nop 0
	s_nop 0
	s_nop 0
	s_nop 0
	s_nop 0
	s_nop 0
	s_nop 0
	s_nop 0
	s_nop 0
	s_nop 0
	s_nop 0
	s_nop 0
	s_nop 0
	s_nop 0
	s_nop 0
	s_nop 0
	s_nop 0
	s_nop 0
	s_nop 0
	s_nop 0
	s_nop 0
	s_nop 0
	s_nop 0
	s_nop 0
	s_nop 0
	s_nop 0
	s_nop 0
	s_nop 0
	s_nop 0
	s_nop 0
	s_nop 0
	s_nop 0
	s_nop 0
	s_nop 0
	s_nop 0
	s_nop 0
	s_nop 0
	s_nop 0
	s_nop 0
	s_nop 0
	s_nop 0
	s_nop 0
	s_nop 0
	s_nop 0
	s_nop 0
	s_nop 0
	s_nop 0
	s_nop 0
	s_nop 0
	s_nop 0
	s_nop 0
	s_nop 0
	s_nop 0
	s_nop 0
	s_nop 0
	s_nop 0
	s_nop 0
	s_nop 0
	s_nop 0
	s_nop 0
	s_nop 0
	s_nop 0
	s_nop 0
	s_nop 0
	s_nop 0
	s_nop 0
	s_nop 0
	s_nop 0
	s_nop 0
	s_nop 0
	s_nop 0
	s_nop 0
	s_nop 0
	s_nop 0
	s_nop 0
	s_nop 0
	s_nop 0
	s_nop 0
	s_nop 0
	s_nop 0
	s_nop 0
	s_nop 0
	s_nop 0
	s_nop 0
	s_nop 0
	s_nop 0
	s_nop 0
	s_nop 0
	s_nop 0
	s_nop 0
	s_nop 0
	s_nop 0
	s_nop 0
	s_nop 0
	s_nop 0
	s_nop 0
	s_nop 0
	s_nop 0
	s_nop 0
	s_nop 0
	s_nop 0
	s_nop 0
	s_nop 0
	s_nop 0
	s_nop 0
	s_nop 0
	s_nop 0
	s_nop 0
	s_nop 0
	s_nop 0
	s_nop 0
	s_nop 0
	s_nop 0
	s_nop 0
	s_nop 0
	s_nop 0
	s_nop 0
	s_nop 0
	s_nop 0
	s_nop 0
	s_nop 0
	s_nop 0
	s_nop 0
	s_nop 0
	s_nop 0
	s_nop 0
	s_nop 0
	s_nop 0
	s_nop 0
	s_nop 0
	s_nop 0
	s_nop 0
	s_nop 0
	s_nop 0
	s_nop 0
	s_nop 0
	s_nop 0
	s_nop 0
	s_nop 0
	s_nop 0
	s_nop 0
	s_nop 0
	s_nop 0
	s_nop 0
	s_nop 0
	s_nop 0
	s_nop 0
	s_nop 0
	s_nop 0
	s_nop 0
	s_nop 0
	s_nop 0
	s_nop 0
	s_nop 0
	s_nop 0
	s_nop 0
	s_nop 0
	s_nop 0
	s_nop 0
	s_nop 0
	s_nop 0
	s_nop 0
	s_nop 0
	s_nop 0
	s_nop 0
	s_nop 0
	s_nop 0
	s_nop 0
	s_nop 0
	s_nop 0
	s_nop 0
	s_nop 0
	s_nop 0
	s_nop 0
	s_nop 0
	s_nop 0
	s_nop 0
	s_nop 0
	s_nop 0
	s_nop 0
	s_nop 0
	s_nop 0
	s_nop 0
	s_nop 0
	s_nop 0
	s_nop 0
	s_nop 0
	s_nop 0
	s_nop 0
	s_nop 0
	s_nop 0
	s_nop 0
	s_nop 0
	s_nop 0
	s_nop 0
	s_nop 0
	s_nop 0
	s_nop 0
	s_nop 0
	s_nop 0
	s_nop 0
	s_nop 0
	s_nop 0
	s_nop 0
	s_nop 0
	s_nop 0
	s_nop 0
	s_nop 0
	s_nop 0
	s_nop 0
	s_nop 0
	s_nop 0
	s_nop 0
	s_nop 0
	s_nop 0
	s_nop 0
	s_nop 0
	s_nop 0
	s_nop 0
	s_nop 0
	s_nop 0
	s_nop 0
	s_nop 0
	s_nop 0
	s_nop 0
	s_nop 0
	s_nop 0
	s_nop 0
	s_nop 0
	s_nop 0
	s_nop 0
	s_nop 0
	s_nop 0
	s_nop 0
	s_nop 0
	s_nop 0
	s_nop 0
	s_nop 0
	s_nop 0
	s_nop 0
	s_nop 0
	s_nop 0
	s_nop 0
	s_nop 0
	s_nop 0
	s_nop 0
	s_nop 0
	s_nop 0
	s_nop 0
	s_nop 0
	s_nop 0
	s_nop 0
	s_nop 0
	s_nop 0
	s_nop 0
	s_nop 0
	s_nop 0
	s_nop 0
	s_nop 0
	s_nop 0
	s_nop 0
	s_nop 0
	s_nop 0
	s_nop 0
	s_nop 0
	s_nop 0
	s_nop 0
	s_nop 0
	s_nop 0
	s_nop 0
	s_nop 0
	s_nop 0
	s_nop 0
	s_nop 0
	s_nop 0
	s_nop 0
	s_nop 0
	s_nop 0
	s_nop 0
	s_nop 0
	s_nop 0
	s_nop 0
	s_nop 0
	s_nop 0
	s_nop 0
	s_nop 0
	s_nop 0
	s_nop 0
	s_nop 0
	s_nop 0
	s_nop 0
	s_nop 0
	s_nop 0
	s_nop 0
	s_nop 0
	s_nop 0
	s_nop 0
	s_nop 0
	s_nop 0
	s_nop 0
	s_nop 0
	s_nop 0
	s_nop 0
	s_nop 0
	s_nop 0
	s_nop 0
	s_nop 0
	s_nop 0
	s_nop 0
	s_nop 0
	s_nop 0
	s_nop 0
	s_nop 0
	s_nop 0
	s_nop 0
	s_nop 0
	s_nop 0
	s_nop 0
	s_nop 0
	s_nop 0
	s_nop 0
	s_nop 0
	s_nop 0
	s_nop 0
	s_nop 0
	s_nop 0
	s_nop 0
	s_nop 0
	s_nop 0
	s_nop 0
	s_nop 0
	s_nop 0
	s_nop 0
	s_nop 0
	s_nop 0
	s_nop 0
	s_nop 0
	s_nop 0
	s_nop 0
	s_nop 0
	s_nop 0
	s_nop 0
	s_nop 0
	s_nop 0
	s_nop 0
	s_nop 0
	s_nop 0
	s_nop 0
	s_nop 0
	s_nop 0
	s_nop 0
	s_nop 0
	s_nop 0
	s_nop 0
	s_nop 0
	s_nop 0
	s_nop 0
	s_nop 0
	s_nop 0
	s_nop 0
	s_nop 0
	s_nop 0
	s_nop 0
	s_nop 0
	s_nop 0
	s_nop 0
	s_nop 0
	s_nop 0
	s_nop 0
	s_nop 0
	s_nop 0
	s_nop 0
	s_nop 0
	s_nop 0
	s_nop 0
	s_nop 0
	s_nop 0
	s_nop 0
	s_nop 0
	s_nop 0
	s_nop 0
	s_nop 0
	s_nop 0
	s_nop 0
	s_nop 0
	s_nop 0
	s_nop 0
	s_nop 0
	s_nop 0
	s_nop 0
	s_nop 0
	s_nop 0
	s_nop 0
	s_nop 0
	s_nop 0
	s_nop 0
	s_nop 0
	s_nop 0
	s_nop 0
	s_nop 0
	s_nop 0
	s_nop 0
	s_nop 0
	s_nop 0
	s_nop 0
	s_nop 0
	s_nop 0
	s_nop 0
	s_nop 0
	s_nop 0
	s_nop 0
	s_nop 0
	s_nop 0
	s_nop 0
	s_nop 0
	s_nop 0
	s_nop 0
	s_nop 0
	s_nop 0
	s_nop 0
	s_nop 0
	s_nop 0
	s_nop 0
	s_nop 0
	s_nop 0
	s_nop 0
	s_nop 0
	s_nop 0
	s_nop 0
	s_nop 0
	s_nop 0
	s_nop 0
	s_nop 0
	s_nop 0
	s_nop 0
	s_nop 0
	s_nop 0
	s_nop 0
	s_nop 0
	s_nop 0
	s_nop 0
	s_nop 0
	s_nop 0
	s_nop 0
	s_nop 0
	s_nop 0
	s_nop 0
	s_nop 0
	s_nop 0
	s_nop 0
	s_nop 0
	s_nop 0
	s_nop 0
	s_nop 0
	s_nop 0
	s_nop 0
	s_nop 0
	s_nop 0
	s_nop 0
	s_nop 0
	s_nop 0
	s_nop 0
	s_nop 0
	s_nop 0
	s_nop 0
	s_nop 0
	s_nop 0
	s_nop 0
	s_nop 0
	s_nop 0
	s_nop 0
	s_nop 0
	s_nop 0
	s_nop 0
	s_nop 0
	s_nop 0
	s_nop 0
	s_nop 0
	s_nop 0
	s_nop 0
	s_nop 0
	s_nop 0
	s_nop 0
	s_nop 0
	s_nop 0
	s_nop 0
	s_nop 0
	s_nop 0
	s_nop 0
	s_nop 0
	s_nop 0
	s_nop 0
	s_nop 0
	s_nop 0
	s_nop 0
	s_nop 0
	s_nop 0
	s_nop 0
	s_nop 0
	s_nop 0
	s_nop 0
	s_nop 0
	s_nop 0
	s_nop 0
	s_nop 0
	s_nop 0
	s_nop 0
	s_nop 0
	s_nop 0
	s_nop 0
	s_nop 0
	s_nop 0
	s_nop 0
	s_nop 0
	s_nop 0
	s_nop 0
	s_nop 0
	s_nop 0
	s_nop 0
	s_nop 0
	s_nop 0
	s_nop 0
	s_nop 0
	s_nop 0
	s_nop 0
	s_nop 0
	s_nop 0
	s_nop 0
	s_nop 0
	s_nop 0
	s_nop 0
	s_nop 0
	s_nop 0
	s_nop 0
	s_nop 0
	s_nop 0
	s_nop 0
	s_nop 0
	s_nop 0
	s_nop 0
	s_nop 0
	s_nop 0
	s_nop 0
	s_nop 0
	s_nop 0
	s_nop 0
	s_nop 0
	s_nop 0
	s_nop 0
	s_nop 0
	s_nop 0
	s_nop 0
	s_nop 0
	s_nop 0
	s_nop 0
	s_nop 0
	s_nop 0
	s_nop 0
	s_nop 0
	s_nop 0
	s_nop 0
	s_nop 0
	s_nop 0
	s_nop 0
	s_nop 0
	s_nop 0
	s_nop 0
	s_nop 0
	s_nop 0
	s_nop 0
	s_nop 0
	s_nop 0
	s_nop 0
	s_nop 0
	s_nop 0
	s_nop 0
	s_nop 0
	s_nop 0
	s_nop 0
	s_nop 0
	s_nop 0
	s_nop 0
	s_nop 0
	s_nop 0
	s_nop 0
	s_nop 0
	s_nop 0
	s_nop 0
	s_nop 0
	s_nop 0
; #define LAS __attribute__((address_space(3)))
; DI float bf2f(bf16_t v) { return __uint_as_float(((unsigned)v) << 16); }
; DI bf16_t f2bf(float f) { return (bf16_t)(cvt_pk(f, 0.f) & 0xffffu); }
; DI float logsig16(float z) { return (fminf(z, 0.f) - __logf(1.0f + __expf(-fabsf(z)))) * (1.0f / 16.0f); }
; DI void gla_gate_phase(const Params& P, LAS unsigned char* lds, int lj) {
;     ...
;   for (int item = blockIdx.x; item < 512; item += gridDim.x) {
;     __syncthreads();
;     { const int row = tid >> 3, part = tid & 7; *(LAS f32x4*)(zL + row * 32 + part * 4) = *(const f32x4*)(zbuf + ((size_t)item * 64 + row) * 32 + part * 4); }
;     __syncthreads();
;     float lsb[64]; float totb = 0.f;
; #pragma unroll
;     for (int i = 0; i < 64; ++i) {
;       float z = bb_;
; #pragma unroll
;       for (int j4 = 0; j4 < 4; ++j4) { const f32x4 zz = *(const LAS f32x4*)(zL + i * 32 + 16 + j4 * 4); z += zz[0] * wb[j4 * 4] + zz[1] * wb[j4 * 4 + 1] + zz[2] * wb[j4 * 4 + 2] + zz[3] * wb[j4 * 4 + 3]; }
;       lsb[i] = logsig16(z); totb += lsb[i];
;     }
;     float runf = 0.f, runb = 0.f;
; #pragma unroll
;     for (int ib = 0; ib < 4; ++ib) {
;       bf16_t qraw[16], kraw[16];
; #pragma unroll
;       for (int ii = 0; ii < 16; ++ii) { const bf16_t* pr = proj + ((size_t)item * 64 + ib * 16 + ii) * 3072 + col; qraw[ii] = pr[0]; kraw[ii] = pr[512]; }
;       asm volatile("" ::: "memory");
; #pragma unroll
;       for (int ii = 0; ii < 16; ++ii) {
;         const int i = ib * 16 + ii;
;         float z = bf_;
; #pragma unroll
;         for (int j4 = 0; j4 < 4; ++j4) { const f32x4 zz = *(const LAS f32x4*)(zL + i * 32 + j4 * 4); z += zz[0] * wf[j4 * 4] + zz[1] * wf[j4 * 4 + 1] + zz[2] * wf[j4 * 4 + 2] + zz[3] * wf[j4 * 4 + 3]; }
;         runf += logsig16(z);
;         const float Bi = totb - runb; runb += lsb[i];
;         const size_t tokrow = (size_t)item * 64 + i;
;         bf16_t* pr = proj + tokrow * 3072 + col;
;         const float q = bf2f(qraw[ii]), k = bf2f(kraw[ii]);
;         pr[0] = f2bf(q * __expf(runf)); pr[512] = f2bf(k * __expf(-runf));
;         QB[tokrow * 512 + col] = f2bf(q * __expf(Bi)); KB[tokrow * 512 + col] = f2bf(k * __expf(-Bi));
;       }
;       asm volatile("" ::: "memory");
;     }
;     dect[(size_t)item * 512 + col] = __expf(runf);
;     dect[(size_t)(512 + item) * 512 + col] = __expf(totb);
;   }
	s_nop 0
	s_nop 0
	s_nop 0
	s_nop 0
	s_nop 0
	s_nop 0
	s_nop 0
	s_nop 0
	s_nop 0
	s_nop 0
	s_nop 0
	s_nop 0
	s_nop 0
	s_nop 0
	s_nop 0
	s_nop 0
	s_nop 0
	s_nop 0
	s_nop 0
	s_nop 0
	s_nop 0
	s_nop 0
	s_nop 0
	s_nop 0
	s_nop 0
	s_nop 0
	s_nop 0
	s_nop 0
	s_nop 0
	s_nop 0
	s_nop 0
	s_nop 0
	s_nop 0
	s_nop 0
	s_nop 0
	s_nop 0
	s_nop 0
	s_nop 0
	s_nop 0
	s_nop 0
	s_nop 0
	s_nop 0
	s_nop 0
	s_nop 0
	s_nop 0
	s_nop 0
	s_nop 0
	s_nop 0
	s_nop 0
	s_nop 0
	s_nop 0
	s_nop 0
	s_nop 0
	s_nop 0
	s_nop 0
	s_nop 0
	s_nop 0
	s_nop 0
	s_nop 0
	s_nop 0
	s_nop 0
	s_nop 0
	s_nop 0
	s_nop 0
	s_nop 0
	s_nop 0
	s_nop 0
	s_nop 0
	s_nop 0
	s_nop 0
	s_nop 0
	s_nop 0
	s_nop 0
	s_nop 0
	s_nop 0
	s_nop 0
	s_nop 0
	s_nop 0
	s_nop 0
	s_nop 0
	s_nop 0
	s_nop 0
	s_nop 0
	s_nop 0
	s_nop 0
	s_nop 0
	s_nop 0
	s_nop 0
	s_nop 0
	s_nop 0
	s_nop 0
	s_nop 0
	s_nop 0
	s_nop 0
	s_nop 0
	s_nop 0
	s_nop 0
	s_nop 0
	s_nop 0
	s_nop 0
	s_nop 0
	s_nop 0
	s_nop 0
	s_nop 0
	s_nop 0
	s_nop 0
	s_nop 0
	s_nop 0
	s_nop 0
	s_nop 0
	s_nop 0
	s_nop 0
	s_nop 0
	s_nop 0
	s_nop 0
	s_nop 0
	s_nop 0
	s_nop 0
	s_nop 0
	s_nop 0
	s_nop 0
	s_nop 0
	s_nop 0
	s_nop 0
	s_nop 0
	s_nop 0
	s_nop 0
	s_nop 0
	s_nop 0
	s_nop 0
	s_nop 0
	s_nop 0
	s_nop 0
	s_nop 0
	s_nop 0
	s_nop 0
	s_nop 0
	s_nop 0
	s_nop 0
	s_nop 0
	s_nop 0
	s_nop 0
	s_nop 0
	s_nop 0
	s_nop 0
	s_nop 0
	s_nop 0
	s_nop 0
	s_nop 0
	s_nop 0
	s_nop 0
	s_nop 0
	s_nop 0
	s_nop 0
	s_nop 0
	s_nop 0
	s_nop 0
	s_nop 0
	s_nop 0
	s_nop 0
	s_nop 0
	s_nop 0
	s_nop 0
	s_nop 0
	s_nop 0
	s_nop 0
	s_nop 0
	s_nop 0
	s_nop 0
	s_nop 0
	s_nop 0
	s_nop 0
	s_nop 0
	s_nop 0
	s_nop 0
	s_nop 0
	s_nop 0
	s_nop 0
	s_nop 0
	s_nop 0
	s_nop 0
	s_nop 0
	s_nop 0
	s_nop 0
	s_nop 0
	s_nop 0
	s_nop 0
	s_nop 0
	s_nop 0
	s_nop 0
	s_nop 0
	s_nop 0
	s_nop 0
	s_nop 0
	s_nop 0
	s_nop 0
	s_nop 0
	s_nop 0
	s_nop 0
	s_nop 0
	s_nop 0
	s_nop 0
	s_nop 0
	s_nop 0
	s_nop 0
	s_nop 0
	s_nop 0
	s_nop 0
	s_nop 0
	s_nop 0
	s_nop 0
	s_nop 0
	s_nop 0
	s_nop 0
	s_nop 0
	s_nop 0
	s_nop 0
	s_nop 0
	s_nop 0
	s_nop 0
	s_nop 0
	s_nop 0
	s_nop 0
	s_nop 0
	s_nop 0
	s_nop 0
	s_nop 0
	s_nop 0
	s_nop 0
	s_nop 0
	s_nop 0
	s_nop 0
	s_nop 0
	s_nop 0
	s_nop 0
	s_nop 0
	s_nop 0
	s_nop 0
	s_nop 0
	s_nop 0
	s_nop 0
	s_nop 0
	s_nop 0
	s_nop 0
	s_nop 0
	s_nop 0
	s_nop 0
	s_nop 0
	s_nop 0
	s_nop 0
	s_nop 0
	s_nop 0
	s_nop 0
	s_nop 0
	s_nop 0
	s_nop 0
	s_nop 0
	s_nop 0
	s_nop 0
	s_nop 0
	s_nop 0
	s_nop 0
	s_nop 0
	s_nop 0
	s_nop 0
	s_nop 0
	s_nop 0
	s_nop 0
	s_nop 0
	s_nop 0
	s_nop 0
	s_nop 0
	s_nop 0
	s_nop 0
	s_nop 0
	s_nop 0
	s_nop 0
	s_nop 0
	s_nop 0
	s_nop 0
	s_nop 0
	s_nop 0
	s_nop 0
	s_nop 0
	s_nop 0
	s_nop 0
	s_nop 0
	s_nop 0
	s_nop 0
	s_nop 0
	s_nop 0
	s_nop 0
	s_nop 0
	s_nop 0
	s_nop 0
	s_nop 0
	s_nop 0
	s_nop 0
	s_nop 0
	s_nop 0
	s_nop 0
	s_nop 0
	s_nop 0
	s_nop 0
	s_nop 0
	s_nop 0
	s_nop 0
	s_nop 0
	s_nop 0
	s_nop 0
	s_nop 0
	s_nop 0
	s_nop 0
	s_nop 0
	s_nop 0
	s_nop 0
	s_nop 0
	s_nop 0
	s_nop 0
	s_nop 0
	s_nop 0
	s_nop 0
	s_nop 0
	s_nop 0
	s_nop 0
	s_nop 0
	s_nop 0
	s_nop 0
	s_nop 0
	s_nop 0
	s_nop 0
	s_nop 0
	s_nop 0
	s_nop 0
	s_nop 0
	s_nop 0
	s_nop 0
	s_nop 0
	s_nop 0
	s_nop 0
	s_nop 0
	s_nop 0
	s_nop 0
	s_nop 0
	s_nop 0
	s_nop 0
	s_nop 0
	s_nop 0
	s_nop 0
	s_nop 0
	s_nop 0
	s_nop 0
	s_nop 0
	s_nop 0
	s_nop 0
	s_nop 0
	s_nop 0
	s_nop 0
	s_nop 0
	s_nop 0
	s_nop 0
	s_nop 0
	s_nop 0
	s_nop 0
	s_nop 0
	s_nop 0
	s_nop 0
	s_nop 0
	s_nop 0
	s_nop 0
	s_nop 0
	s_nop 0
	s_nop 0
	s_nop 0
	s_nop 0
	s_nop 0
	s_nop 0
	s_nop 0
	s_nop 0
	s_nop 0
	s_nop 0
	s_nop 0
	s_nop 0
	s_nop 0
	s_nop 0
	s_nop 0
	s_nop 0
	s_nop 0
	s_nop 0
	s_nop 0
	s_nop 0
	s_nop 0
	s_nop 0
	s_nop 0
	s_nop 0
	s_nop 0
	s_nop 0
	s_nop 0
	s_nop 0
	s_nop 0
	s_nop 0
	s_nop 0
	s_nop 0
	s_nop 0
	s_nop 0
	s_nop 0
	s_nop 0
	s_nop 0
	s_nop 0
	s_nop 0
	s_nop 0
	s_nop 0
	s_nop 0
	s_nop 0
	s_nop 0
	s_nop 0
	s_nop 0
	s_nop 0
	s_nop 0
	s_nop 0
	s_nop 0
	s_nop 0
	s_nop 0
	s_nop 0
	s_nop 0
	s_nop 0
	s_nop 0
	s_nop 0
	s_nop 0
	s_nop 0
	s_nop 0
	s_nop 0
	s_nop 0
	s_nop 0
	s_nop 0
	s_nop 0
	s_nop 0
	s_nop 0
	s_nop 0
	s_nop 0
	s_nop 0
	s_nop 0
	s_nop 0
	s_nop 0
	s_nop 0
	s_nop 0
	s_nop 0
	s_nop 0
	s_nop 0
	s_nop 0
	s_nop 0
	s_nop 0
	s_nop 0
	s_nop 0
	s_nop 0
	s_nop 0
	s_nop 0
	s_nop 0
	s_nop 0
	s_nop 0
	s_nop 0
	s_nop 0
	s_nop 0
	s_nop 0
	s_nop 0
	s_nop 0
	s_nop 0
	s_nop 0
	s_nop 0
	s_nop 0
	s_nop 0
	s_nop 0
	s_nop 0
	s_nop 0
	s_nop 0
	s_nop 0
	s_nop 0
	s_nop 0
	s_nop 0
	s_nop 0
	s_nop 0
	s_nop 0
	s_nop 0
	s_nop 0
	s_nop 0
	s_nop 0
	s_nop 0
	s_nop 0
	s_nop 0
	s_nop 0
	s_nop 0
	s_nop 0
	s_nop 0
	s_nop 0
	s_nop 0
	s_nop 0
	s_nop 0
	s_nop 0
	s_nop 0
	s_nop 0
	s_nop 0
	s_nop 0
	s_nop 0
	s_nop 0
	s_nop 0
	s_nop 0
	s_nop 0
	s_nop 0
	s_nop 0
	s_nop 0
	s_nop 0
	s_nop 0
	s_nop 0
	s_nop 0
	s_nop 0
	s_nop 0
	s_nop 0
	s_nop 0
	s_nop 0
	s_nop 0
	s_nop 0
	s_nop 0
	s_nop 0
	s_nop 0
	s_nop 0
	s_nop 0
	s_nop 0
	s_nop 0
	s_nop 0
	s_nop 0
	s_nop 0
	s_nop 0
	s_nop 0
	s_nop 0
	s_nop 0
	s_nop 0
	s_nop 0
	s_nop 0
	s_nop 0
	s_nop 0
	s_nop 0
	s_nop 0
	s_nop 0
	s_nop 0
	s_nop 0
	s_nop 0
	s_nop 0
	s_nop 0
	s_nop 0
	s_nop 0
	s_nop 0
	s_nop 0
	s_nop 0
	s_nop 0
	s_nop 0
	s_nop 0
	s_nop 0
	s_nop 0
	s_nop 0
	s_nop 0
	s_nop 0
	s_nop 0
	s_nop 0
	s_nop 0
	s_nop 0
	s_nop 0
	s_nop 0
	s_nop 0
	s_nop 0
	s_nop 0
	s_nop 0
	s_nop 0
	s_nop 0
	s_nop 0
	s_nop 0
	s_nop 0
	s_nop 0
	s_nop 0
	s_nop 0
	s_nop 0
	s_nop 0
	s_nop 0
	s_nop 0
	s_nop 0
	s_nop 0
	s_nop 0
	s_nop 0
	s_nop 0
	s_nop 0
	s_nop 0
	s_nop 0
	s_nop 0
	s_nop 0
	s_nop 0
	s_nop 0
	s_nop 0
	s_nop 0
	s_nop 0
	s_nop 0
	s_nop 0
	s_nop 0
	s_nop 0
	s_nop 0
	s_nop 0
	s_nop 0
	s_nop 0
	s_nop 0
	s_nop 0
	s_nop 0
	s_nop 0
	s_nop 0
	s_nop 0
	s_nop 0
	s_nop 0
	s_nop 0
	s_nop 0
	s_nop 0
	s_nop 0
	s_nop 0
	s_nop 0
	s_nop 0
	s_nop 0
	s_nop 0
	s_nop 0
	s_nop 0
	s_nop 0
	s_nop 0
; #define LAS __attribute__((address_space(3)))
; DI float bf2f(bf16_t v) { return __uint_as_float(((unsigned)v) << 16); }
; DI bf16_t f2bf(float f) { return (bf16_t)(cvt_pk(f, 0.f) & 0xffffu); }
; DI float logsig16(float z) { return (fminf(z, 0.f) - __logf(1.0f + __expf(-fabsf(z)))) * (1.0f / 16.0f); }
; DI void gla_gate_phase(const Params& P, LAS unsigned char* lds, int lj) {
;     ...
;   for (int item = blockIdx.x; item < 512; item += gridDim.x) {
;     __syncthreads();
;     { const int row = tid >> 3, part = tid & 7; *(LAS f32x4*)(zL + row * 32 + part * 4) = *(const f32x4*)(zbuf + ((size_t)item * 64 + row) * 32 + part * 4); }
;     __syncthreads();
;     float lsb[64]; float totb = 0.f;
; #pragma unroll
;     for (int i = 0; i < 64; ++i) {
;       float z = bb_;
; #pragma unroll
;       for (int j4 = 0; j4 < 4; ++j4) { const f32x4 zz = *(const LAS f32x4*)(zL + i * 32 + 16 + j4 * 4); z += zz[0] * wb[j4 * 4] + zz[1] * wb[j4 * 4 + 1] + zz[2] * wb[j4 * 4 + 2] + zz[3] * wb[j4 * 4 + 3]; }
;       lsb[i] = logsig16(z); totb += lsb[i];
;     }
;     float runf = 0.f, runb = 0.f;
; #pragma unroll
;     for (int ib = 0; ib < 4; ++ib) {
;       bf16_t qraw[16], kraw[16];
; #pragma unroll
;       for (int ii = 0; ii < 16; ++ii) { const bf16_t* pr = proj + ((size_t)item * 64 + ib * 16 + ii) * 3072 + col; qraw[ii] = pr[0]; kraw[ii] = pr[512]; }
;       asm volatile("" ::: "memory");
; #pragma unroll
;       for (int ii = 0; ii < 16; ++ii) {
;         const int i = ib * 16 + ii;
;         float z = bf_;
; #pragma unroll
;         for (int j4 = 0; j4 < 4; ++j4) { const f32x4 zz = *(const LAS f32x4*)(zL + i * 32 + j4 * 4); z += zz[0] * wf[j4 * 4] + zz[1] * wf[j4 * 4 + 1] + zz[2] * wf[j4 * 4 + 2] + zz[3] * wf[j4 * 4 + 3]; }
;         runf += logsig16(z);
;         const float Bi = totb - runb; runb += lsb[i];
;         const size_t tokrow = (size_t)item * 64 + i;
;         bf16_t* pr = proj + tokrow * 3072 + col;
;         const float q = bf2f(qraw[ii]), k = bf2f(kraw[ii]);
;         pr[0] = f2bf(q * __expf(runf)); pr[512] = f2bf(k * __expf(-runf));
;         QB[tokrow * 512 + col] = f2bf(q * __expf(Bi)); KB[tokrow * 512 + col] = f2bf(k * __expf(-Bi));
;       }
;       asm volatile("" ::: "memory");
;     }
;     dect[(size_t)item * 512 + col] = __expf(runf);
;     dect[(size_t)(512 + item) * 512 + col] = __expf(totb);
;   }
	s_nop 0
	s_nop 0
	s_nop 0
	s_nop 0
	s_nop 0
	s_nop 0
	s_nop 0
	s_nop 0
	s_nop 0
	s_nop 0
	s_nop 0
	s_nop 0
	s_nop 0
	s_nop 0
	s_nop 0
	s_nop 0
	s_nop 0
	s_nop 0
	s_nop 0
	s_nop 0
	s_nop 0
	s_nop 0
	s_nop 0
	s_nop 0
	s_nop 0
	s_nop 0
	s_nop 0
	s_nop 0
	s_nop 0
	s_nop 0
	s_nop 0
	s_nop 0
	s_nop 0
	s_nop 0
	s_nop 0
	s_nop 0
	s_nop 0
	s_nop 0
	s_nop 0
	s_nop 0
	s_nop 0
	s_nop 0
	s_nop 0
	s_nop 0
	s_nop 0
	s_nop 0
	s_nop 0
	s_nop 0
	s_nop 0
	s_nop 0
	s_nop 0
	s_nop 0
	s_nop 0
	s_nop 0
	s_nop 0
	s_nop 0
	s_nop 0
	s_nop 0
	s_nop 0
	s_nop 0
	s_nop 0
	s_nop 0
	s_nop 0
	s_nop 0
	s_nop 0
	s_nop 0
	s_nop 0
	s_nop 0
	s_nop 0
	s_nop 0
	s_nop 0
	s_nop 0
	s_nop 0
	s_nop 0
	s_nop 0
	s_nop 0
	s_nop 0
	s_nop 0
	s_nop 0
	s_nop 0
	s_nop 0
	s_nop 0
	s_nop 0
	s_nop 0
	s_nop 0
	s_nop 0
	s_nop 0
	s_nop 0
	s_nop 0
	s_nop 0
	s_nop 0
	s_nop 0
	s_nop 0
	s_nop 0
	s_nop 0
	s_nop 0
	s_nop 0
	s_nop 0
	s_nop 0
	s_nop 0
	s_nop 0
	s_nop 0
	s_nop 0
	s_nop 0
	s_nop 0
	s_nop 0
	s_nop 0
	s_nop 0
	s_nop 0
	s_nop 0
	s_nop 0
	s_nop 0
	s_nop 0
	s_nop 0
	s_nop 0
	s_nop 0
	s_nop 0
	s_nop 0
	s_nop 0
	s_nop 0
	s_nop 0
	s_nop 0
	s_nop 0
	s_nop 0
	s_nop 0
	s_nop 0
	s_nop 0
	s_nop 0
	s_nop 0
	s_nop 0
	s_nop 0
	s_nop 0
	s_nop 0
	s_nop 0
	s_nop 0
	s_nop 0
	s_nop 0
	s_nop 0
	s_nop 0
	s_nop 0
	s_nop 0
	s_nop 0
	s_nop 0
	s_nop 0
	s_nop 0
	s_nop 0
	s_nop 0
	s_nop 0
	s_nop 0
	s_nop 0
	s_nop 0
	s_nop 0
	s_nop 0
	s_nop 0
	s_nop 0
	s_nop 0
	s_nop 0
	s_nop 0
	s_nop 0
	s_nop 0
	s_nop 0
	s_nop 0
	s_nop 0
	s_nop 0
	s_nop 0
	s_nop 0
	s_nop 0
	s_nop 0
	s_nop 0
	s_nop 0
	s_nop 0
	s_nop 0
	s_nop 0
	s_nop 0
	s_nop 0
	s_nop 0
	s_nop 0
	s_nop 0
	s_nop 0
	s_nop 0
	s_nop 0
	s_nop 0
	s_nop 0
	s_nop 0
	s_nop 0
	s_nop 0
	s_nop 0
	s_nop 0
	s_nop 0
	s_nop 0
	s_nop 0
	s_nop 0
	s_nop 0
	s_nop 0
	s_nop 0
	s_nop 0
	s_nop 0
	s_nop 0
	s_nop 0
	s_nop 0
	s_nop 0
	s_nop 0
	s_nop 0
	s_nop 0
	s_nop 0
	s_nop 0
	s_nop 0
	s_nop 0
	s_nop 0
	s_nop 0
	s_nop 0
	s_nop 0
	s_nop 0
	s_nop 0
	s_nop 0
	s_nop 0
	s_nop 0
	s_nop 0
	s_nop 0
	s_nop 0
	s_nop 0
	s_nop 0
	s_nop 0
	s_nop 0
	s_nop 0
	s_nop 0
	s_nop 0
	s_nop 0
	s_nop 0
	s_nop 0
	s_nop 0
	s_nop 0
	s_nop 0
	s_nop 0
	s_nop 0
	s_nop 0
	s_nop 0
	s_nop 0
	s_nop 0
	s_nop 0
	s_nop 0
	s_nop 0
	s_nop 0
	s_nop 0
	s_nop 0
	s_nop 0
	s_nop 0
	s_nop 0
	s_nop 0
	s_nop 0
	s_nop 0
	s_nop 0
	s_nop 0
	s_nop 0
	s_nop 0
	s_nop 0
	s_nop 0
	s_nop 0
	s_nop 0
	s_nop 0
	s_nop 0
	s_nop 0
	s_nop 0
	s_nop 0
	s_nop 0
	s_nop 0
	s_nop 0
	s_nop 0
	s_nop 0
	s_nop 0
	s_nop 0
	s_nop 0
	s_nop 0
	s_nop 0
	s_nop 0
	s_nop 0
	s_nop 0
	s_nop 0
	s_nop 0
	s_nop 0
	s_nop 0
	s_nop 0
	s_nop 0
	s_nop 0
	s_nop 0
	s_nop 0
	s_nop 0
	s_nop 0
	s_nop 0
	s_nop 0
	s_nop 0
	s_nop 0
	s_nop 0
	s_nop 0
	s_nop 0
	s_nop 0
	s_nop 0
	s_nop 0
	s_nop 0
	s_nop 0
	s_nop 0
	s_nop 0
	s_nop 0
	s_nop 0
	s_nop 0
	s_nop 0
	s_nop 0
	s_nop 0
	s_nop 0
	s_nop 0
	s_nop 0
	s_nop 0
	s_nop 0
	s_nop 0
	s_nop 0
	s_nop 0
	s_nop 0
	s_nop 0
	s_nop 0
	s_nop 0
	s_nop 0
	s_nop 0
	s_nop 0
	s_nop 0
	s_nop 0
	s_nop 0
	s_nop 0
	s_nop 0
	s_nop 0
	s_nop 0
	s_nop 0
	s_nop 0
	s_nop 0
	s_nop 0
	s_nop 0
	s_nop 0
	s_nop 0
	s_nop 0
	s_nop 0
	s_nop 0
	s_nop 0
	s_nop 0
	s_nop 0
	s_nop 0
	s_nop 0
	s_nop 0
	s_nop 0
	s_nop 0
	s_nop 0
	s_nop 0
	s_nop 0
	s_nop 0
	s_nop 0
	s_nop 0
	s_nop 0
	s_nop 0
	s_nop 0
	s_nop 0
	s_nop 0
	s_nop 0
	s_nop 0
	s_nop 0
	s_nop 0
	s_nop 0
	s_nop 0
	s_nop 0
	s_nop 0
	s_nop 0
	s_nop 0
	s_nop 0
	s_nop 0
	s_nop 0
	s_nop 0
	s_nop 0
	s_nop 0
	s_nop 0
	s_nop 0
	s_nop 0
	s_nop 0
	s_nop 0
	s_nop 0
	s_nop 0
	s_nop 0
	s_nop 0
	s_nop 0
	s_nop 0
	s_nop 0
	s_nop 0
	s_nop 0
	s_nop 0
	s_nop 0
	s_nop 0
	s_nop 0
	s_nop 0
	s_nop 0
	s_nop 0
	s_nop 0
	s_nop 0
	s_nop 0
	s_nop 0
	s_nop 0
	s_nop 0
	s_nop 0
	s_nop 0
	s_nop 0
	s_nop 0
	s_nop 0
	s_nop 0
	s_nop 0
	s_nop 0
	s_nop 0
	s_nop 0
	s_nop 0
	s_nop 0
	s_nop 0
	s_nop 0
	s_nop 0
	s_nop 0
	s_nop 0
	s_nop 0
	s_nop 0
	s_nop 0
	s_nop 0
	s_nop 0
	s_nop 0
	s_nop 0
	s_nop 0
	s_nop 0
	s_nop 0
	s_nop 0
	s_nop 0
	s_nop 0
	s_nop 0
	s_nop 0
	s_nop 0
	s_nop 0
	s_nop 0
	s_nop 0
	s_nop 0
	s_nop 0
	s_nop 0
	s_nop 0
	s_nop 0
	s_nop 0
	s_nop 0
	s_nop 0
	s_nop 0
	s_nop 0
	s_nop 0
	s_nop 0
	s_nop 0
	s_nop 0
	s_nop 0
	s_nop 0
	s_nop 0
	s_nop 0
	s_nop 0
	s_nop 0
	s_nop 0
	s_nop 0
	s_nop 0
	s_nop 0
	s_nop 0
	s_nop 0
	s_nop 0
	s_nop 0
	s_nop 0
	s_nop 0
	s_nop 0
	s_nop 0
	s_nop 0
	s_nop 0
	s_nop 0
	s_nop 0
	s_nop 0
	s_nop 0
	s_nop 0
	s_nop 0
	s_nop 0
	s_nop 0
	s_nop 0
	s_nop 0
	s_nop 0
	s_nop 0
	s_nop 0
	s_nop 0
	s_nop 0
	s_nop 0
	s_nop 0
	s_nop 0
	s_nop 0
	s_nop 0
	s_nop 0
	s_nop 0
	s_nop 0
	s_nop 0
	s_nop 0
	s_nop 0
	s_nop 0
	s_nop 0
	s_nop 0
	s_nop 0
	s_nop 0
	s_nop 0
	s_nop 0
	s_nop 0
	s_nop 0
	s_nop 0
	s_nop 0
	s_nop 0
	s_nop 0
	s_nop 0
	s_nop 0
	s_nop 0
	s_nop 0
	s_nop 0
	s_nop 0
	s_nop 0
	s_nop 0
	s_nop 0
	s_nop 0
	s_nop 0
	s_nop 0
	s_nop 0
	s_nop 0
	s_nop 0
	s_nop 0
	s_nop 0
	s_nop 0
	s_nop 0
	s_nop 0
	s_nop 0
	s_nop 0
	s_nop 0
	s_nop 0
	s_nop 0
	s_nop 0
	s_nop 0
	s_nop 0
	s_nop 0
	s_nop 0
	s_nop 0
	s_nop 0
	s_nop 0
	s_nop 0
	s_nop 0
	s_nop 0
	s_nop 0
	s_nop 0
	s_nop 0
	s_nop 0
	s_nop 0
	s_nop 0
	s_nop 0
	s_nop 0
	s_nop 0
	s_nop 0
	s_nop 0
	s_nop 0
	s_nop 0
	s_nop 0
	s_nop 0
	s_nop 0
	s_nop 0
	s_nop 0
	s_nop 0
	s_nop 0
	s_nop 0
	s_nop 0
	s_nop 0
	s_nop 0
	s_nop 0
	s_nop 0
	s_nop 0
	s_nop 0
	s_nop 0
	s_nop 0
	s_nop 0
	s_nop 0
	s_nop 0
	s_nop 0
	s_nop 0
	s_nop 0
	s_nop 0
	s_nop 0
	s_nop 0
	s_nop 0
	s_nop 0
	s_nop 0
	s_nop 0
	s_nop 0
	s_nop 0
	s_nop 0
	s_nop 0
	s_nop 0
	s_nop 0
	s_nop 0
	s_nop 0
	s_nop 0
	s_nop 0
	s_nop 0
	s_nop 0
	s_nop 0
	s_nop 0
	s_nop 0
	s_nop 0
	s_nop 0
	s_nop 0
	s_nop 0
	s_nop 0
	s_nop 0
	s_nop 0
	s_nop 0
	s_nop 0
	s_nop 0
	s_nop 0
	s_nop 0
	s_nop 0
	s_nop 0
	s_nop 0
	s_nop 0
	s_nop 0
	s_nop 0
	s_nop 0
	s_nop 0
	s_nop 0
	s_nop 0
; #define LAS __attribute__((address_space(3)))
; DI float bf2f(bf16_t v) { return __uint_as_float(((unsigned)v) << 16); }
; DI bf16_t f2bf(float f) { return (bf16_t)(cvt_pk(f, 0.f) & 0xffffu); }
; DI float logsig16(float z) { return (fminf(z, 0.f) - __logf(1.0f + __expf(-fabsf(z)))) * (1.0f / 16.0f); }
; DI void gla_gate_phase(const Params& P, LAS unsigned char* lds, int lj) {
;     ...
;   for (int item = blockIdx.x; item < 512; item += gridDim.x) {
;     __syncthreads();
;     { const int row = tid >> 3, part = tid & 7; *(LAS f32x4*)(zL + row * 32 + part * 4) = *(const f32x4*)(zbuf + ((size_t)item * 64 + row) * 32 + part * 4); }
;     __syncthreads();
;     float lsb[64]; float totb = 0.f;
; #pragma unroll
;     for (int i = 0; i < 64; ++i) {
;       float z = bb_;
; #pragma unroll
;       for (int j4 = 0; j4 < 4; ++j4) { const f32x4 zz = *(const LAS f32x4*)(zL + i * 32 + 16 + j4 * 4); z += zz[0] * wb[j4 * 4] + zz[1] * wb[j4 * 4 + 1] + zz[2] * wb[j4 * 4 + 2] + zz[3] * wb[j4 * 4 + 3]; }
;       lsb[i] = logsig16(z); totb += lsb[i];
;     }
;     float runf = 0.f, runb = 0.f;
; #pragma unroll
;     for (int ib = 0; ib < 4; ++ib) {
;       bf16_t qraw[16], kraw[16];
; #pragma unroll
;       for (int ii = 0; ii < 16; ++ii) { const bf16_t* pr = proj + ((size_t)item * 64 + ib * 16 + ii) * 3072 + col; qraw[ii] = pr[0]; kraw[ii] = pr[512]; }
;       asm volatile("" ::: "memory");
; #pragma unroll
;       for (int ii = 0; ii < 16; ++ii) {
;         const int i = ib * 16 + ii;
;         float z = bf_;
; #pragma unroll
;         for (int j4 = 0; j4 < 4; ++j4) { const f32x4 zz = *(const LAS f32x4*)(zL + i * 32 + j4 * 4); z += zz[0] * wf[j4 * 4] + zz[1] * wf[j4 * 4 + 1] + zz[2] * wf[j4 * 4 + 2] + zz[3] * wf[j4 * 4 + 3]; }
;         runf += logsig16(z);
;         const float Bi = totb - runb; runb += lsb[i];
;         const size_t tokrow = (size_t)item * 64 + i;
;         bf16_t* pr = proj + tokrow * 3072 + col;
;         const float q = bf2f(qraw[ii]), k = bf2f(kraw[ii]);
;         pr[0] = f2bf(q * __expf(runf)); pr[512] = f2bf(k * __expf(-runf));
;         QB[tokrow * 512 + col] = f2bf(q * __expf(Bi)); KB[tokrow * 512 + col] = f2bf(k * __expf(-Bi));
;       }
;       asm volatile("" ::: "memory");
;     }
;     dect[(size_t)item * 512 + col] = __expf(runf);
;     dect[(size_t)(512 + item) * 512 + col] = __expf(totb);
;   }
	s_nop 0
	s_nop 0
	s_nop 0
	s_nop 0
	s_nop 0
	s_nop 0
	s_nop 0
	s_nop 0
	s_nop 0
	s_nop 0
	s_nop 0
	s_nop 0
	s_nop 0
	s_nop 0
	s_nop 0
	s_nop 0
	s_nop 0
	s_nop 0
	s_nop 0
	s_nop 0
	s_nop 0
	s_nop 0
	s_nop 0
	s_nop 0
	s_nop 0
	s_nop 0
	s_nop 0
	s_nop 0
	s_nop 0
	s_nop 0
	s_nop 0
	s_nop 0
	s_nop 0
	s_nop 0
	s_nop 0
	s_nop 0
	s_nop 0
	s_nop 0
	s_nop 0
	s_nop 0
	s_nop 0
	s_nop 0
	s_nop 0
	s_nop 0
	s_nop 0
	s_nop 0
	s_nop 0
	s_nop 0
	s_nop 0
	s_nop 0
	s_nop 0
	s_nop 0
	s_nop 0
	s_nop 0
	s_nop 0
	s_nop 0
	s_nop 0
	s_nop 0
	s_nop 0
	s_nop 0
	s_nop 0
	s_nop 0
	s_nop 0
	s_nop 0
	s_nop 0
	s_nop 0
	s_nop 0
	s_nop 0
	s_nop 0
	s_nop 0
	s_nop 0
	s_nop 0
	s_nop 0
	s_nop 0
	s_nop 0
	s_nop 0
	s_nop 0
	s_nop 0
	s_nop 0
	s_nop 0
	s_nop 0
	s_nop 0
	s_nop 0
	s_nop 0
	s_nop 0
	s_nop 0
	s_nop 0
	s_nop 0
	s_nop 0
	s_nop 0
	s_nop 0
	s_nop 0
	s_nop 0
	s_nop 0
	s_nop 0
	s_nop 0
	s_nop 0
	s_nop 0
	s_nop 0
	s_nop 0
	s_nop 0
	s_nop 0
	s_nop 0
	s_nop 0
	s_nop 0
	s_nop 0
	s_nop 0
	s_nop 0
	s_nop 0
	s_nop 0
	s_nop 0
	s_nop 0
	s_nop 0
	s_nop 0
	s_nop 0
	s_nop 0
	s_nop 0
	s_nop 0
	s_nop 0
	s_nop 0
	s_nop 0
	s_nop 0
	s_nop 0
	s_nop 0
	s_nop 0
	s_nop 0
	s_nop 0
	s_nop 0
	s_nop 0
	s_nop 0
	s_nop 0
	s_nop 0
	s_nop 0
	s_nop 0
	s_nop 0
	s_nop 0
	s_nop 0
	s_nop 0
	s_nop 0
	s_nop 0
	s_nop 0
	s_nop 0
	s_nop 0
	s_nop 0
	s_nop 0
	s_nop 0
	s_nop 0
	s_nop 0
	s_nop 0
	s_nop 0
	s_nop 0
	s_nop 0
	s_nop 0
	s_nop 0
	s_nop 0
	s_nop 0
	s_nop 0
	s_nop 0
	s_nop 0
	s_nop 0
	s_nop 0
	s_nop 0
	s_nop 0
	s_nop 0
	s_nop 0
	s_nop 0
	s_nop 0
	s_nop 0
	s_nop 0
	s_nop 0
	s_nop 0
	s_nop 0
	s_nop 0
	s_nop 0
	s_nop 0
	s_nop 0
	s_nop 0
	s_nop 0
	s_nop 0
	s_nop 0
	s_nop 0
	s_nop 0
	s_nop 0
	s_nop 0
	s_nop 0
	s_nop 0
	s_nop 0
	s_nop 0
	s_nop 0
	s_nop 0
	s_nop 0
	s_nop 0
	s_nop 0
	s_nop 0
	s_nop 0
	s_nop 0
	s_nop 0
	s_nop 0
	s_nop 0
	s_nop 0
	s_nop 0
	s_nop 0
	s_nop 0
	s_nop 0
	s_nop 0
	s_nop 0
	s_nop 0
	s_nop 0
	s_nop 0
	s_nop 0
	s_nop 0
	s_nop 0
	s_nop 0
	s_nop 0
	s_nop 0
	s_nop 0
	s_nop 0
	s_nop 0
	s_nop 0
	s_nop 0
	s_nop 0
	s_nop 0
	s_nop 0
	s_nop 0
	s_nop 0
	s_nop 0
	s_nop 0
	s_nop 0
	s_nop 0
	s_nop 0
	s_nop 0
	s_nop 0
	s_nop 0
	s_nop 0
	s_nop 0
	s_nop 0
	s_nop 0
	s_nop 0
	s_nop 0
	s_nop 0
	s_nop 0
	s_nop 0
	s_nop 0
	s_nop 0
	s_nop 0
	s_nop 0
	s_nop 0
	s_nop 0
	s_nop 0
	s_nop 0
	s_nop 0
	s_nop 0
	s_nop 0
	s_nop 0
	s_nop 0
	s_nop 0
	s_nop 0
	s_nop 0
	s_nop 0
	s_nop 0
	s_nop 0
	s_nop 0
	s_nop 0
	s_nop 0
	s_nop 0
	s_nop 0
	s_nop 0
	s_nop 0
	s_nop 0
	s_nop 0
	s_nop 0
	s_nop 0
	s_nop 0
	s_nop 0
	s_nop 0
	s_nop 0
	s_nop 0
	s_nop 0
	s_nop 0
	s_nop 0
	s_nop 0
	s_nop 0
	s_nop 0
	s_nop 0
	s_nop 0
	s_nop 0
	s_nop 0
	s_nop 0
	s_nop 0
	s_nop 0
	s_nop 0
	s_nop 0
	s_nop 0
	s_nop 0
	s_nop 0
	s_nop 0
	s_nop 0
	s_nop 0
	s_nop 0
	s_nop 0
	s_nop 0
	s_nop 0
	s_nop 0
	s_nop 0
	s_nop 0
	s_nop 0
	s_nop 0
	s_nop 0
	s_nop 0
	s_nop 0
	s_nop 0
	s_nop 0
	s_nop 0
	s_nop 0
	s_nop 0
	s_nop 0
	s_nop 0
	s_nop 0
	s_nop 0
	s_nop 0
	s_nop 0
	s_nop 0
	s_nop 0
	s_nop 0
	s_nop 0
	s_nop 0
	s_nop 0
	s_nop 0
	s_nop 0
	s_nop 0
	s_nop 0
	s_nop 0
	s_nop 0
	s_nop 0
	s_nop 0
	s_nop 0
	s_nop 0
	s_nop 0
	s_nop 0
	s_nop 0
	s_nop 0
	s_nop 0
	s_nop 0
	s_nop 0
	s_nop 0
	s_nop 0
	s_nop 0
	s_nop 0
	s_nop 0
	s_nop 0
	s_nop 0
	s_nop 0
	s_nop 0
	s_nop 0
	s_nop 0
	s_nop 0
	s_nop 0
	s_nop 0
	s_nop 0
	s_nop 0
	s_nop 0
	s_nop 0
	s_nop 0
	s_nop 0
	s_nop 0
	s_nop 0
	s_nop 0
	s_nop 0
	s_nop 0
	s_nop 0
	s_nop 0
	s_nop 0
	s_nop 0
	s_nop 0
	s_nop 0
	s_nop 0
	s_nop 0
	s_nop 0
	s_nop 0
	s_nop 0
	s_nop 0
	s_nop 0
	s_nop 0
	s_nop 0
	s_nop 0
	s_nop 0
	s_nop 0
	s_nop 0
	s_nop 0
	s_nop 0
	s_nop 0
	s_nop 0
	s_nop 0
	s_nop 0
	s_nop 0
	s_nop 0
	s_nop 0
	s_nop 0
	s_nop 0
	s_nop 0
	s_nop 0
	s_nop 0
	s_nop 0
	s_nop 0
	s_nop 0
	s_nop 0
	s_nop 0
	s_nop 0
	s_nop 0
	s_nop 0
	s_nop 0
	s_nop 0
	s_nop 0
	s_nop 0
	s_nop 0
	s_nop 0
	s_nop 0
	s_nop 0
	s_nop 0
	s_nop 0
	s_nop 0
	s_nop 0
	s_nop 0
	s_nop 0
	s_nop 0
	s_nop 0
	s_nop 0
	s_nop 0
	s_nop 0
	s_nop 0
	s_nop 0
	s_nop 0
	s_nop 0
	s_nop 0
	s_nop 0
	s_nop 0
	s_nop 0
	s_nop 0
	s_nop 0
	s_nop 0
	s_nop 0
	s_nop 0
	s_nop 0
	s_nop 0
	s_nop 0
	s_nop 0
	s_nop 0
	s_nop 0
	s_nop 0
	s_nop 0
	s_nop 0
	s_nop 0
	s_nop 0
	s_nop 0
	s_nop 0
	s_nop 0
	s_nop 0
	s_nop 0
	s_nop 0
	s_nop 0
	s_nop 0
	s_nop 0
	s_nop 0
	s_nop 0
	s_nop 0
	s_nop 0
	s_nop 0
	s_nop 0
	s_nop 0
	s_nop 0
	s_nop 0
	s_nop 0
	s_nop 0
	s_nop 0
	s_nop 0
	s_nop 0
	s_nop 0
	s_nop 0
	s_nop 0
	s_nop 0
	s_nop 0
	s_nop 0
	s_nop 0
	s_nop 0
	s_nop 0
	s_nop 0
	s_nop 0
	s_nop 0
	s_nop 0
	s_nop 0
	s_nop 0
	s_nop 0
	s_nop 0
	s_nop 0
	s_nop 0
	s_nop 0
	s_nop 0
	s_nop 0
	s_nop 0
	s_nop 0
	s_nop 0
	s_nop 0
	s_nop 0
	s_nop 0
	s_nop 0
	s_nop 0
	s_nop 0
	s_nop 0
	s_nop 0
	s_nop 0
	s_nop 0
	s_nop 0
	s_nop 0
	s_nop 0
	s_nop 0
	s_nop 0
	s_nop 0
	s_nop 0
	s_nop 0
	s_nop 0
	s_nop 0
	s_nop 0
	s_nop 0
	s_nop 0
	s_nop 0
	s_nop 0
	s_nop 0
	s_nop 0
	s_nop 0
	s_nop 0
	s_nop 0
	s_nop 0
	s_nop 0
	s_nop 0
	s_nop 0
	s_nop 0
	s_nop 0
	s_nop 0
	s_nop 0
	s_nop 0
	s_nop 0
	s_nop 0
	s_nop 0
	s_nop 0
	s_nop 0
	s_nop 0
	s_nop 0
	s_nop 0
	s_nop 0
	s_nop 0
	s_nop 0
	s_nop 0
	s_nop 0
	s_nop 0
	s_nop 0
	s_nop 0
	s_nop 0
	s_nop 0
	s_nop 0
	s_nop 0
	s_nop 0
	s_nop 0
	s_nop 0
	s_nop 0
	s_nop 0
	s_nop 0
	s_nop 0
	s_nop 0
	s_nop 0
	s_nop 0
	s_nop 0
	s_nop 0
	s_nop 0
	s_nop 0
	s_nop 0
	s_nop 0
	s_nop 0
	s_nop 0
	s_nop 0
	s_nop 0
	s_nop 0
	s_nop 0
	s_nop 0
	s_nop 0
	s_nop 0
	s_nop 0
	s_nop 0
	s_nop 0
	s_nop 0
	s_nop 0
	s_nop 0
	s_nop 0
	s_nop 0
	s_nop 0
	s_nop 0
	s_nop 0
	s_nop 0
	s_nop 0
	s_nop 0
	s_nop 0
	s_nop 0
	s_nop 0
	s_nop 0
	s_nop 0
	s_nop 0
	s_nop 0
	s_nop 0
	s_nop 0
	s_nop 0
	s_nop 0
	s_nop 0
	s_nop 0
	s_nop 0
	s_nop 0
	s_nop 0
	s_nop 0
	s_nop 0
	s_nop 0
	s_nop 0
	s_nop 0
	s_nop 0
	s_nop 0
	s_nop 0
	s_nop 0
	s_nop 0
	s_nop 0
	s_nop 0
; #define LAS __attribute__((address_space(3)))
; DI float bf2f(bf16_t v) { return __uint_as_float(((unsigned)v) << 16); }
; DI bf16_t f2bf(float f) { return (bf16_t)(cvt_pk(f, 0.f) & 0xffffu); }
; DI float logsig16(float z) { return (fminf(z, 0.f) - __logf(1.0f + __expf(-fabsf(z)))) * (1.0f / 16.0f); }
; DI void gla_gate_phase(const Params& P, LAS unsigned char* lds, int lj) {
;     ...
;   for (int item = blockIdx.x; item < 512; item += gridDim.x) {
;     __syncthreads();
;     { const int row = tid >> 3, part = tid & 7; *(LAS f32x4*)(zL + row * 32 + part * 4) = *(const f32x4*)(zbuf + ((size_t)item * 64 + row) * 32 + part * 4); }
;     __syncthreads();
;     float lsb[64]; float totb = 0.f;
; #pragma unroll
;     for (int i = 0; i < 64; ++i) {
;       float z = bb_;
; #pragma unroll
;       for (int j4 = 0; j4 < 4; ++j4) { const f32x4 zz = *(const LAS f32x4*)(zL + i * 32 + 16 + j4 * 4); z += zz[0] * wb[j4 * 4] + zz[1] * wb[j4 * 4 + 1] + zz[2] * wb[j4 * 4 + 2] + zz[3] * wb[j4 * 4 + 3]; }
;       lsb[i] = logsig16(z); totb += lsb[i];
;     }
;     float runf = 0.f, runb = 0.f;
; #pragma unroll
;     for (int ib = 0; ib < 4; ++ib) {
;       bf16_t qraw[16], kraw[16];
; #pragma unroll
;       for (int ii = 0; ii < 16; ++ii) { const bf16_t* pr = proj + ((size_t)item * 64 + ib * 16 + ii) * 3072 + col; qraw[ii] = pr[0]; kraw[ii] = pr[512]; }
;       asm volatile("" ::: "memory");
; #pragma unroll
;       for (int ii = 0; ii < 16; ++ii) {
;         const int i = ib * 16 + ii;
;         float z = bf_;
; #pragma unroll
;         for (int j4 = 0; j4 < 4; ++j4) { const f32x4 zz = *(const LAS f32x4*)(zL + i * 32 + j4 * 4); z += zz[0] * wf[j4 * 4] + zz[1] * wf[j4 * 4 + 1] + zz[2] * wf[j4 * 4 + 2] + zz[3] * wf[j4 * 4 + 3]; }
;         runf += logsig16(z);
;         const float Bi = totb - runb; runb += lsb[i];
;         const size_t tokrow = (size_t)item * 64 + i;
;         bf16_t* pr = proj + tokrow * 3072 + col;
;         const float q = bf2f(qraw[ii]), k = bf2f(kraw[ii]);
;         pr[0] = f2bf(q * __expf(runf)); pr[512] = f2bf(k * __expf(-runf));
;         QB[tokrow * 512 + col] = f2bf(q * __expf(Bi)); KB[tokrow * 512 + col] = f2bf(k * __expf(-Bi));
;       }
;       asm volatile("" ::: "memory");
;     }
;     dect[(size_t)item * 512 + col] = __expf(runf);
;     dect[(size_t)(512 + item) * 512 + col] = __expf(totb);
;   }
	s_nop 0
	s_nop 0
	s_nop 0
	s_nop 0
	s_nop 0
	s_nop 0
	s_nop 0
	s_nop 0
	s_nop 0
	s_nop 0
	s_nop 0
	s_nop 0
	s_nop 0
	s_nop 0
	s_nop 0
	s_nop 0
	s_nop 0
	s_nop 0
	s_nop 0
	s_nop 0
	s_nop 0
	s_nop 0
	s_nop 0
	s_nop 0
	s_nop 0
	s_nop 0
	s_nop 0
	s_nop 0
	s_nop 0
	s_nop 0
	s_nop 0
	s_nop 0
	s_nop 0
	s_nop 0
	s_nop 0
	s_nop 0
	s_nop 0
	s_nop 0
	s_nop 0
	s_nop 0
	s_nop 0
	s_nop 0
	s_nop 0
	s_nop 0
	s_nop 0
	s_nop 0
	s_nop 0
	s_nop 0
	s_nop 0
	s_nop 0
	s_nop 0
	s_nop 0
	s_nop 0
	s_nop 0
	s_nop 0
	s_nop 0
	s_nop 0
	s_nop 0
	s_nop 0
	s_nop 0
	s_nop 0
	s_nop 0
	s_nop 0
	s_nop 0
	s_nop 0
	s_nop 0
	s_nop 0
	s_nop 0
	s_nop 0
	s_nop 0
	s_nop 0
	s_nop 0
	s_nop 0
	s_nop 0
	s_nop 0
	s_nop 0
	s_nop 0
	s_nop 0
	s_nop 0
	s_nop 0
	s_nop 0
	s_nop 0
	s_nop 0
	s_nop 0
	s_nop 0
	s_nop 0
	s_nop 0
	s_nop 0
	s_nop 0
	s_nop 0
	s_nop 0
	s_nop 0
	s_nop 0
	s_nop 0
	s_nop 0
	s_nop 0
	s_nop 0
	s_nop 0
	s_nop 0
	s_nop 0
	s_nop 0
	s_nop 0
	s_nop 0
	s_nop 0
	s_nop 0
	s_nop 0
	s_nop 0
	s_nop 0
	s_nop 0
	s_nop 0
	s_nop 0
	s_nop 0
	s_nop 0
	s_nop 0
	s_nop 0
	s_nop 0
	s_nop 0
	s_nop 0
	s_nop 0
	s_nop 0
	s_nop 0
	s_nop 0
	s_nop 0
	s_nop 0
	s_nop 0
	s_nop 0
	s_nop 0
	s_nop 0
	s_nop 0
	s_nop 0
	s_nop 0
	s_nop 0
	s_nop 0
	s_nop 0
	s_nop 0
	s_nop 0
	s_nop 0
	s_nop 0
	s_nop 0
	s_nop 0
	s_nop 0
	s_nop 0
	s_nop 0
	s_nop 0
	s_nop 0
	s_nop 0
	s_nop 0
	s_nop 0
	s_nop 0
	s_nop 0
	s_nop 0
	s_nop 0
	s_nop 0
	s_nop 0
	s_nop 0
	s_nop 0
	s_nop 0
	s_nop 0
	s_nop 0
	s_nop 0
	s_nop 0
	s_nop 0
	s_nop 0
	s_nop 0
	s_nop 0
	s_nop 0
	s_nop 0
	s_nop 0
	s_nop 0
	s_nop 0
	s_nop 0
	s_nop 0
	s_nop 0
	s_nop 0
	s_nop 0
	s_nop 0
	s_nop 0
	s_nop 0
	s_nop 0
	s_nop 0
	s_nop 0
	s_nop 0
	s_nop 0
	s_nop 0
	s_nop 0
	s_nop 0
	s_nop 0
	s_nop 0
	s_nop 0
	s_nop 0
	s_nop 0
	s_nop 0
	s_nop 0
	s_nop 0
	s_nop 0
	s_nop 0
	s_nop 0
	s_nop 0
	s_nop 0
	s_nop 0
	s_nop 0
	s_nop 0
	s_nop 0
	s_nop 0
	s_nop 0
	s_nop 0
	s_nop 0
	s_nop 0
	s_nop 0
	s_nop 0
	s_nop 0
	s_nop 0
	s_nop 0
	s_nop 0
	s_nop 0
	s_nop 0
	s_nop 0
	s_nop 0
	s_nop 0
	s_nop 0
	s_nop 0
	s_nop 0
	s_nop 0
	s_nop 0
	s_nop 0
	s_nop 0
	s_nop 0
	s_nop 0
	s_nop 0
	s_nop 0
	s_nop 0
	s_nop 0
	s_nop 0
	s_nop 0
	s_nop 0
	s_nop 0
	s_nop 0
	s_nop 0
	s_nop 0
	s_nop 0
	s_nop 0
	s_nop 0
	s_nop 0
	s_nop 0
	s_nop 0
	s_nop 0
	s_nop 0
	s_nop 0
	s_nop 0
	s_nop 0
	s_nop 0
	s_nop 0
	s_nop 0
	s_nop 0
	s_nop 0
	s_nop 0
	s_nop 0
	s_nop 0
	s_nop 0
	s_nop 0
	s_nop 0
	s_nop 0
	s_nop 0
	s_nop 0
	s_nop 0
	s_nop 0
	s_nop 0
	s_nop 0
	s_nop 0
	s_nop 0
	s_nop 0
	s_nop 0
	s_nop 0
	s_nop 0
	s_nop 0
	s_nop 0
	s_nop 0
	s_nop 0
	s_nop 0
	s_nop 0
	s_nop 0
	s_nop 0
	s_nop 0
	s_nop 0
	s_nop 0
	s_nop 0
	s_nop 0
	s_nop 0
	s_nop 0
	s_nop 0
	s_nop 0
	s_nop 0
	s_nop 0
	s_nop 0
	s_nop 0
	s_nop 0
	s_nop 0
	s_nop 0
	s_nop 0
	s_nop 0
	s_nop 0
	s_nop 0
	s_nop 0
	s_nop 0
	s_nop 0
	s_nop 0
	s_nop 0
	s_nop 0
	s_nop 0
	s_nop 0
	s_nop 0
	s_nop 0
	s_nop 0
	s_nop 0
	s_nop 0
	s_nop 0
	s_nop 0
	s_nop 0
	s_nop 0
	s_nop 0
	s_nop 0
	s_nop 0
	s_nop 0
	s_nop 0
	s_nop 0
	s_nop 0
	s_nop 0
	s_nop 0
	s_nop 0
	s_nop 0
	s_nop 0
	s_nop 0
	s_nop 0
	s_nop 0
	s_nop 0
	s_nop 0
	s_nop 0
	s_nop 0
	s_nop 0
	s_nop 0
	s_nop 0
	s_nop 0
	s_nop 0
	s_nop 0
	s_nop 0
	s_nop 0
	s_nop 0
	s_nop 0
	s_nop 0
	s_nop 0
	s_nop 0
	s_nop 0
	s_nop 0
	s_nop 0
	s_nop 0
	s_nop 0
	s_nop 0
	s_nop 0
	s_nop 0
	s_nop 0
	s_nop 0
	s_nop 0
	s_nop 0
	s_nop 0
	s_nop 0
	s_nop 0
	s_nop 0
	s_nop 0
	s_nop 0
	s_nop 0
	s_nop 0
	s_nop 0
	s_nop 0
	s_nop 0
	s_nop 0
	s_nop 0
	s_nop 0
	s_nop 0
	s_nop 0
	s_nop 0
	s_nop 0
	s_nop 0
	s_nop 0
	s_nop 0
	s_nop 0
	s_nop 0
	s_nop 0
	s_nop 0
	s_nop 0
	s_nop 0
	s_nop 0
	s_nop 0
	s_nop 0
	s_nop 0
	s_nop 0
	s_nop 0
	s_nop 0
	s_nop 0
	s_nop 0
	s_nop 0
	s_nop 0
	s_nop 0
	s_nop 0
	s_nop 0
	s_nop 0
	s_nop 0
	s_nop 0
	s_nop 0
	s_nop 0
	s_nop 0
	s_nop 0
	s_nop 0
	s_nop 0
	s_nop 0
	s_nop 0
	s_nop 0
	s_nop 0
	s_nop 0
	s_nop 0
	s_nop 0
	s_nop 0
	s_nop 0
	s_nop 0
	s_nop 0
	s_nop 0
	s_nop 0
	s_nop 0
	s_nop 0
	s_nop 0
	s_nop 0
	s_nop 0
	s_nop 0
	s_nop 0
	s_nop 0
	s_nop 0
	s_nop 0
	s_nop 0
	s_nop 0
	s_nop 0
	s_nop 0
	s_nop 0
	s_nop 0
	s_nop 0
	s_nop 0
	s_nop 0
	s_nop 0
	s_nop 0
	s_nop 0
	s_nop 0
	s_nop 0
	s_nop 0
	s_nop 0
	s_nop 0
	s_nop 0
	s_nop 0
	s_nop 0
	s_nop 0
	s_nop 0
	s_nop 0
	s_nop 0
	s_nop 0
	s_nop 0
	s_nop 0
	s_nop 0
	s_nop 0
	s_nop 0
	s_nop 0
	s_nop 0
	s_nop 0
	s_nop 0
	s_nop 0
	s_nop 0
	s_nop 0
	s_nop 0
	s_nop 0
	s_nop 0
	s_nop 0
	s_nop 0
	s_nop 0
	s_nop 0
	s_nop 0
	s_nop 0
	s_nop 0
	s_nop 0
	s_nop 0
	s_nop 0
	s_nop 0
	s_nop 0
	s_nop 0
	s_nop 0
	s_nop 0
	s_nop 0
	s_nop 0
	s_nop 0
	s_nop 0
	s_nop 0
	s_nop 0
	s_nop 0
	s_nop 0
	s_nop 0
	s_nop 0
	s_nop 0
	s_nop 0
	s_nop 0
	s_nop 0
	s_nop 0
	s_nop 0
	s_nop 0
	s_nop 0
	s_nop 0
	s_nop 0
	s_nop 0
	s_nop 0
	s_nop 0
	s_nop 0
	s_nop 0
	s_nop 0
	s_nop 0
	s_nop 0
	s_nop 0
	s_nop 0
	s_nop 0
	s_nop 0
	s_nop 0
	s_nop 0
	s_nop 0
	s_nop 0
	s_nop 0
	s_nop 0
	s_nop 0
	s_nop 0
	s_nop 0
	s_nop 0
	s_nop 0
	s_nop 0
	s_nop 0
	s_nop 0
	s_nop 0
	s_nop 0
	s_nop 0
	s_nop 0
	s_nop 0
	s_nop 0
	s_nop 0
	s_nop 0
	s_nop 0
	s_nop 0
	s_nop 0
	s_nop 0
	s_nop 0
	s_nop 0
	s_nop 0
	s_nop 0
	s_nop 0
	s_nop 0
	s_nop 0
	s_nop 0
	s_nop 0
	s_nop 0
	s_nop 0
	s_nop 0
	s_nop 0
	s_nop 0
	s_nop 0
	s_nop 0
	s_nop 0
	s_nop 0
	s_nop 0
	s_nop 0
	s_nop 0
	s_nop 0
	s_nop 0
	s_nop 0
	s_nop 0
	s_nop 0
	s_nop 0
	s_nop 0
	s_nop 0
	s_nop 0
	s_nop 0
	s_nop 0
	s_nop 0
	s_nop 0
	s_nop 0
	s_nop 0
	s_nop 0
	s_nop 0
	s_nop 0
	s_nop 0
	s_nop 0
	s_nop 0
	s_nop 0
	s_nop 0
	s_nop 0
	s_nop 0
	s_nop 0
	s_nop 0
	s_nop 0
	s_nop 0
	s_nop 0
	s_nop 0
	s_nop 0
	s_nop 0
	s_nop 0
	s_nop 0
	s_nop 0
	s_nop 0
	s_nop 0
	s_nop 0
	s_nop 0
	s_nop 0
	s_nop 0
	s_nop 0
	s_nop 0
	s_nop 0
	s_nop 0
	s_nop 0
	s_nop 0
	s_nop 0
	s_nop 0
	s_nop 0
	s_nop 0
	s_nop 0
	s_nop 0
	s_nop 0
	s_nop 0
	s_nop 0
; #define LAS __attribute__((address_space(3)))
; DI float bf2f(bf16_t v) { return __uint_as_float(((unsigned)v) << 16); }
; DI bf16_t f2bf(float f) { return (bf16_t)(cvt_pk(f, 0.f) & 0xffffu); }
; DI float logsig16(float z) { return (fminf(z, 0.f) - __logf(1.0f + __expf(-fabsf(z)))) * (1.0f / 16.0f); }
; DI void gla_gate_phase(const Params& P, LAS unsigned char* lds, int lj) {
;     ...
;   for (int item = blockIdx.x; item < 512; item += gridDim.x) {
;     __syncthreads();
;     { const int row = tid >> 3, part = tid & 7; *(LAS f32x4*)(zL + row * 32 + part * 4) = *(const f32x4*)(zbuf + ((size_t)item * 64 + row) * 32 + part * 4); }
;     __syncthreads();
;     float lsb[64]; float totb = 0.f;
; #pragma unroll
;     for (int i = 0; i < 64; ++i) {
;       float z = bb_;
; #pragma unroll
;       for (int j4 = 0; j4 < 4; ++j4) { const f32x4 zz = *(const LAS f32x4*)(zL + i * 32 + 16 + j4 * 4); z += zz[0] * wb[j4 * 4] + zz[1] * wb[j4 * 4 + 1] + zz[2] * wb[j4 * 4 + 2] + zz[3] * wb[j4 * 4 + 3]; }
;       lsb[i] = logsig16(z); totb += lsb[i];
;     }
;     float runf = 0.f, runb = 0.f;
; #pragma unroll
;     for (int ib = 0; ib < 4; ++ib) {
;       bf16_t qraw[16], kraw[16];
; #pragma unroll
;       for (int ii = 0; ii < 16; ++ii) { const bf16_t* pr = proj + ((size_t)item * 64 + ib * 16 + ii) * 3072 + col; qraw[ii] = pr[0]; kraw[ii] = pr[512]; }
;       asm volatile("" ::: "memory");
; #pragma unroll
;       for (int ii = 0; ii < 16; ++ii) {
;         const int i = ib * 16 + ii;
;         float z = bf_;
; #pragma unroll
;         for (int j4 = 0; j4 < 4; ++j4) { const f32x4 zz = *(const LAS f32x4*)(zL + i * 32 + j4 * 4); z += zz[0] * wf[j4 * 4] + zz[1] * wf[j4 * 4 + 1] + zz[2] * wf[j4 * 4 + 2] + zz[3] * wf[j4 * 4 + 3]; }
;         runf += logsig16(z);
;         const float Bi = totb - runb; runb += lsb[i];
;         const size_t tokrow = (size_t)item * 64 + i;
;         bf16_t* pr = proj + tokrow * 3072 + col;
;         const float q = bf2f(qraw[ii]), k = bf2f(kraw[ii]);
;         pr[0] = f2bf(q * __expf(runf)); pr[512] = f2bf(k * __expf(-runf));
;         QB[tokrow * 512 + col] = f2bf(q * __expf(Bi)); KB[tokrow * 512 + col] = f2bf(k * __expf(-Bi));
;       }
;       asm volatile("" ::: "memory");
;     }
;     dect[(size_t)item * 512 + col] = __expf(runf);
;     dect[(size_t)(512 + item) * 512 + col] = __expf(totb);
;   }
	s_nop 0
	s_nop 0
	s_nop 0
	s_nop 0
	s_nop 0
	s_nop 0
	s_nop 0
	s_nop 0
	s_nop 0
	s_nop 0
	s_nop 0
	s_nop 0
	s_nop 0
	s_nop 0
	s_nop 0
	s_nop 0
	s_nop 0
	s_nop 0
	s_nop 0
	s_nop 0
	s_nop 0
	s_nop 0
	s_nop 0
	s_nop 0
	s_nop 0
	s_nop 0
	s_nop 0
	s_nop 0
	s_nop 0
	s_nop 0
	s_nop 0
	s_nop 0
	s_nop 0
	s_nop 0
	s_nop 0
	s_nop 0
	s_nop 0
	s_nop 0
	s_nop 0
	s_nop 0
	s_nop 0
	s_nop 0
	s_nop 0
	s_nop 0
	s_nop 0
	s_nop 0
	s_nop 0
	s_nop 0
	s_nop 0
	s_nop 0
	s_nop 0
	s_nop 0
	s_nop 0
	s_nop 0
	s_nop 0
	s_nop 0
	s_nop 0
	s_nop 0
	s_nop 0
	s_nop 0
	s_nop 0
	s_nop 0
	s_nop 0
	s_nop 0
	s_nop 0
	s_nop 0
	s_nop 0
	s_nop 0
	s_nop 0
	s_nop 0
	s_nop 0
	s_nop 0
	s_nop 0
	s_nop 0
	s_nop 0
	s_nop 0
	s_nop 0
	s_nop 0
	s_nop 0
	s_nop 0
	s_nop 0
	s_nop 0
	s_nop 0
	s_nop 0
	s_nop 0
	s_nop 0
	s_nop 0
	s_nop 0
	s_nop 0
	s_nop 0
	s_nop 0
	s_nop 0
	s_nop 0
	s_nop 0
	s_nop 0
	s_nop 0
	s_nop 0
	s_nop 0
	s_nop 0
	s_nop 0
	s_nop 0
	s_nop 0
	s_nop 0
	s_nop 0
	s_nop 0
	s_nop 0
	s_nop 0
	s_nop 0
	s_nop 0
	s_nop 0
	s_nop 0
	s_nop 0
	s_nop 0
	s_nop 0
	s_nop 0
	s_nop 0
	s_nop 0
	s_nop 0
	s_nop 0
	s_nop 0
	s_nop 0
	s_nop 0
	s_nop 0
	s_nop 0
	s_nop 0
	s_nop 0
	s_nop 0
	s_nop 0
	s_nop 0
	s_nop 0
	s_nop 0
	s_nop 0
	s_nop 0
	s_nop 0
	s_nop 0
	s_nop 0
	s_nop 0
	s_nop 0
	s_nop 0
	s_nop 0
	s_nop 0
	s_nop 0
	s_nop 0
	s_nop 0
	s_nop 0
	s_nop 0
	s_nop 0
	s_nop 0
	s_nop 0
	s_nop 0
	s_nop 0
	s_nop 0
	s_nop 0
	s_nop 0
	s_nop 0
	s_nop 0
	s_nop 0
	s_nop 0
	s_nop 0
	s_nop 0
	s_nop 0
	s_nop 0
	s_nop 0
	s_nop 0
	s_nop 0
	s_nop 0
	s_nop 0
	s_nop 0
	s_nop 0
	s_nop 0
	s_nop 0
	s_nop 0
	s_nop 0
	s_nop 0
	s_nop 0
	s_nop 0
	s_nop 0
	s_nop 0
	s_nop 0
	s_nop 0
	s_nop 0
	s_nop 0
	s_nop 0
	s_nop 0
	s_nop 0
	s_nop 0
	s_nop 0
	s_nop 0
	s_nop 0
	s_nop 0
	s_nop 0
	s_nop 0
	s_nop 0
	s_nop 0
	s_nop 0
	s_nop 0
	s_nop 0
	s_nop 0
	s_nop 0
	s_nop 0
	s_nop 0
	s_nop 0
	s_nop 0
	s_nop 0
	s_nop 0
	s_nop 0
	s_nop 0
	s_nop 0
	s_nop 0
	s_nop 0
	s_nop 0
	s_nop 0
	s_nop 0
	s_nop 0
	s_nop 0
	s_nop 0
	s_nop 0
	s_nop 0
	s_nop 0
	s_nop 0
	s_nop 0
	s_nop 0
	s_nop 0
	s_nop 0
	s_nop 0
	s_nop 0
	s_nop 0
	s_nop 0
	s_nop 0
	s_nop 0
	s_nop 0
	s_nop 0
	s_nop 0
	s_nop 0
	s_nop 0
	s_nop 0
	s_nop 0
	s_nop 0
	s_nop 0
	s_nop 0
	s_nop 0
	s_nop 0
	s_nop 0
	s_nop 0
	s_nop 0
	s_nop 0
	s_nop 0
	s_nop 0
	s_nop 0
	s_nop 0
	s_nop 0
	s_nop 0
	s_nop 0
	s_nop 0
	s_nop 0
	s_nop 0
	s_nop 0
	s_nop 0
	s_nop 0
	s_nop 0
	s_nop 0
	s_nop 0
	s_nop 0
	s_nop 0
	s_nop 0
	s_nop 0
	s_nop 0
	s_nop 0
	s_nop 0
	s_nop 0
	s_nop 0
	s_nop 0
	s_nop 0
	s_nop 0
	s_nop 0
	s_nop 0
	s_nop 0
	s_nop 0
	s_nop 0
	s_nop 0
	s_nop 0
	s_nop 0
	s_nop 0
	s_nop 0
	s_nop 0
	s_nop 0
	s_nop 0
	s_nop 0
	s_nop 0
	s_nop 0
	s_nop 0
	s_nop 0
	s_nop 0
	s_nop 0
	s_nop 0
	s_nop 0
	s_nop 0
	s_nop 0
	s_nop 0
	s_nop 0
	s_nop 0
	s_nop 0
	s_nop 0
	s_nop 0
	s_nop 0
	s_nop 0
	s_nop 0
	s_nop 0
	s_nop 0
	s_nop 0
	s_nop 0
	s_nop 0
	s_nop 0
	s_nop 0
	s_nop 0
	s_nop 0
	s_nop 0
	s_nop 0
	s_nop 0
	s_nop 0
	s_nop 0
	s_nop 0
	s_nop 0
	s_nop 0
	s_nop 0
	s_nop 0
	s_nop 0
	s_nop 0
	s_nop 0
	s_nop 0
	s_nop 0
	s_nop 0
	s_nop 0
	s_nop 0
	s_nop 0
	s_nop 0
	s_nop 0
	s_nop 0
	s_nop 0
	s_nop 0
	s_nop 0
	s_nop 0
	s_nop 0
	s_nop 0
	s_nop 0
	s_nop 0
	s_nop 0
	s_nop 0
	s_nop 0
	s_nop 0
	s_nop 0
	s_nop 0
	s_nop 0
	s_nop 0
	s_nop 0
	s_nop 0
	s_nop 0
	s_nop 0
	s_nop 0
	s_nop 0
	s_nop 0
	s_nop 0
	s_nop 0
	s_nop 0
	s_nop 0
	s_nop 0
	s_nop 0
	s_nop 0
	s_nop 0
	s_nop 0
	s_nop 0
	s_nop 0
	s_nop 0
	s_nop 0
	s_nop 0
	s_nop 0
	s_nop 0
	s_nop 0
	s_nop 0
	s_nop 0
	s_nop 0
	s_nop 0
	s_nop 0
	s_nop 0
	s_nop 0
	s_nop 0
	s_nop 0
	s_nop 0
	s_nop 0
	s_nop 0
	s_nop 0
	s_nop 0
	s_nop 0
	s_nop 0
	s_nop 0
	s_nop 0
	s_nop 0
	s_nop 0
	s_nop 0
	s_nop 0
	s_nop 0
	s_nop 0
	s_nop 0
	s_nop 0
	s_nop 0
	s_nop 0
	s_nop 0
	s_nop 0
	s_nop 0
	s_nop 0
	s_nop 0
	s_nop 0
	s_nop 0
	s_nop 0
	s_nop 0
	s_nop 0
	s_nop 0
	s_nop 0
	s_nop 0
	s_nop 0
	s_nop 0
	s_nop 0
	s_nop 0
	s_nop 0
	s_nop 0
	s_nop 0
	s_nop 0
	s_nop 0
	s_nop 0
	s_nop 0
	s_nop 0
	s_nop 0
	s_nop 0
	s_nop 0
	s_nop 0
	s_nop 0
	s_nop 0
	s_nop 0
	s_nop 0
	s_nop 0
	s_nop 0
	s_nop 0
	s_nop 0
	s_nop 0
	s_nop 0
	s_nop 0
	s_nop 0
	s_nop 0
	s_nop 0
	s_nop 0
	s_nop 0
	s_nop 0
	s_nop 0
	s_nop 0
	s_nop 0
	s_nop 0
	s_nop 0
	s_nop 0
	s_nop 0
	s_nop 0
	s_nop 0
	s_nop 0
	s_nop 0
	s_nop 0
	s_nop 0
	s_nop 0
	s_nop 0
	s_nop 0
	s_nop 0
	s_nop 0
	s_nop 0
	s_nop 0
	s_nop 0
	s_nop 0
	s_nop 0
	s_nop 0
	s_nop 0
	s_nop 0
	s_nop 0
	s_nop 0
	s_nop 0
	s_nop 0
	s_nop 0
	s_nop 0
	s_nop 0
	s_nop 0
	s_nop 0
	s_nop 0
	s_nop 0
	s_nop 0
	s_nop 0
	s_nop 0
	s_nop 0
	s_nop 0
	s_nop 0
	s_nop 0
	s_nop 0
	s_nop 0
	s_nop 0
	s_nop 0
	s_nop 0
	s_nop 0
	s_nop 0
	s_nop 0
	s_nop 0
	s_nop 0
	s_nop 0
	s_nop 0
	s_nop 0
	s_nop 0
	s_nop 0
	s_nop 0
	s_nop 0
	s_nop 0
	s_nop 0
	s_nop 0
	s_nop 0
	s_nop 0
	s_nop 0
	s_nop 0
	s_nop 0
	s_nop 0
	s_nop 0
	s_nop 0
	s_nop 0
	s_nop 0
	s_nop 0
	s_nop 0
	s_nop 0
	s_nop 0
	s_nop 0
	s_nop 0
	s_nop 0
	s_nop 0
	s_nop 0
	s_nop 0
	s_nop 0
	s_nop 0
	s_nop 0
	s_nop 0
	s_nop 0
	s_nop 0
	s_nop 0
	s_nop 0
	s_nop 0
	s_nop 0
	s_nop 0
	s_nop 0
	s_nop 0
	s_nop 0
	s_nop 0
	s_nop 0
	s_nop 0
	s_nop 0
	s_nop 0
	s_nop 0
	s_nop 0
	s_nop 0
	s_nop 0
	s_nop 0
	s_nop 0
	s_nop 0
	s_nop 0
	s_nop 0
	s_nop 0
	s_nop 0
	s_nop 0
	s_nop 0
	s_nop 0
	s_nop 0
	s_nop 0
	s_nop 0
	s_nop 0
	s_nop 0
	s_nop 0
	s_nop 0
	s_nop 0
	s_nop 0
	s_nop 0
	s_nop 0
	s_nop 0
	s_nop 0
	s_nop 0
	s_nop 0
	s_nop 0
	s_nop 0
	s_nop 0
	s_nop 0
	s_nop 0
	s_nop 0
	s_nop 0
	s_nop 0
	s_nop 0
	s_nop 0
	s_nop 0
	s_nop 0
	s_nop 0
	s_nop 0
	s_nop 0
	s_nop 0
	s_nop 0
	s_nop 0
	s_nop 0
	s_nop 0
	s_nop 0
	s_nop 0
	s_nop 0
	s_nop 0
	s_nop 0
	s_nop 0
	s_nop 0
	s_nop 0
	s_nop 0
	s_nop 0
	s_nop 0
	s_nop 0
	s_nop 0
	s_nop 0
	s_nop 0
	s_nop 0
	s_nop 0
	s_nop 0
	s_nop 0
	s_nop 0
	s_nop 0
	s_nop 0
	s_nop 0
; #define LAS __attribute__((address_space(3)))
; DI float bf2f(bf16_t v) { return __uint_as_float(((unsigned)v) << 16); }
; DI bf16_t f2bf(float f) { return (bf16_t)(cvt_pk(f, 0.f) & 0xffffu); }
; DI float logsig16(float z) { return (fminf(z, 0.f) - __logf(1.0f + __expf(-fabsf(z)))) * (1.0f / 16.0f); }
; DI void gla_gate_phase(const Params& P, LAS unsigned char* lds, int lj) {
;     ...
;   for (int item = blockIdx.x; item < 512; item += gridDim.x) {
;     __syncthreads();
;     { const int row = tid >> 3, part = tid & 7; *(LAS f32x4*)(zL + row * 32 + part * 4) = *(const f32x4*)(zbuf + ((size_t)item * 64 + row) * 32 + part * 4); }
;     __syncthreads();
;     float lsb[64]; float totb = 0.f;
; #pragma unroll
;     for (int i = 0; i < 64; ++i) {
;       float z = bb_;
; #pragma unroll
;       for (int j4 = 0; j4 < 4; ++j4) { const f32x4 zz = *(const LAS f32x4*)(zL + i * 32 + 16 + j4 * 4); z += zz[0] * wb[j4 * 4] + zz[1] * wb[j4 * 4 + 1] + zz[2] * wb[j4 * 4 + 2] + zz[3] * wb[j4 * 4 + 3]; }
;       lsb[i] = logsig16(z); totb += lsb[i];
;     }
;     float runf = 0.f, runb = 0.f;
; #pragma unroll
;     for (int ib = 0; ib < 4; ++ib) {
;       bf16_t qraw[16], kraw[16];
; #pragma unroll
;       for (int ii = 0; ii < 16; ++ii) { const bf16_t* pr = proj + ((size_t)item * 64 + ib * 16 + ii) * 3072 + col; qraw[ii] = pr[0]; kraw[ii] = pr[512]; }
;       asm volatile("" ::: "memory");
; #pragma unroll
;       for (int ii = 0; ii < 16; ++ii) {
;         const int i = ib * 16 + ii;
;         float z = bf_;
; #pragma unroll
;         for (int j4 = 0; j4 < 4; ++j4) { const f32x4 zz = *(const LAS f32x4*)(zL + i * 32 + j4 * 4); z += zz[0] * wf[j4 * 4] + zz[1] * wf[j4 * 4 + 1] + zz[2] * wf[j4 * 4 + 2] + zz[3] * wf[j4 * 4 + 3]; }
;         runf += logsig16(z);
;         const float Bi = totb - runb; runb += lsb[i];
;         const size_t tokrow = (size_t)item * 64 + i;
;         bf16_t* pr = proj + tokrow * 3072 + col;
;         const float q = bf2f(qraw[ii]), k = bf2f(kraw[ii]);
;         pr[0] = f2bf(q * __expf(runf)); pr[512] = f2bf(k * __expf(-runf));
;         QB[tokrow * 512 + col] = f2bf(q * __expf(Bi)); KB[tokrow * 512 + col] = f2bf(k * __expf(-Bi));
;       }
;       asm volatile("" ::: "memory");
;     }
;     dect[(size_t)item * 512 + col] = __expf(runf);
;     dect[(size_t)(512 + item) * 512 + col] = __expf(totb);
;   }
	s_nop 0
	s_nop 0
	s_nop 0
	s_nop 0
	s_nop 0
	s_nop 0
	s_nop 0
	s_nop 0
	s_nop 0
	s_nop 0
	s_nop 0
	s_nop 0
	s_nop 0
	s_nop 0
	s_nop 0
	s_nop 0
	s_nop 0
	s_nop 0
	s_nop 0
	s_nop 0
	s_nop 0
	s_nop 0
	s_nop 0
	s_nop 0
	s_nop 0
	s_nop 0
	s_nop 0
	s_nop 0
	s_nop 0
	s_nop 0
	s_nop 0
	s_nop 0
	s_nop 0
	s_nop 0
	s_nop 0
	s_nop 0
	s_nop 0
	s_nop 0
	s_nop 0
	s_nop 0
	s_nop 0
	s_nop 0
	s_nop 0
	s_nop 0
	s_nop 0
	s_nop 0
	s_nop 0
	s_nop 0
	s_nop 0
	s_nop 0
	s_nop 0
	s_nop 0
	s_nop 0
	s_nop 0
	s_nop 0
	s_nop 0
	s_nop 0
	s_nop 0
	s_nop 0
	s_nop 0
	s_nop 0
	s_nop 0
	s_nop 0
	s_nop 0
	s_nop 0
	s_nop 0
	s_nop 0
	s_nop 0
	s_nop 0
	s_nop 0
	s_nop 0
	s_nop 0
	s_nop 0
	s_nop 0
	s_nop 0
	s_nop 0
	s_nop 0
	s_nop 0
	s_nop 0
	s_nop 0
	s_nop 0
	s_nop 0
	s_nop 0
	s_nop 0
	s_nop 0
	s_nop 0
	s_nop 0
	s_nop 0
	s_nop 0
	s_nop 0
	s_nop 0
	s_nop 0
	s_nop 0
	s_nop 0
	s_nop 0
	s_nop 0
	s_nop 0
	s_nop 0
	s_nop 0
	s_nop 0
	s_nop 0
	s_nop 0
	s_nop 0
	s_nop 0
	s_nop 0
	s_nop 0
	s_nop 0
	s_nop 0
	s_nop 0
	s_nop 0
	s_nop 0
	s_nop 0
	s_nop 0
	s_nop 0
	s_nop 0
	s_nop 0
	s_nop 0
	s_nop 0
	s_nop 0
	s_nop 0
	s_nop 0
	s_nop 0
	s_nop 0
	s_nop 0
	s_nop 0
	s_nop 0
	s_nop 0
	s_nop 0
	s_nop 0
	s_nop 0
	s_nop 0
	s_nop 0
	s_nop 0
	s_nop 0
	s_nop 0
	s_nop 0
	s_nop 0
	s_nop 0
	s_nop 0
	s_nop 0
	s_nop 0
	s_nop 0
	s_nop 0
	s_nop 0
	s_nop 0
	s_nop 0
	s_nop 0
	s_nop 0
	s_nop 0
	s_nop 0
	s_nop 0
	s_nop 0
	s_nop 0
	s_nop 0
	s_nop 0
	s_nop 0
	s_nop 0
	s_nop 0
	s_nop 0
	s_nop 0
	s_nop 0
	s_nop 0
	s_nop 0
	s_nop 0
	s_nop 0
	s_nop 0
	s_nop 0
	s_nop 0
	s_nop 0
	s_nop 0
	s_nop 0
	s_nop 0
	s_nop 0
	s_nop 0
	s_nop 0
	s_nop 0
	s_nop 0
	s_nop 0
	s_nop 0
	s_nop 0
	s_nop 0
	s_nop 0
	s_nop 0
	s_nop 0
	s_nop 0
	s_nop 0
	s_nop 0
	s_nop 0
	s_nop 0
	s_nop 0
	s_nop 0
	s_nop 0
	s_nop 0
	s_nop 0
	s_nop 0
	s_nop 0
	s_nop 0
	s_nop 0
	s_nop 0
	s_nop 0
	s_nop 0
	s_nop 0
	s_nop 0
	s_nop 0
	s_nop 0
	s_nop 0
	s_nop 0
	s_nop 0
	s_nop 0
	s_nop 0
	s_nop 0
	s_nop 0
	s_nop 0
	s_nop 0
	s_nop 0
	s_nop 0
	s_nop 0
	s_nop 0
	s_nop 0
	s_nop 0
	s_nop 0
	s_nop 0
	s_nop 0
	s_nop 0
	s_nop 0
	s_nop 0
	s_nop 0
	s_nop 0
	s_nop 0
	s_nop 0
	s_nop 0
	s_nop 0
	s_nop 0
	s_nop 0
	s_nop 0
	s_nop 0
	s_nop 0
	s_nop 0
	s_nop 0
	s_nop 0
	s_nop 0
	s_nop 0
	s_nop 0
	s_nop 0
	s_nop 0
	s_nop 0
	s_nop 0
	s_nop 0
	s_nop 0
	s_nop 0
	s_nop 0
	s_nop 0
	s_nop 0
	s_nop 0
	s_nop 0
	s_nop 0
	s_nop 0
	s_nop 0
	s_nop 0
	s_nop 0
	s_nop 0
	s_nop 0
	s_nop 0
	s_nop 0
	s_nop 0
	s_nop 0
	s_nop 0
	s_nop 0
	s_nop 0
	s_nop 0
	s_nop 0
	s_nop 0
	s_nop 0
	s_nop 0
	s_nop 0
	s_nop 0
	s_nop 0
	s_nop 0
	s_nop 0
	s_nop 0
	s_nop 0
	s_nop 0
	s_nop 0
	s_nop 0
	s_nop 0
	s_nop 0
	s_nop 0
	s_nop 0
	s_nop 0
	s_nop 0
	s_nop 0
	s_nop 0
	s_nop 0
	s_nop 0
	s_nop 0
	s_nop 0
	s_nop 0
	s_nop 0
	s_nop 0
	s_nop 0
	s_nop 0
	s_nop 0
	s_nop 0
	s_nop 0
	s_nop 0
	s_nop 0
	s_nop 0
	s_nop 0
	s_nop 0
	s_nop 0
	s_nop 0
	s_nop 0
	s_nop 0
	s_nop 0
	s_nop 0
	s_nop 0
	s_nop 0
	s_nop 0
	s_nop 0
	s_nop 0
	s_nop 0
	s_nop 0
	s_nop 0
	s_nop 0
	s_nop 0
	s_nop 0
	s_nop 0
	s_nop 0
	s_nop 0
	s_nop 0
	s_nop 0
	s_nop 0
	s_nop 0
	s_nop 0
	s_nop 0
	s_nop 0
	s_nop 0
	s_nop 0
	s_nop 0
	s_nop 0
	s_nop 0
	s_nop 0
	s_nop 0
	s_nop 0
	s_nop 0
	s_nop 0
	s_nop 0
	s_nop 0
	s_nop 0
	s_nop 0
	s_nop 0
	s_nop 0
	s_nop 0
	s_nop 0
	s_nop 0
	s_nop 0
	s_nop 0
	s_nop 0
	s_nop 0
	s_nop 0
	s_nop 0
	s_nop 0
	s_nop 0
	s_nop 0
	s_nop 0
	s_nop 0
	s_nop 0
	s_nop 0
	s_nop 0
	s_nop 0
	s_nop 0
	s_nop 0
	s_nop 0
	s_nop 0
	s_nop 0
	s_nop 0
	s_nop 0
	s_nop 0
	s_nop 0
	s_nop 0
	s_nop 0
	s_nop 0
	s_nop 0
	s_nop 0
	s_nop 0
	s_nop 0
	s_nop 0
	s_nop 0
	s_nop 0
	s_nop 0
	s_nop 0
	s_nop 0
	s_nop 0
	s_nop 0
	s_nop 0
	s_nop 0
	s_nop 0
	s_nop 0
	s_nop 0
	s_nop 0
	s_nop 0
	s_nop 0
	s_nop 0
	s_nop 0
	s_nop 0
	s_nop 0
	s_nop 0
	s_nop 0
	s_nop 0
	s_nop 0
	s_nop 0
	s_nop 0
	s_nop 0
	s_nop 0
	s_nop 0
	s_nop 0
	s_nop 0
	s_nop 0
	s_nop 0
	s_nop 0
	s_nop 0
	s_nop 0
	s_nop 0
	s_nop 0
	s_nop 0
	s_nop 0
	s_nop 0
	s_nop 0
	s_nop 0
	s_nop 0
	s_nop 0
	s_nop 0
	s_nop 0
	s_nop 0
	s_nop 0
	s_nop 0
	s_nop 0
	s_nop 0
	s_nop 0
	s_nop 0
	s_nop 0
	s_nop 0
	s_nop 0
	s_nop 0
	s_nop 0
	s_nop 0
	s_nop 0
	s_nop 0
	s_nop 0
	s_nop 0
	s_nop 0
	s_nop 0
	s_nop 0
	s_nop 0
	s_nop 0
	s_nop 0
	s_nop 0
	s_nop 0
	s_nop 0
	s_nop 0
	s_nop 0
	s_nop 0
	s_nop 0
	s_nop 0
	s_nop 0
	s_nop 0
	s_nop 0
	s_nop 0
	s_nop 0
	s_nop 0
	s_nop 0
	s_nop 0
	s_nop 0
	s_nop 0
	s_nop 0
	s_nop 0
	s_nop 0
	s_nop 0
	s_nop 0
	s_nop 0
	s_nop 0
	s_nop 0
	s_nop 0
	s_nop 0
	s_nop 0
	s_nop 0
	s_nop 0
	s_nop 0
	s_nop 0
	s_nop 0
	s_nop 0
	s_nop 0
	s_nop 0
	s_nop 0
	s_nop 0
	s_nop 0
	s_nop 0
	s_nop 0
	s_nop 0
	s_nop 0
	s_nop 0
	s_nop 0
	s_nop 0
	s_nop 0
	s_nop 0
	s_nop 0
	s_nop 0
	s_nop 0
	s_nop 0
	s_nop 0
	s_nop 0
	s_nop 0
	s_nop 0
	s_nop 0
	s_nop 0
	s_nop 0
	s_nop 0
	s_nop 0
	s_nop 0
	s_nop 0
	s_nop 0
	s_nop 0
	s_nop 0
	s_nop 0
	s_nop 0
	s_nop 0
	s_nop 0
	s_nop 0
	s_nop 0
	s_nop 0
	s_nop 0
	s_nop 0
	s_nop 0
	s_nop 0
	s_nop 0
	s_nop 0
	s_nop 0
	s_nop 0
	s_nop 0
	s_nop 0
	s_nop 0
	s_nop 0
	s_nop 0
	s_nop 0
	s_nop 0
	s_nop 0
	s_nop 0
	s_nop 0
	s_nop 0
	s_nop 0
	s_nop 0
	s_nop 0
	s_nop 0
	s_nop 0
	s_nop 0
	s_nop 0
	s_nop 0
	s_nop 0
	s_nop 0
	s_nop 0
	s_nop 0
	s_nop 0
	s_nop 0
	s_nop 0
	s_nop 0
	s_nop 0
	s_nop 0
	s_nop 0
	s_nop 0
	s_nop 0
	s_nop 0
	s_nop 0
	s_nop 0
	s_nop 0
	s_nop 0
	s_nop 0
	s_nop 0
	s_nop 0
	s_nop 0
	s_nop 0
	s_nop 0
	s_nop 0
	s_nop 0
	s_nop 0
	s_nop 0
	s_nop 0
	s_nop 0
	s_nop 0
	s_nop 0
	s_nop 0
	s_nop 0
	s_nop 0
	s_nop 0
	s_nop 0
	s_nop 0
	s_nop 0
	s_nop 0
	s_nop 0
	s_nop 0
	s_nop 0
	s_nop 0
	s_nop 0
	s_nop 0
	s_nop 0
	s_nop 0
	s_nop 0
	s_nop 0
	s_nop 0
	s_nop 0
	s_nop 0
	s_nop 0
	s_nop 0
	s_nop 0
	s_nop 0
	s_nop 0
	s_nop 0
	s_nop 0
	s_nop 0
	s_nop 0
	s_nop 0
	s_nop 0
	s_nop 0
	s_nop 0
	s_nop 0
	s_nop 0
	s_nop 0
	s_nop 0
; #define LAS __attribute__((address_space(3)))
; DI float bf2f(bf16_t v) { return __uint_as_float(((unsigned)v) << 16); }
; DI bf16_t f2bf(float f) { return (bf16_t)(cvt_pk(f, 0.f) & 0xffffu); }
; DI float logsig16(float z) { return (fminf(z, 0.f) - __logf(1.0f + __expf(-fabsf(z)))) * (1.0f / 16.0f); }
; DI void gla_gate_phase(const Params& P, LAS unsigned char* lds, int lj) {
;     ...
;   for (int item = blockIdx.x; item < 512; item += gridDim.x) {
;     __syncthreads();
;     { const int row = tid >> 3, part = tid & 7; *(LAS f32x4*)(zL + row * 32 + part * 4) = *(const f32x4*)(zbuf + ((size_t)item * 64 + row) * 32 + part * 4); }
;     __syncthreads();
;     float lsb[64]; float totb = 0.f;
; #pragma unroll
;     for (int i = 0; i < 64; ++i) {
;       float z = bb_;
; #pragma unroll
;       for (int j4 = 0; j4 < 4; ++j4) { const f32x4 zz = *(const LAS f32x4*)(zL + i * 32 + 16 + j4 * 4); z += zz[0] * wb[j4 * 4] + zz[1] * wb[j4 * 4 + 1] + zz[2] * wb[j4 * 4 + 2] + zz[3] * wb[j4 * 4 + 3]; }
;       lsb[i] = logsig16(z); totb += lsb[i];
;     }
;     float runf = 0.f, runb = 0.f;
; #pragma unroll
;     for (int ib = 0; ib < 4; ++ib) {
;       bf16_t qraw[16], kraw[16];
; #pragma unroll
;       for (int ii = 0; ii < 16; ++ii) { const bf16_t* pr = proj + ((size_t)item * 64 + ib * 16 + ii) * 3072 + col; qraw[ii] = pr[0]; kraw[ii] = pr[512]; }
;       asm volatile("" ::: "memory");
; #pragma unroll
;       for (int ii = 0; ii < 16; ++ii) {
;         const int i = ib * 16 + ii;
;         float z = bf_;
; #pragma unroll
;         for (int j4 = 0; j4 < 4; ++j4) { const f32x4 zz = *(const LAS f32x4*)(zL + i * 32 + j4 * 4); z += zz[0] * wf[j4 * 4] + zz[1] * wf[j4 * 4 + 1] + zz[2] * wf[j4 * 4 + 2] + zz[3] * wf[j4 * 4 + 3]; }
;         runf += logsig16(z);
;         const float Bi = totb - runb; runb += lsb[i];
;         const size_t tokrow = (size_t)item * 64 + i;
;         bf16_t* pr = proj + tokrow * 3072 + col;
;         const float q = bf2f(qraw[ii]), k = bf2f(kraw[ii]);
;         pr[0] = f2bf(q * __expf(runf)); pr[512] = f2bf(k * __expf(-runf));
;         QB[tokrow * 512 + col] = f2bf(q * __expf(Bi)); KB[tokrow * 512 + col] = f2bf(k * __expf(-Bi));
;       }
;       asm volatile("" ::: "memory");
;     }
;     dect[(size_t)item * 512 + col] = __expf(runf);
;     dect[(size_t)(512 + item) * 512 + col] = __expf(totb);
;   }
	s_nop 0
	s_nop 0
	s_nop 0
	s_nop 0
	s_nop 0
	s_nop 0
	s_nop 0
	s_nop 0
	s_nop 0
	s_nop 0
	s_nop 0
	s_nop 0
	s_nop 0
	s_nop 0
	s_nop 0
	s_nop 0
	s_nop 0
	s_nop 0
	s_nop 0
	s_nop 0
	s_nop 0
	s_nop 0
	s_nop 0
	s_nop 0
	s_nop 0
	s_nop 0
	s_nop 0
	s_nop 0
	s_nop 0
	s_nop 0
	s_nop 0
	s_nop 0
	s_nop 0
	s_nop 0
	s_nop 0
	s_nop 0
	s_nop 0
	s_nop 0
	s_nop 0
	s_nop 0
	s_nop 0
	s_nop 0
	s_nop 0
	s_nop 0
	s_nop 0
	s_nop 0
	s_nop 0
	s_nop 0
	s_nop 0
	s_nop 0
	s_nop 0
	s_nop 0
	s_nop 0
	s_nop 0
	s_nop 0
	s_nop 0
	s_nop 0
	s_nop 0
	s_nop 0
	s_nop 0
	s_nop 0
	s_nop 0
	s_nop 0
	s_nop 0
	s_nop 0
	s_nop 0
	s_nop 0
	s_nop 0
	s_nop 0
	s_nop 0
	s_nop 0
	s_nop 0
	s_nop 0
	s_nop 0
	s_nop 0
	s_nop 0
	s_nop 0
	s_nop 0
	s_nop 0
	s_nop 0
	s_nop 0
	s_nop 0
	s_nop 0
	s_nop 0
	s_nop 0
	s_nop 0
	s_nop 0
	s_nop 0
	s_nop 0
	s_nop 0
	s_nop 0
	s_nop 0
	s_nop 0
	s_nop 0
	s_nop 0
	s_nop 0
	s_nop 0
	s_nop 0
	s_nop 0
	s_nop 0
	s_nop 0
	s_nop 0
	s_nop 0
	s_nop 0
	s_nop 0
	s_nop 0
	s_nop 0
	s_nop 0
	s_nop 0
	s_nop 0
	s_nop 0
	s_nop 0
	s_nop 0
	s_nop 0
	s_nop 0
	s_nop 0
	s_nop 0
	s_nop 0
	s_nop 0
	s_nop 0
	s_nop 0
	s_nop 0
	s_nop 0
	s_nop 0
	s_nop 0
	s_nop 0
	s_nop 0
	s_nop 0
	s_nop 0
	s_nop 0
	s_nop 0
	s_nop 0
	s_nop 0
	s_nop 0
	s_nop 0
	s_nop 0
	s_nop 0
	s_nop 0
	s_nop 0
	s_nop 0
	s_nop 0
	s_nop 0
	s_nop 0
	s_nop 0
	s_nop 0
	s_nop 0
	s_nop 0
	s_nop 0
	s_nop 0
	s_nop 0
	s_nop 0
	s_nop 0
	s_nop 0
	s_nop 0
	s_nop 0
	s_nop 0
	s_nop 0
	s_nop 0
	s_nop 0
	s_nop 0
	s_nop 0
	s_nop 0
	s_nop 0
	s_nop 0
	s_nop 0
	s_nop 0
	s_nop 0
	s_nop 0
	s_nop 0
	s_nop 0
	s_nop 0
	s_nop 0
	s_nop 0
	s_nop 0
	s_nop 0
	s_nop 0
	s_nop 0
	s_nop 0
	s_nop 0
	s_nop 0
	s_nop 0
	s_nop 0
	s_nop 0
	s_nop 0
	s_nop 0
	s_nop 0
	s_nop 0
	s_nop 0
	s_nop 0
	s_nop 0
	s_nop 0
	s_nop 0
	s_nop 0
	s_nop 0
	s_nop 0
	s_nop 0
	s_nop 0
	s_nop 0
	s_nop 0
	s_nop 0
	s_nop 0
	s_nop 0
	s_nop 0
	s_nop 0
	s_nop 0
	s_nop 0
	s_nop 0
	s_nop 0
	s_nop 0
	s_nop 0
	s_nop 0
	s_nop 0
	s_nop 0
	s_nop 0
	s_nop 0
	s_nop 0
	s_nop 0
	s_nop 0
	s_nop 0
	s_nop 0
	s_nop 0
	s_nop 0
	s_nop 0
	s_nop 0
	s_nop 0
	s_nop 0
	s_nop 0
	s_nop 0
	s_nop 0
	s_nop 0
	s_nop 0
	s_nop 0
	s_nop 0
	s_nop 0
	s_nop 0
	s_nop 0
	s_nop 0
	s_nop 0
	s_nop 0
	s_nop 0
	s_nop 0
	s_nop 0
	s_nop 0
	s_nop 0
	s_nop 0
	s_nop 0
	s_nop 0
	s_nop 0
	s_nop 0
	s_nop 0
	s_nop 0
	s_nop 0
	s_nop 0
	s_nop 0
	s_nop 0
	s_nop 0
	s_nop 0
	s_nop 0
	s_nop 0
	s_nop 0
	s_nop 0
	s_nop 0
	s_nop 0
	s_nop 0
	s_nop 0
	s_nop 0
	s_nop 0
	s_nop 0
	s_nop 0
	s_nop 0
	s_nop 0
	s_nop 0
	s_nop 0
	s_nop 0
	s_nop 0
	s_nop 0
	s_nop 0
	s_nop 0
	s_nop 0
	s_nop 0
	s_nop 0
	s_nop 0
	s_nop 0
	s_nop 0
	s_nop 0
	s_nop 0
	s_nop 0
	s_nop 0
	s_nop 0
	s_nop 0
	s_nop 0
	s_nop 0
	s_nop 0
	s_nop 0
	s_nop 0
	s_nop 0
	s_nop 0
	s_nop 0
	s_nop 0
	s_nop 0
	s_nop 0
	s_nop 0
	s_nop 0
	s_nop 0
	s_nop 0
	s_nop 0
	s_nop 0
	s_nop 0
	s_nop 0
	s_nop 0
	s_nop 0
	s_nop 0
	s_nop 0
	s_nop 0
	s_nop 0
	s_nop 0
	s_nop 0
	s_nop 0
	s_nop 0
	s_nop 0
	s_nop 0
	s_nop 0
	s_nop 0
	s_nop 0
	s_nop 0
	s_nop 0
	s_nop 0
	s_nop 0
	s_nop 0
	s_nop 0
	s_nop 0
	s_nop 0
	s_nop 0
	s_nop 0
	s_nop 0
	s_nop 0
	s_nop 0
	s_nop 0
	s_nop 0
	s_nop 0
	s_nop 0
	s_nop 0
	s_nop 0
	s_nop 0
	s_nop 0
	s_nop 0
	s_nop 0
	s_nop 0
	s_nop 0
	s_nop 0
	s_nop 0
	s_nop 0
	s_nop 0
	s_nop 0
	s_nop 0
	s_nop 0
	s_nop 0
	s_nop 0
	s_nop 0
	s_nop 0
	s_nop 0
	s_nop 0
	s_nop 0
	s_nop 0
	s_nop 0
	s_nop 0
	s_nop 0
	s_nop 0
	s_nop 0
	s_nop 0
	s_nop 0
	s_nop 0
	s_nop 0
	s_nop 0
	s_nop 0
	s_nop 0
	s_nop 0
	s_nop 0
	s_nop 0
	s_nop 0
	s_nop 0
	s_nop 0
	s_nop 0
	s_nop 0
	s_nop 0
	s_nop 0
	s_nop 0
	s_nop 0
	s_nop 0
	s_nop 0
	s_nop 0
	s_nop 0
	s_nop 0
	s_nop 0
	s_nop 0
	s_nop 0
	s_nop 0
	s_nop 0
	s_nop 0
	s_nop 0
	s_nop 0
	s_nop 0
	s_nop 0
	s_nop 0
	s_nop 0
	s_nop 0
	s_nop 0
	s_nop 0
	s_nop 0
	s_nop 0
	s_nop 0
	s_nop 0
	s_nop 0
	s_nop 0
	s_nop 0
	s_nop 0
	s_nop 0
	s_nop 0
	s_nop 0
	s_nop 0
	s_nop 0
	s_nop 0
	s_nop 0
	s_nop 0
	s_nop 0
	s_nop 0
	s_nop 0
	s_nop 0
	s_nop 0
	s_nop 0
	s_nop 0
	s_nop 0
	s_nop 0
	s_nop 0
	s_nop 0
	s_nop 0
	s_nop 0
	s_nop 0
	s_nop 0
	s_nop 0
	s_nop 0
	s_nop 0
	s_nop 0
	s_nop 0
	s_nop 0
	s_nop 0
	s_nop 0
	s_nop 0
	s_nop 0
	s_nop 0
	s_nop 0
	s_nop 0
	s_nop 0
	s_nop 0
	s_nop 0
	s_nop 0
	s_nop 0
	s_nop 0
	s_nop 0
	s_nop 0
	s_nop 0
	s_nop 0
	s_nop 0
	s_nop 0
	s_nop 0
	s_nop 0
	s_nop 0
	s_nop 0
	s_nop 0
	s_nop 0
	s_nop 0
	s_nop 0
	s_nop 0
	s_nop 0
	s_nop 0
	s_nop 0
	s_nop 0
	s_nop 0
	s_nop 0
	s_nop 0
	s_nop 0
	s_nop 0
	s_nop 0
	s_nop 0
	s_nop 0
	s_nop 0
	s_nop 0
	s_nop 0
	s_nop 0
	s_nop 0
	s_nop 0
	s_nop 0
	s_nop 0
	s_nop 0
	s_nop 0
	s_nop 0
	s_nop 0
	s_nop 0
	s_nop 0
	s_nop 0
	s_nop 0
	s_nop 0
	s_nop 0
	s_nop 0
	s_nop 0
	s_nop 0
	s_nop 0
	s_nop 0
	s_nop 0
	s_nop 0
	s_nop 0
	s_nop 0
	s_nop 0
	s_nop 0
	s_nop 0
	s_nop 0
	s_nop 0
	s_nop 0
	s_nop 0
	s_nop 0
	s_nop 0
	s_nop 0
	s_nop 0
	s_nop 0
	s_nop 0
	s_nop 0
	s_nop 0
	s_nop 0
	s_nop 0
	s_nop 0
	s_nop 0
	s_nop 0
	s_nop 0
	s_nop 0
	s_nop 0
	s_nop 0
	s_nop 0
	s_nop 0
	s_nop 0
	s_nop 0
	s_nop 0
	s_nop 0
	s_nop 0
	s_nop 0
	s_nop 0
	s_nop 0
	s_nop 0
	s_nop 0
	s_nop 0
	s_nop 0
	s_nop 0
	s_nop 0
	s_nop 0
	s_nop 0
	s_nop 0
	s_nop 0
	s_nop 0
	s_nop 0
	s_nop 0
	s_nop 0
	s_nop 0
	s_nop 0
	s_nop 0
	s_nop 0
	s_nop 0
	s_nop 0
	s_nop 0
	s_nop 0
	s_nop 0
	s_nop 0
	s_nop 0
	s_nop 0
	s_nop 0
	s_nop 0
	s_nop 0
	s_nop 0
	s_nop 0
	s_nop 0
	s_nop 0
	s_nop 0
	s_nop 0
	s_nop 0
	s_nop 0
	s_nop 0
	s_nop 0
	s_nop 0
	s_nop 0
	s_nop 0
	s_nop 0
	s_nop 0
	s_nop 0
	s_nop 0
	s_nop 0
	s_nop 0
	s_nop 0
	s_nop 0
	s_nop 0
	s_nop 0
	s_nop 0
	s_nop 0
	s_nop 0
	s_nop 0
	s_nop 0
	s_nop 0
	s_nop 0
	s_nop 0
	s_nop 0
	s_nop 0
	s_nop 0
	s_nop 0
	s_nop 0
	s_nop 0
	s_nop 0
	s_nop 0
	s_nop 0
	s_nop 0
	s_nop 0
	s_nop 0
	s_nop 0
	s_nop 0
	s_nop 0
	s_nop 0
	s_nop 0
	s_nop 0
	s_nop 0
	s_nop 0
	s_nop 0
; #define LAS __attribute__((address_space(3)))
; DI float bf2f(bf16_t v) { return __uint_as_float(((unsigned)v) << 16); }
; DI bf16_t f2bf(float f) { return (bf16_t)(cvt_pk(f, 0.f) & 0xffffu); }
; DI float logsig16(float z) { return (fminf(z, 0.f) - __logf(1.0f + __expf(-fabsf(z)))) * (1.0f / 16.0f); }
; DI void gla_gate_phase(const Params& P, LAS unsigned char* lds, int lj) {
;     ...
;   for (int item = blockIdx.x; item < 512; item += gridDim.x) {
;     __syncthreads();
;     { const int row = tid >> 3, part = tid & 7; *(LAS f32x4*)(zL + row * 32 + part * 4) = *(const f32x4*)(zbuf + ((size_t)item * 64 + row) * 32 + part * 4); }
;     __syncthreads();
;     float lsb[64]; float totb = 0.f;
; #pragma unroll
;     for (int i = 0; i < 64; ++i) {
;       float z = bb_;
; #pragma unroll
;       for (int j4 = 0; j4 < 4; ++j4) { const f32x4 zz = *(const LAS f32x4*)(zL + i * 32 + 16 + j4 * 4); z += zz[0] * wb[j4 * 4] + zz[1] * wb[j4 * 4 + 1] + zz[2] * wb[j4 * 4 + 2] + zz[3] * wb[j4 * 4 + 3]; }
;       lsb[i] = logsig16(z); totb += lsb[i];
;     }
;     float runf = 0.f, runb = 0.f;
; #pragma unroll
;     for (int ib = 0; ib < 4; ++ib) {
;       bf16_t qraw[16], kraw[16];
; #pragma unroll
;       for (int ii = 0; ii < 16; ++ii) { const bf16_t* pr = proj + ((size_t)item * 64 + ib * 16 + ii) * 3072 + col; qraw[ii] = pr[0]; kraw[ii] = pr[512]; }
;       asm volatile("" ::: "memory");
; #pragma unroll
;       for (int ii = 0; ii < 16; ++ii) {
;         const int i = ib * 16 + ii;
;         float z = bf_;
; #pragma unroll
;         for (int j4 = 0; j4 < 4; ++j4) { const f32x4 zz = *(const LAS f32x4*)(zL + i * 32 + j4 * 4); z += zz[0] * wf[j4 * 4] + zz[1] * wf[j4 * 4 + 1] + zz[2] * wf[j4 * 4 + 2] + zz[3] * wf[j4 * 4 + 3]; }
;         runf += logsig16(z);
;         const float Bi = totb - runb; runb += lsb[i];
;         const size_t tokrow = (size_t)item * 64 + i;
;         bf16_t* pr = proj + tokrow * 3072 + col;
;         const float q = bf2f(qraw[ii]), k = bf2f(kraw[ii]);
;         pr[0] = f2bf(q * __expf(runf)); pr[512] = f2bf(k * __expf(-runf));
;         QB[tokrow * 512 + col] = f2bf(q * __expf(Bi)); KB[tokrow * 512 + col] = f2bf(k * __expf(-Bi));
;       }
;       asm volatile("" ::: "memory");
;     }
;     dect[(size_t)item * 512 + col] = __expf(runf);
;     dect[(size_t)(512 + item) * 512 + col] = __expf(totb);
;   }
	s_nop 0
	s_nop 0
	s_nop 0
	s_nop 0
	s_nop 0
	s_nop 0
	s_nop 0
	s_nop 0
	s_nop 0
	s_nop 0
	s_nop 0
	s_nop 0
	s_nop 0
	s_nop 0
	s_nop 0
	s_nop 0
	s_nop 0
	s_nop 0
	s_nop 0
	s_nop 0
	s_nop 0
	s_nop 0
	s_nop 0
	s_nop 0
	s_nop 0
	s_nop 0
	s_nop 0
	s_nop 0
	s_nop 0
	s_nop 0
	s_nop 0
	s_nop 0
	s_nop 0
	s_nop 0
	s_nop 0
	s_nop 0
	s_nop 0
	s_nop 0
	s_nop 0
	s_nop 0
	s_nop 0
	s_nop 0
	s_nop 0
	s_nop 0
	s_nop 0
	s_nop 0
	s_nop 0
	s_nop 0
	s_nop 0
	s_nop 0
	s_nop 0
	s_nop 0
	s_nop 0
	s_nop 0
	s_nop 0
	s_nop 0
	s_nop 0
	s_nop 0
	s_nop 0
	s_nop 0
	s_nop 0
	s_nop 0
	s_nop 0
	s_nop 0
	s_nop 0
	s_nop 0
	s_nop 0
	s_nop 0
	s_nop 0
	s_nop 0
	s_nop 0
	s_nop 0
	s_nop 0
	s_nop 0
	s_nop 0
	s_nop 0
	s_nop 0
	s_nop 0
	s_nop 0
	s_nop 0
	s_nop 0
	s_nop 0
	s_nop 0
	s_nop 0
	s_nop 0
	s_nop 0
	s_nop 0
	s_nop 0
	s_nop 0
	s_nop 0
	s_nop 0
	s_nop 0
	s_nop 0
	s_nop 0
	s_nop 0
	s_nop 0
	s_nop 0
	s_nop 0
	s_nop 0
	s_nop 0
	s_nop 0
	s_nop 0
	s_nop 0
	s_nop 0
	s_nop 0
	s_nop 0
	s_nop 0
	s_nop 0
	s_nop 0
	s_nop 0
	s_nop 0
	s_nop 0
	s_nop 0
	s_nop 0
	s_nop 0
	s_nop 0
	s_nop 0
	s_nop 0
	s_nop 0
	s_nop 0
	s_nop 0
	s_nop 0
	s_nop 0
	s_nop 0
	s_nop 0
	s_nop 0
	s_nop 0
	s_nop 0
	s_nop 0
	s_nop 0
	s_nop 0
	s_nop 0
	s_nop 0
	s_nop 0
	s_nop 0
	s_nop 0
	s_nop 0
	s_nop 0
	s_nop 0
	s_nop 0
	s_nop 0
	s_nop 0
	s_nop 0
	s_nop 0
	s_nop 0
	s_nop 0
	s_nop 0
	s_nop 0
	s_nop 0
	s_nop 0
	s_nop 0
	s_nop 0
	s_nop 0
	s_nop 0
	s_nop 0
	s_nop 0
	s_nop 0
	s_nop 0
	s_nop 0
	s_nop 0
	s_nop 0
	s_nop 0
	s_nop 0
	s_nop 0
	s_nop 0
	s_nop 0
	s_nop 0
	s_nop 0
	s_nop 0
	s_nop 0
	s_nop 0
	s_nop 0
	s_nop 0
	s_nop 0
	s_nop 0
	s_nop 0
	s_nop 0
	s_nop 0
	s_nop 0
	s_nop 0
	s_nop 0
	s_nop 0
	s_nop 0
	s_nop 0
	s_nop 0
	s_nop 0
	s_nop 0
	s_nop 0
	s_nop 0
	s_nop 0
	s_nop 0
	s_nop 0
	s_nop 0
	s_nop 0
	s_nop 0
	s_nop 0
	s_nop 0
	s_nop 0
	s_nop 0
	s_nop 0
	s_nop 0
	s_nop 0
	s_nop 0
	s_nop 0
	s_nop 0
	s_nop 0
	s_nop 0
	s_nop 0
	s_nop 0
	s_nop 0
	s_nop 0
	s_nop 0
	s_nop 0
	s_nop 0
	s_nop 0
	s_nop 0
	s_nop 0
	s_nop 0
	s_nop 0
	s_nop 0
	s_nop 0
	s_nop 0
	s_nop 0
	s_nop 0
	s_nop 0
	s_nop 0
	s_nop 0
	s_nop 0
	s_nop 0
	s_nop 0
	s_nop 0
	s_nop 0
	s_nop 0
	s_nop 0
	s_nop 0
	s_nop 0
	s_nop 0
	s_nop 0
	s_nop 0
	s_nop 0
	s_nop 0
	s_nop 0
	s_nop 0
	s_nop 0
	s_nop 0
	s_nop 0
	s_nop 0
	s_nop 0
	s_nop 0
	s_nop 0
	s_nop 0
	s_nop 0
	s_nop 0
	s_nop 0
	s_nop 0
	s_nop 0
	s_nop 0
	s_nop 0
	s_nop 0
	s_nop 0
	s_nop 0
	s_nop 0
	s_nop 0
	s_nop 0
	s_nop 0
	s_nop 0
	s_nop 0
	s_nop 0
	s_nop 0
	s_nop 0
	s_nop 0
	s_nop 0
	s_nop 0
	s_nop 0
	s_nop 0
	s_nop 0
	s_nop 0
	s_nop 0
	s_nop 0
	s_nop 0
	s_nop 0
	s_nop 0
	s_nop 0
	s_nop 0
	s_nop 0
	s_nop 0
	s_nop 0
	s_nop 0
	s_nop 0
	s_nop 0
	s_nop 0
	s_nop 0
	s_nop 0
	s_nop 0
	s_nop 0
	s_nop 0
	s_nop 0
	s_nop 0
	s_nop 0
	s_nop 0
	s_nop 0
	s_nop 0
	s_nop 0
	s_nop 0
	s_nop 0
	s_nop 0
	s_nop 0
	s_nop 0
	s_nop 0
	s_nop 0
	s_nop 0
	s_nop 0
	s_nop 0
	s_nop 0
	s_nop 0
	s_nop 0
	s_nop 0
	s_nop 0
	s_nop 0
	s_nop 0
	s_nop 0
	s_nop 0
	s_nop 0
	s_nop 0
	s_nop 0
	s_nop 0
	s_nop 0
	s_nop 0
	s_nop 0
	s_nop 0
	s_nop 0
	s_nop 0
	s_nop 0
	s_nop 0
	s_nop 0
	s_nop 0
	s_nop 0
	s_nop 0
	s_nop 0
	s_nop 0
	s_nop 0
	s_nop 0
	s_nop 0
	s_nop 0
	s_nop 0
	s_nop 0
	s_nop 0
	s_nop 0
	s_nop 0
	s_nop 0
	s_nop 0
	s_nop 0
	s_nop 0
	s_nop 0
	s_nop 0
	s_nop 0
	s_nop 0
	s_nop 0
	s_nop 0
	s_nop 0
	s_nop 0
	s_nop 0
	s_nop 0
	s_nop 0
	s_nop 0
	s_nop 0
	s_nop 0
	s_nop 0
	s_nop 0
	s_nop 0
	s_nop 0
	s_nop 0
	s_nop 0
	s_nop 0
	s_nop 0
	s_nop 0
	s_nop 0
	s_nop 0
	s_nop 0
	s_nop 0
	s_nop 0
	s_nop 0
	s_nop 0
	s_nop 0
	s_nop 0
	s_nop 0
	s_nop 0
	s_nop 0
	s_nop 0
	s_nop 0
	s_nop 0
	s_nop 0
	s_nop 0
	s_nop 0
	s_nop 0
	s_nop 0
	s_nop 0
	s_nop 0
	s_nop 0
	s_nop 0
	s_nop 0
	s_nop 0
	s_nop 0
	s_nop 0
	s_nop 0
	s_nop 0
	s_nop 0
	s_nop 0
	s_nop 0
	s_nop 0
	s_nop 0
	s_nop 0
	s_nop 0
	s_nop 0
	s_nop 0
	s_nop 0
	s_nop 0
	s_nop 0
	s_nop 0
	s_nop 0
	s_nop 0
	s_nop 0
	s_nop 0
	s_nop 0
	s_nop 0
	s_nop 0
	s_nop 0
	s_nop 0
	s_nop 0
	s_nop 0
	s_nop 0
	s_nop 0
	s_nop 0
	s_nop 0
	s_nop 0
	s_nop 0
	s_nop 0
	s_nop 0
	s_nop 0
	s_nop 0
	s_nop 0
	s_nop 0
	s_nop 0
	s_nop 0
	s_nop 0
	s_nop 0
	s_nop 0
	s_nop 0
	s_nop 0
	s_nop 0
	s_nop 0
	s_nop 0
	s_nop 0
	s_nop 0
	s_nop 0
	s_nop 0
	s_nop 0
	s_nop 0
	s_nop 0
	s_nop 0
	s_nop 0
	s_nop 0
	s_nop 0
	s_nop 0
	s_nop 0
	s_nop 0
	s_nop 0
	s_nop 0
	s_nop 0
	s_nop 0
	s_nop 0
	s_nop 0
	s_nop 0
	s_nop 0
	s_nop 0
	s_nop 0
	s_nop 0
	s_nop 0
	s_nop 0
	s_nop 0
	s_nop 0
	s_nop 0
	s_nop 0
	s_nop 0
	s_nop 0
	s_nop 0
	s_nop 0
	s_nop 0
	s_nop 0
	s_nop 0
	s_nop 0
	s_nop 0
	s_nop 0
	s_nop 0
	s_nop 0
	s_nop 0
	s_nop 0
	s_nop 0
	s_nop 0
	s_nop 0
	s_nop 0
	s_nop 0
	s_nop 0
	s_nop 0
	s_nop 0
	s_nop 0
	s_nop 0
	s_nop 0
	s_nop 0
	s_nop 0
	s_nop 0
	s_nop 0
	s_nop 0
	s_nop 0
	s_nop 0
	s_nop 0
	s_nop 0
	s_nop 0
	s_nop 0
	s_nop 0
	s_nop 0
	s_nop 0
	s_nop 0
	s_nop 0
	s_nop 0
	s_nop 0
	s_nop 0
	s_nop 0
	s_nop 0
	s_nop 0
	s_nop 0
	s_nop 0
	s_nop 0
	s_nop 0
	s_nop 0
	s_nop 0
	s_nop 0
	s_nop 0
	s_nop 0
	s_nop 0
	s_nop 0
	s_nop 0
	s_nop 0
	s_nop 0
	s_nop 0
	s_nop 0
	s_nop 0
	s_nop 0
	s_nop 0
	s_nop 0
	s_nop 0
	s_nop 0
	s_nop 0
	s_nop 0
	s_nop 0
	s_nop 0
	s_nop 0
	s_nop 0
	s_nop 0
	s_nop 0
	s_nop 0
	s_nop 0
	s_nop 0
	s_nop 0
	s_nop 0
	s_nop 0
	s_nop 0
	s_nop 0
	s_nop 0
	s_nop 0
	s_nop 0
	s_nop 0
	s_nop 0
	s_nop 0
	s_nop 0
	s_nop 0
	s_nop 0
	s_nop 0
	s_nop 0
	s_nop 0
	s_nop 0
	s_nop 0
	s_nop 0
	s_nop 0
	s_nop 0
	s_nop 0
	s_nop 0
	s_nop 0
	s_nop 0
	s_nop 0
	s_nop 0
	s_nop 0
	s_nop 0
	s_nop 0
	s_nop 0
	s_nop 0
	s_nop 0
	s_nop 0
	s_nop 0
	s_nop 0
	s_nop 0
	s_nop 0
	s_nop 0
	s_nop 0
	s_nop 0
	s_nop 0
	s_nop 0
	s_nop 0
	s_nop 0
	s_nop 0
	s_nop 0
	s_nop 0
	s_nop 0
	s_nop 0
	s_nop 0
	s_nop 0
	s_nop 0
	s_nop 0
	s_nop 0
	s_nop 0
	s_nop 0
	s_nop 0
	s_nop 0
	s_nop 0
	s_nop 0
	s_nop 0
	s_nop 0
; #define LAS __attribute__((address_space(3)))
; DI float bf2f(bf16_t v) { return __uint_as_float(((unsigned)v) << 16); }
; DI bf16_t f2bf(float f) { return (bf16_t)(cvt_pk(f, 0.f) & 0xffffu); }
; DI float logsig16(float z) { return (fminf(z, 0.f) - __logf(1.0f + __expf(-fabsf(z)))) * (1.0f / 16.0f); }
; DI void gla_gate_phase(const Params& P, LAS unsigned char* lds, int lj) {
;     ...
;   for (int item = blockIdx.x; item < 512; item += gridDim.x) {
;     __syncthreads();
;     { const int row = tid >> 3, part = tid & 7; *(LAS f32x4*)(zL + row * 32 + part * 4) = *(const f32x4*)(zbuf + ((size_t)item * 64 + row) * 32 + part * 4); }
;     __syncthreads();
;     float lsb[64]; float totb = 0.f;
; #pragma unroll
;     for (int i = 0; i < 64; ++i) {
;       float z = bb_;
; #pragma unroll
;       for (int j4 = 0; j4 < 4; ++j4) { const f32x4 zz = *(const LAS f32x4*)(zL + i * 32 + 16 + j4 * 4); z += zz[0] * wb[j4 * 4] + zz[1] * wb[j4 * 4 + 1] + zz[2] * wb[j4 * 4 + 2] + zz[3] * wb[j4 * 4 + 3]; }
;       lsb[i] = logsig16(z); totb += lsb[i];
;     }
;     float runf = 0.f, runb = 0.f;
; #pragma unroll
;     for (int ib = 0; ib < 4; ++ib) {
;       bf16_t qraw[16], kraw[16];
; #pragma unroll
;       for (int ii = 0; ii < 16; ++ii) { const bf16_t* pr = proj + ((size_t)item * 64 + ib * 16 + ii) * 3072 + col; qraw[ii] = pr[0]; kraw[ii] = pr[512]; }
;       asm volatile("" ::: "memory");
; #pragma unroll
;       for (int ii = 0; ii < 16; ++ii) {
;         const int i = ib * 16 + ii;
;         float z = bf_;
; #pragma unroll
;         for (int j4 = 0; j4 < 4; ++j4) { const f32x4 zz = *(const LAS f32x4*)(zL + i * 32 + j4 * 4); z += zz[0] * wf[j4 * 4] + zz[1] * wf[j4 * 4 + 1] + zz[2] * wf[j4 * 4 + 2] + zz[3] * wf[j4 * 4 + 3]; }
;         runf += logsig16(z);
;         const float Bi = totb - runb; runb += lsb[i];
;         const size_t tokrow = (size_t)item * 64 + i;
;         bf16_t* pr = proj + tokrow * 3072 + col;
;         const float q = bf2f(qraw[ii]), k = bf2f(kraw[ii]);
;         pr[0] = f2bf(q * __expf(runf)); pr[512] = f2bf(k * __expf(-runf));
;         QB[tokrow * 512 + col] = f2bf(q * __expf(Bi)); KB[tokrow * 512 + col] = f2bf(k * __expf(-Bi));
;       }
;       asm volatile("" ::: "memory");
;     }
;     dect[(size_t)item * 512 + col] = __expf(runf);
;     dect[(size_t)(512 + item) * 512 + col] = __expf(totb);
;   }
	s_nop 0
	s_nop 0
	s_nop 0
	s_nop 0
	s_nop 0
	s_nop 0
	s_nop 0
	s_nop 0
	s_nop 0
	s_nop 0
	s_nop 0
	s_nop 0
	s_nop 0
	s_nop 0
	s_nop 0
	s_nop 0
	s_nop 0
	s_nop 0
	s_nop 0
	s_nop 0
	s_nop 0
	s_nop 0
	s_nop 0
	s_nop 0
	s_nop 0
	s_nop 0
	s_nop 0
	s_nop 0
	s_nop 0
	s_nop 0
	s_nop 0
	s_nop 0
	s_nop 0
	s_nop 0
	s_nop 0
	s_nop 0
	s_nop 0
	s_nop 0
	s_nop 0
	s_nop 0
	s_nop 0
	s_nop 0
	s_nop 0
	s_nop 0
	s_nop 0
	s_nop 0
	s_nop 0
	s_nop 0
	s_nop 0
	s_nop 0
	s_nop 0
	s_nop 0
	s_nop 0
	s_nop 0
	s_nop 0
	s_nop 0
	s_nop 0
	s_nop 0
	s_nop 0
	s_nop 0
	s_nop 0
	s_nop 0
	s_nop 0
	s_nop 0
	s_nop 0
	s_nop 0
	s_nop 0
	s_nop 0
	s_nop 0
	s_nop 0
	s_nop 0
	s_nop 0
	s_nop 0
	s_nop 0
	s_nop 0
	s_nop 0
	s_nop 0
	s_nop 0
	s_nop 0
	s_nop 0
	s_nop 0
	s_nop 0
	s_nop 0
	s_nop 0
	s_nop 0
	s_nop 0
	s_nop 0
	s_nop 0
	s_nop 0
	s_nop 0
	s_nop 0
	s_nop 0
	s_nop 0
	s_nop 0
	s_nop 0
	s_nop 0
	s_nop 0
	s_nop 0
	s_nop 0
	s_nop 0
	s_nop 0
	s_nop 0
	s_nop 0
	s_nop 0
	s_nop 0
	s_nop 0
	s_nop 0
	s_nop 0
	s_nop 0
	s_nop 0
	s_nop 0
	s_nop 0
	s_nop 0
	s_nop 0
	s_nop 0
	s_nop 0
	s_nop 0
	s_nop 0
	s_nop 0
	s_nop 0
	s_nop 0
	s_nop 0
	s_nop 0
	s_nop 0
	s_nop 0
	s_nop 0
	s_nop 0
	s_nop 0
	s_nop 0
	s_nop 0
	s_nop 0
	s_nop 0
	s_nop 0
	s_nop 0
	s_nop 0
	s_nop 0
	s_nop 0
	s_nop 0
	s_nop 0
	s_nop 0
	s_nop 0
	s_nop 0
	s_nop 0
	s_nop 0
	s_nop 0
	s_nop 0
	s_nop 0
	s_nop 0
	s_nop 0
	s_nop 0
	s_nop 0
	s_nop 0
	s_nop 0
	s_nop 0
	s_nop 0
	s_nop 0
	s_nop 0
	s_nop 0
	s_nop 0
	s_nop 0
	s_nop 0
	s_nop 0
	s_nop 0
	s_nop 0
	s_nop 0
	s_nop 0
	s_nop 0
	s_nop 0
	s_nop 0
	s_nop 0
	s_nop 0
	s_nop 0
	s_nop 0
	s_nop 0
	s_nop 0
	s_nop 0
	s_nop 0
	s_nop 0
	s_nop 0
	s_nop 0
	s_nop 0
	s_nop 0
	s_nop 0
	s_nop 0
	s_nop 0
	s_nop 0
	s_nop 0
	s_nop 0
	s_nop 0
	s_nop 0
	s_nop 0
	s_nop 0
	s_nop 0
	s_nop 0
	s_nop 0
	s_nop 0
	s_nop 0
	s_nop 0
	s_nop 0
	s_nop 0
	s_nop 0
	s_nop 0
	s_nop 0
	s_nop 0
	s_nop 0
	s_nop 0
	s_nop 0
	s_nop 0
	s_nop 0
	s_nop 0
	s_nop 0
	s_nop 0
	s_nop 0
	s_nop 0
	s_nop 0
	s_nop 0
	s_nop 0
	s_nop 0
	s_nop 0
	s_nop 0
	s_nop 0
	s_nop 0
	s_nop 0
	s_nop 0
	s_nop 0
	s_nop 0
	s_nop 0
	s_nop 0
	s_nop 0
	s_nop 0
	s_nop 0
	s_nop 0
	s_nop 0
	s_nop 0
	s_nop 0
	s_nop 0
	s_nop 0
	s_nop 0
	s_nop 0
	s_nop 0
	s_nop 0
	s_nop 0
	s_nop 0
	s_nop 0
	s_nop 0
	s_nop 0
	s_nop 0
	s_nop 0
	s_nop 0
	s_nop 0
	s_nop 0
	s_nop 0
	s_nop 0
	s_nop 0
	s_nop 0
	s_nop 0
	s_nop 0
	s_nop 0
	s_nop 0
	s_nop 0
	s_nop 0
	s_nop 0
	s_nop 0
	s_nop 0
	s_nop 0
	s_nop 0
	s_nop 0
	s_nop 0
	s_nop 0
	s_nop 0
	s_nop 0
	s_nop 0
	s_nop 0
	s_nop 0
	s_nop 0
	s_nop 0
	s_nop 0
	s_nop 0
	s_nop 0
	s_nop 0
	s_nop 0
	s_nop 0
	s_nop 0
	s_nop 0
	s_nop 0
	s_nop 0
	s_nop 0
	s_nop 0
	s_nop 0
	s_nop 0
	s_nop 0
	s_nop 0
	s_nop 0
	s_nop 0
	s_nop 0
	s_nop 0
	s_nop 0
	s_nop 0
	s_nop 0
	s_nop 0
	s_nop 0
	s_nop 0
	s_nop 0
	s_nop 0
	s_nop 0
	s_nop 0
	s_nop 0
	s_nop 0
	s_nop 0
	s_nop 0
	s_nop 0
	s_nop 0
	s_nop 0
	s_nop 0
	s_nop 0
	s_nop 0
	s_nop 0
	s_nop 0
	s_nop 0
	s_nop 0
	s_nop 0
	s_nop 0
	s_nop 0
	s_nop 0
	s_nop 0
	s_nop 0
	s_nop 0
	s_nop 0
	s_nop 0
	s_nop 0
	s_nop 0
	s_nop 0
	s_nop 0
	s_nop 0
	s_nop 0
	s_nop 0
	s_nop 0
	s_nop 0
	s_nop 0
	s_nop 0
	s_nop 0
	s_nop 0
	s_nop 0
	s_nop 0
	s_nop 0
	s_nop 0
	s_nop 0
	s_nop 0
	s_nop 0
	s_nop 0
	s_nop 0
	s_nop 0
	s_nop 0
	s_nop 0
	s_nop 0
	s_nop 0
	s_nop 0
	s_nop 0
	s_nop 0
	s_nop 0
	s_nop 0
	s_nop 0
	s_nop 0
	s_nop 0
	s_nop 0
	s_nop 0
	s_nop 0
	s_nop 0
	s_nop 0
	s_nop 0
	s_nop 0
	s_nop 0
	s_nop 0
	s_nop 0
	s_nop 0
	s_nop 0
	s_nop 0
	s_nop 0
	s_nop 0
	s_nop 0
	s_nop 0
	s_nop 0
	s_nop 0
	s_nop 0
	s_nop 0
	s_nop 0
	s_nop 0
	s_nop 0
	s_nop 0
	s_nop 0
	s_nop 0
	s_nop 0
	s_nop 0
	s_nop 0
	s_nop 0
	s_nop 0
	s_nop 0
	s_nop 0
	s_nop 0
	s_nop 0
	s_nop 0
	s_nop 0
	s_nop 0
	s_nop 0
	s_nop 0
	s_nop 0
	s_nop 0
	s_nop 0
	s_nop 0
	s_nop 0
	s_nop 0
	s_nop 0
	s_nop 0
	s_nop 0
	s_nop 0
	s_nop 0
	s_nop 0
	s_nop 0
	s_nop 0
	s_nop 0
	s_nop 0
	s_nop 0
	s_nop 0
	s_nop 0
	s_nop 0
	s_nop 0
	s_nop 0
	s_nop 0
	s_nop 0
	s_nop 0
	s_nop 0
	s_nop 0
	s_nop 0
	s_nop 0
	s_nop 0
	s_nop 0
	s_nop 0
	s_nop 0
	s_nop 0
	s_nop 0
	s_nop 0
	s_nop 0
	s_nop 0
	s_nop 0
	s_nop 0
	s_nop 0
	s_nop 0
	s_nop 0
	s_nop 0
	s_nop 0
	s_nop 0
	s_nop 0
	s_nop 0
	s_nop 0
	s_nop 0
	s_nop 0
	s_nop 0
	s_nop 0
	s_nop 0
	s_nop 0
	s_nop 0
	s_nop 0
	s_nop 0
	s_nop 0
	s_nop 0
	s_nop 0
	s_nop 0
	s_nop 0
	s_nop 0
	s_nop 0
	s_nop 0
	s_nop 0
	s_nop 0
	s_nop 0
	s_nop 0
	s_nop 0
	s_nop 0
	s_nop 0
	s_nop 0
	s_nop 0
	s_nop 0
	s_nop 0
	s_nop 0
	s_nop 0
	s_nop 0
	s_nop 0
	s_nop 0
	s_nop 0
	s_nop 0
	s_nop 0
	s_nop 0
	s_nop 0
	s_nop 0
	s_nop 0
	s_nop 0
	s_nop 0
	s_nop 0
	s_nop 0
	s_nop 0
	s_nop 0
	s_nop 0
	s_nop 0
	s_nop 0
	s_nop 0
	s_nop 0
	s_nop 0
	s_nop 0
	s_nop 0
	s_nop 0
	s_nop 0
	s_nop 0
	s_nop 0
	s_nop 0
	s_nop 0
	s_nop 0
	s_nop 0
	s_nop 0
	s_nop 0
	s_nop 0
	s_nop 0
	s_nop 0
	s_nop 0
	s_nop 0
	s_nop 0
	s_nop 0
	s_nop 0
	s_nop 0
	s_nop 0
	s_nop 0
	s_nop 0
	s_nop 0
	s_nop 0
	s_nop 0
	s_nop 0
	s_nop 0
	s_nop 0
	s_nop 0
	s_nop 0
	s_nop 0
	s_nop 0
	s_nop 0
	s_nop 0
	s_nop 0
	s_nop 0
	s_nop 0
	s_nop 0
	s_nop 0
	s_nop 0
	s_nop 0
	s_nop 0
	s_nop 0
	s_nop 0
	s_nop 0
	s_nop 0
	s_nop 0
	s_nop 0
	s_nop 0
	s_nop 0
	s_nop 0
	s_nop 0
	s_nop 0
	s_nop 0
	s_nop 0
	s_nop 0
	s_nop 0
	s_nop 0
	s_nop 0
	s_nop 0
	s_nop 0
	s_nop 0
	s_nop 0
	s_nop 0
	s_nop 0
	s_nop 0
	s_nop 0
	s_nop 0
	s_nop 0
	s_nop 0
	s_nop 0
	s_nop 0
	s_nop 0
	s_nop 0
	s_nop 0
	s_nop 0
	s_nop 0
	s_nop 0
	s_nop 0
	s_nop 0
	s_nop 0
	s_nop 0
	s_nop 0
	s_nop 0
	s_nop 0
	s_nop 0
	s_nop 0
	s_nop 0
	s_nop 0
	s_nop 0
	s_nop 0
	s_nop 0
	s_nop 0
	s_nop 0
	s_nop 0
	s_nop 0
	s_nop 0
	s_nop 0
; #define LAS __attribute__((address_space(3)))
; DI float bf2f(bf16_t v) { return __uint_as_float(((unsigned)v) << 16); }
; DI bf16_t f2bf(float f) { return (bf16_t)(cvt_pk(f, 0.f) & 0xffffu); }
; DI float logsig16(float z) { return (fminf(z, 0.f) - __logf(1.0f + __expf(-fabsf(z)))) * (1.0f / 16.0f); }
; DI void gla_gate_phase(const Params& P, LAS unsigned char* lds, int lj) {
;     ...
;   for (int item = blockIdx.x; item < 512; item += gridDim.x) {
;     __syncthreads();
;     { const int row = tid >> 3, part = tid & 7; *(LAS f32x4*)(zL + row * 32 + part * 4) = *(const f32x4*)(zbuf + ((size_t)item * 64 + row) * 32 + part * 4); }
;     __syncthreads();
;     float lsb[64]; float totb = 0.f;
; #pragma unroll
;     for (int i = 0; i < 64; ++i) {
;       float z = bb_;
; #pragma unroll
;       for (int j4 = 0; j4 < 4; ++j4) { const f32x4 zz = *(const LAS f32x4*)(zL + i * 32 + 16 + j4 * 4); z += zz[0] * wb[j4 * 4] + zz[1] * wb[j4 * 4 + 1] + zz[2] * wb[j4 * 4 + 2] + zz[3] * wb[j4 * 4 + 3]; }
;       lsb[i] = logsig16(z); totb += lsb[i];
;     }
;     float runf = 0.f, runb = 0.f;
; #pragma unroll
;     for (int ib = 0; ib < 4; ++ib) {
;       bf16_t qraw[16], kraw[16];
; #pragma unroll
;       for (int ii = 0; ii < 16; ++ii) { const bf16_t* pr = proj + ((size_t)item * 64 + ib * 16 + ii) * 3072 + col; qraw[ii] = pr[0]; kraw[ii] = pr[512]; }
;       asm volatile("" ::: "memory");
; #pragma unroll
;       for (int ii = 0; ii < 16; ++ii) {
;         const int i = ib * 16 + ii;
;         float z = bf_;
; #pragma unroll
;         for (int j4 = 0; j4 < 4; ++j4) { const f32x4 zz = *(const LAS f32x4*)(zL + i * 32 + j4 * 4); z += zz[0] * wf[j4 * 4] + zz[1] * wf[j4 * 4 + 1] + zz[2] * wf[j4 * 4 + 2] + zz[3] * wf[j4 * 4 + 3]; }
;         runf += logsig16(z);
;         const float Bi = totb - runb; runb += lsb[i];
;         const size_t tokrow = (size_t)item * 64 + i;
;         bf16_t* pr = proj + tokrow * 3072 + col;
;         const float q = bf2f(qraw[ii]), k = bf2f(kraw[ii]);
;         pr[0] = f2bf(q * __expf(runf)); pr[512] = f2bf(k * __expf(-runf));
;         QB[tokrow * 512 + col] = f2bf(q * __expf(Bi)); KB[tokrow * 512 + col] = f2bf(k * __expf(-Bi));
;       }
;       asm volatile("" ::: "memory");
;     }
;     dect[(size_t)item * 512 + col] = __expf(runf);
;     dect[(size_t)(512 + item) * 512 + col] = __expf(totb);
;   }
	s_nop 0
	s_nop 0
	s_nop 0
	s_nop 0
	s_nop 0
	s_nop 0
	s_nop 0
	s_nop 0
	s_nop 0
	s_nop 0
	s_nop 0
	s_nop 0
	s_nop 0
	s_nop 0
	s_nop 0
	s_nop 0
	s_nop 0
	s_nop 0
	s_nop 0
	s_nop 0
	s_nop 0
	s_nop 0
	s_nop 0
	s_nop 0
	s_nop 0
	s_nop 0
	s_nop 0
	s_nop 0
	s_nop 0
	s_nop 0
	s_nop 0
	s_nop 0
	s_nop 0
	s_nop 0
	s_nop 0
	s_nop 0
	s_nop 0
	s_nop 0
	s_nop 0
	s_nop 0
	s_nop 0
	s_nop 0
	s_nop 0
	s_nop 0
	s_nop 0
	s_nop 0
	s_nop 0
	s_nop 0
	s_nop 0
	s_nop 0
	s_nop 0
	s_nop 0
	s_nop 0
	s_nop 0
	s_nop 0
	s_nop 0
	s_nop 0
	s_nop 0
	s_nop 0
	s_nop 0
	s_nop 0
	s_nop 0
	s_nop 0
	s_nop 0
	s_nop 0
	s_nop 0
	s_nop 0
	s_nop 0
	s_nop 0
	s_nop 0
	s_nop 0
	s_nop 0
	s_nop 0
	s_nop 0
	s_nop 0
	s_nop 0
	s_nop 0
	s_nop 0
	s_nop 0
	s_nop 0
	s_nop 0
	s_nop 0
	s_nop 0
	s_nop 0
	s_nop 0
	s_nop 0
	s_nop 0
	s_nop 0
	s_nop 0
	s_nop 0
	s_nop 0
	s_nop 0
	s_nop 0
	s_nop 0
	s_nop 0
	s_nop 0
	s_nop 0
	s_nop 0
	s_nop 0
	s_nop 0
	s_nop 0
	s_nop 0
	s_nop 0
	s_nop 0
	s_nop 0
	s_nop 0
	s_nop 0
	s_nop 0
	s_nop 0
	s_nop 0
	s_nop 0
	s_nop 0
	s_nop 0
	s_nop 0
	s_nop 0
	s_nop 0
	s_nop 0
	s_nop 0
	s_nop 0
	s_nop 0
	s_nop 0
	s_nop 0
	s_nop 0
	s_nop 0
	s_nop 0
	s_nop 0
	s_nop 0
	s_nop 0
	s_nop 0
	s_nop 0
	s_nop 0
	s_nop 0
	s_nop 0
	s_nop 0
	s_nop 0
	s_nop 0
	s_nop 0
	s_nop 0
	s_nop 0
	s_nop 0
	s_nop 0
	s_nop 0
	s_nop 0
	s_nop 0
	s_nop 0
	s_nop 0
	s_nop 0
	s_nop 0
	s_nop 0
	s_nop 0
	s_nop 0
	s_nop 0
	s_nop 0
	s_nop 0
	s_nop 0
	s_nop 0
	s_nop 0
	s_nop 0
	s_nop 0
	s_nop 0
	s_nop 0
	s_nop 0
	s_nop 0
	s_nop 0
	s_nop 0
	s_nop 0
	s_nop 0
	s_nop 0
	s_nop 0
	s_nop 0
	s_nop 0
	s_nop 0
	s_nop 0
	s_nop 0
	s_nop 0
	s_nop 0
	s_nop 0
	s_nop 0
	s_nop 0
	s_nop 0
	s_nop 0
	s_nop 0
	s_nop 0
	s_nop 0
	s_nop 0
	s_nop 0
	s_nop 0
	s_nop 0
	s_nop 0
	s_nop 0
	s_nop 0
	s_nop 0
	s_nop 0
	s_nop 0
	s_nop 0
	s_nop 0
	s_nop 0
	s_nop 0
	s_nop 0
	s_nop 0
	s_nop 0
	s_nop 0
	s_nop 0
	s_nop 0
	s_nop 0
	s_nop 0
	s_nop 0
	s_nop 0
	s_nop 0
	s_nop 0
	s_nop 0
	s_nop 0
	s_nop 0
	s_nop 0
	s_nop 0
	s_nop 0
	s_nop 0
	s_nop 0
	s_nop 0
	s_nop 0
	s_nop 0
	s_nop 0
	s_nop 0
	s_nop 0
	s_nop 0
	s_nop 0
	s_nop 0
	s_nop 0
	s_nop 0
	s_nop 0
	s_nop 0
	s_nop 0
	s_nop 0
	s_nop 0
	s_nop 0
	s_nop 0
	s_nop 0
	s_nop 0
	s_nop 0
	s_nop 0
	s_nop 0
	s_nop 0
	s_nop 0
	s_nop 0
	s_nop 0
	s_nop 0
	s_nop 0
	s_nop 0
	s_nop 0
	s_nop 0
	s_nop 0
	s_nop 0
	s_nop 0
	s_nop 0
	s_nop 0
	s_nop 0
	s_nop 0
	s_nop 0
	s_nop 0
	s_nop 0
	s_nop 0
	s_nop 0
	s_nop 0
	s_nop 0
	s_nop 0
	s_nop 0
	s_nop 0
	s_nop 0
	s_nop 0
	s_nop 0
	s_nop 0
	s_nop 0
	s_nop 0
	s_nop 0
	s_nop 0
	s_nop 0
	s_nop 0
	s_nop 0
	s_nop 0
	s_nop 0
	s_nop 0
	s_nop 0
	s_nop 0
	s_nop 0
	s_nop 0
	s_nop 0
	s_nop 0
	s_nop 0
	s_nop 0
	s_nop 0
	s_nop 0
	s_nop 0
	s_nop 0
	s_nop 0
	s_nop 0
	s_nop 0
	s_nop 0
	s_nop 0
	s_nop 0
	s_nop 0
	s_nop 0
	s_nop 0
	s_nop 0
	s_nop 0
	s_nop 0
	s_nop 0
	s_nop 0
	s_nop 0
	s_nop 0
	s_nop 0
	s_nop 0
	s_nop 0
	s_nop 0
	s_nop 0
	s_nop 0
	s_nop 0
	s_nop 0
	s_nop 0
	s_nop 0
	s_nop 0
	s_nop 0
	s_nop 0
	s_nop 0
	s_nop 0
	s_nop 0
	s_nop 0
	s_nop 0
	s_nop 0
	s_nop 0
	s_nop 0
	s_nop 0
	s_nop 0
	s_nop 0
	s_nop 0
	s_nop 0
	s_nop 0
	s_nop 0
	s_nop 0
	s_nop 0
	s_nop 0
	s_nop 0
	s_nop 0
	s_nop 0
	s_nop 0
	s_nop 0
	s_nop 0
	s_nop 0
	s_nop 0
	s_nop 0
	s_nop 0
	s_nop 0
	s_nop 0
	s_nop 0
	s_nop 0
	s_nop 0
	s_nop 0
	s_nop 0
	s_nop 0
	s_nop 0
	s_nop 0
	s_nop 0
	s_nop 0
	s_nop 0
	s_nop 0
	s_nop 0
	s_nop 0
	s_nop 0
	s_nop 0
	s_nop 0
	s_nop 0
	s_nop 0
	s_nop 0
	s_nop 0
	s_nop 0
	s_nop 0
	s_nop 0
	s_nop 0
	s_nop 0
	s_nop 0
	s_nop 0
	s_nop 0
	s_nop 0
	s_nop 0
	s_nop 0
	s_nop 0
	s_nop 0
	s_nop 0
	s_nop 0
	s_nop 0
	s_nop 0
	s_nop 0
	s_nop 0
	s_nop 0
	s_nop 0
	s_nop 0
	s_nop 0
	s_nop 0
	s_nop 0
	s_nop 0
	s_nop 0
	s_nop 0
	s_nop 0
	s_nop 0
	s_nop 0
	s_nop 0
	s_nop 0
	s_nop 0
	s_nop 0
	s_nop 0
	s_nop 0
	s_nop 0
	s_nop 0
	s_nop 0
	s_nop 0
	s_nop 0
	s_nop 0
	s_nop 0
	s_nop 0
	s_nop 0
	s_nop 0
	s_nop 0
	s_nop 0
	s_nop 0
	s_nop 0
	s_nop 0
	s_nop 0
	s_nop 0
	s_nop 0
	s_nop 0
	s_nop 0
	s_nop 0
	s_nop 0
	s_nop 0
	s_nop 0
	s_nop 0
	s_nop 0
	s_nop 0
	s_nop 0
	s_nop 0
	s_nop 0
	s_nop 0
	s_nop 0
	s_nop 0
	s_nop 0
	s_nop 0
	s_nop 0
	s_nop 0
	s_nop 0
	s_nop 0
	s_nop 0
	s_nop 0
	s_nop 0
	s_nop 0
	s_nop 0
	s_nop 0
	s_nop 0
	s_nop 0
	s_nop 0
	s_nop 0
	s_nop 0
	s_nop 0
	s_nop 0
	s_nop 0
	s_nop 0
	s_nop 0
	s_nop 0
	s_nop 0
	s_nop 0
	s_nop 0
	s_nop 0
	s_nop 0
	s_nop 0
	s_nop 0
	s_nop 0
	s_nop 0
	s_nop 0
	s_nop 0
	s_nop 0
	s_nop 0
	s_nop 0
	s_nop 0
	s_nop 0
	s_nop 0
	s_nop 0
	s_nop 0
	s_nop 0
	s_nop 0
	s_nop 0
	s_nop 0
	s_nop 0
	s_nop 0
	s_nop 0
	s_nop 0
	s_nop 0
	s_nop 0
	s_nop 0
	s_nop 0
	s_nop 0
	s_nop 0
	s_nop 0
	s_nop 0
	s_nop 0
	s_nop 0
	s_nop 0
	s_nop 0
	s_nop 0
	s_nop 0
	s_nop 0
	s_nop 0
	s_nop 0
	s_nop 0
	s_nop 0
	s_nop 0
	s_nop 0
	s_nop 0
	s_nop 0
	s_nop 0
	s_nop 0
	s_nop 0
	s_nop 0
	s_nop 0
	s_nop 0
	s_nop 0
	s_nop 0
	s_nop 0
	s_nop 0
	s_nop 0
	s_nop 0
	s_nop 0
	s_nop 0
	s_nop 0
	s_nop 0
	s_nop 0
	s_nop 0
	s_nop 0
	s_nop 0
	s_nop 0
	s_nop 0
	s_nop 0
	s_nop 0
	s_nop 0
	s_nop 0
	s_nop 0
	s_nop 0
	s_nop 0
	s_nop 0
	s_nop 0
	s_nop 0
	s_nop 0
	s_nop 0
	s_nop 0
	s_nop 0
	s_nop 0
	s_nop 0
	s_nop 0
	s_nop 0
	s_nop 0
	s_nop 0
	s_nop 0
	s_nop 0
	s_nop 0
	s_nop 0
	s_nop 0
	s_nop 0
	s_nop 0
	s_nop 0
	s_nop 0
	s_nop 0
	s_nop 0
	s_nop 0
	s_nop 0
	s_nop 0
	s_nop 0
	s_nop 0
	s_nop 0
	s_nop 0
	s_nop 0
	s_nop 0
	s_nop 0
	s_nop 0
	s_nop 0
	s_nop 0
	s_nop 0
	s_nop 0
	s_nop 0
	s_nop 0
	s_nop 0
	s_nop 0
	s_nop 0
	s_nop 0
	s_nop 0
	s_nop 0
	s_nop 0
	s_nop 0
	s_nop 0
	s_nop 0
	s_nop 0
	s_nop 0
	s_nop 0
	s_nop 0
	s_nop 0
	s_nop 0
	s_nop 0
	s_nop 0
	s_nop 0
	s_nop 0
	s_nop 0
